# pipelined GEMM K loops (mid-iteration barrier) + hand attention + row2 weight-fragment loads hoisted
# speedup vs baseline: 1.0592x; 1.0592x over previous
; #define TIDX tid_opaque()
; DI void wait_vm0() { asm volatile("s_waitcnt vmcnt(0)" ::: "memory"); }
; DI h8 lds128(unsigned a) { h8 r; asm volatile("ds_read_b128 %0, %1" : "=v"(r) : "v"(a)); return r; }
; DI unsigned lds_addr(const void* p) { return (unsigned)(size_t)p; }
; DI void raw_barrier() { asm volatile("" ::: "memory"); __builtin_amdgcn_s_barrier(); asm volatile("" ::: "memory"); }
; template <bool PRE = false, class AF, class BF>
; DI void gemm256(AF aptr, BF bptr, int nk, char* smem, f4 (&acc)[8][4]) {
;   const int tid = TIDX, lane = tid & 63, wave = tid >> 6, fr = lane & 15, fq = lane >> 4, wr = wave >> 1, wc = wave & 1;
; #pragma unroll
;   for (int m = 0; m < 8; m++)
; #pragma unroll
;     for (int n = 0; n < 4; n++) acc[m][n] = (f4){0.f, 0.f, 0.f, 0.f};
;   auto issue = [&](int kt, int st) {
;     char* d = smem + st * 49152 + tid * 16;
; #pragma unroll
;     for (int i = 0; i < 8; i++) glds16(aptr(i) + kt * 64, d + i * 4096);
; #pragma unroll
;     for (int i = 0; i < 4; i++) glds16(bptr(i) + kt * 64, d + 32768 + i * 4096);
;   };
;   const unsigned sw = (unsigned)((fq ^ (fr >> 1)) << 4);
;   const unsigned offA = (wr * 128 + fr) * 128 + sw, offB = 32768 + (wc * 64 + fr) * 128 + sw;
;   const unsigned sbase = lds_addr(smem);
;   if (!PRE) { issue(0, 0); if (nk > 1) issue(1, 1); }
;   int st = 0;
; #pragma unroll 1
;   for (int kt = 0; kt < nk; kt++) {
;     if (kt + 1 < nk) asm volatile("s_waitcnt vmcnt(12)" ::: "memory"); else wait_vm0();
;     raw_barrier();
;     if (kt + 2 < nk) issue(kt + 2, st == 0 ? 2 : st - 1);
;     const unsigned base = sbase + st * 49152;
;     st = st == 2 ? 0 : st + 1;
;     h8 a0[8], b0[4], a1[8], b1[4];
; #pragma unroll
;     for (int m = 0; m < 8; m++) a0[m] = lds128(base + offA + m * 2048);
; #pragma unroll
;     for (int n = 0; n < 4; n++) b0[n] = lds128(base + offB + n * 2048);
; #pragma unroll
;     for (int m = 0; m < 8; m++) a1[m] = lds128(base + (offA ^ 64) + m * 2048);
; #pragma unroll
;     for (int n = 0; n < 4; n++) b1[n] = lds128(base + (offB ^ 64) + n * 2048);
.LBB0_225:
	v_mov_b32_e32 v0, v172
	s_mov_b32 s2, 0x8040
	v_lshlrev_b32_e32 v1, 3, v0
	v_and_b32_e32 v2, 48, v0
	v_bitop3_b32 v1, v1, v2, s36 bitop3:0x6c
	v_lshlrev_b32_e32 v2, 7, v0
	v_and_b32_e32 v3, 0xffffc780, v2
	v_and_b32_e32 v2, 0x2780, v2
	v_or_b32_e32 v4, v1, v2
	s_mov_b32 s22, s28
	v_or_b32_e32 v24, v1, v3
	v_or_b32_e32 v25, 0x8000, v4
	v_lshlrev_b32_e32 v26, 4, v0
	v_bitop3_b32 v27, v1, 64, v3 bitop3:0x36
	v_bitop3_b32 v28, v1, s2, v2 bitop3:0x36
	v_accvgpr_write_b32 a3, 0
	v_accvgpr_write_b32 a2, 0
	v_accvgpr_write_b32 a1, 0
	v_accvgpr_write_b32 a0, 0
	v_accvgpr_write_b32 a7, 0
	v_accvgpr_write_b32 a6, 0
	v_accvgpr_write_b32 a5, 0
	v_accvgpr_write_b32 a4, 0
	v_accvgpr_write_b32 a11, 0
	v_accvgpr_write_b32 a10, 0
	v_accvgpr_write_b32 a9, 0
	v_accvgpr_write_b32 a8, 0
	v_accvgpr_write_b32 a15, 0
	v_accvgpr_write_b32 a14, 0
	v_accvgpr_write_b32 a13, 0
	v_accvgpr_write_b32 a12, 0
	v_accvgpr_write_b32 a19, 0
	v_accvgpr_write_b32 a18, 0
	v_accvgpr_write_b32 a17, 0
	v_accvgpr_write_b32 a16, 0
	v_accvgpr_write_b32 a31, 0
	v_accvgpr_write_b32 a30, 0
	v_accvgpr_write_b32 a29, 0
	v_accvgpr_write_b32 a28, 0
	v_accvgpr_write_b32 a55, 0
	v_accvgpr_write_b32 a54, 0
	v_accvgpr_write_b32 a53, 0
	v_accvgpr_write_b32 a52, 0
	v_accvgpr_write_b32 a71, 0
	v_accvgpr_write_b32 a70, 0
	v_accvgpr_write_b32 a69, 0
	v_accvgpr_write_b32 a68, 0
	v_accvgpr_write_b32 a91, 0
	v_accvgpr_write_b32 a90, 0
	v_accvgpr_write_b32 a89, 0
	v_accvgpr_write_b32 a88, 0
	v_accvgpr_write_b32 a111, 0
	v_accvgpr_write_b32 a110, 0
	v_accvgpr_write_b32 a109, 0
	v_accvgpr_write_b32 a108, 0
	v_accvgpr_write_b32 a127, 0
	v_accvgpr_write_b32 a126, 0
	v_accvgpr_write_b32 a125, 0
	v_accvgpr_write_b32 a124, 0
	v_accvgpr_write_b32 a123, 0
	v_accvgpr_write_b32 a122, 0
	v_accvgpr_write_b32 a121, 0
	v_accvgpr_write_b32 a120, 0
	v_accvgpr_write_b32 a119, 0
	v_accvgpr_write_b32 a118, 0
	v_accvgpr_write_b32 a117, 0
	v_accvgpr_write_b32 a116, 0
	v_accvgpr_write_b32 a115, 0
	v_accvgpr_write_b32 a114, 0
	v_accvgpr_write_b32 a113, 0
	v_accvgpr_write_b32 a112, 0
	v_accvgpr_write_b32 a107, 0
	v_accvgpr_write_b32 a106, 0
	v_accvgpr_write_b32 a105, 0
	v_accvgpr_write_b32 a104, 0
	v_accvgpr_write_b32 a103, 0
	v_accvgpr_write_b32 a102, 0
	v_accvgpr_write_b32 a101, 0
	v_accvgpr_write_b32 a100, 0
	v_accvgpr_write_b32 a99, 0
	v_accvgpr_write_b32 a98, 0
	v_accvgpr_write_b32 a97, 0
	v_accvgpr_write_b32 a96, 0
	v_accvgpr_write_b32 a95, 0
	v_accvgpr_write_b32 a94, 0
	v_accvgpr_write_b32 a93, 0
	v_accvgpr_write_b32 a92, 0
	v_accvgpr_write_b32 a87, 0
	v_accvgpr_write_b32 a86, 0
	v_accvgpr_write_b32 a85, 0
	v_accvgpr_write_b32 a84, 0
	v_accvgpr_write_b32 a83, 0
	v_accvgpr_write_b32 a82, 0
	v_accvgpr_write_b32 a81, 0
	v_accvgpr_write_b32 a80, 0
	v_accvgpr_write_b32 a79, 0
	v_accvgpr_write_b32 a78, 0
	v_accvgpr_write_b32 a77, 0
	v_accvgpr_write_b32 a76, 0
	v_accvgpr_write_b32 a75, 0
	v_accvgpr_write_b32 a74, 0
	v_accvgpr_write_b32 a73, 0
	v_accvgpr_write_b32 a72, 0
	v_accvgpr_write_b32 a67, 0
	v_accvgpr_write_b32 a66, 0
	v_accvgpr_write_b32 a65, 0
	v_accvgpr_write_b32 a64, 0
	v_accvgpr_write_b32 a63, 0
	v_accvgpr_write_b32 a62, 0
	v_accvgpr_write_b32 a61, 0
	v_accvgpr_write_b32 a60, 0
	v_accvgpr_write_b32 a59, 0
	v_accvgpr_write_b32 a58, 0
	v_accvgpr_write_b32 a57, 0
	v_accvgpr_write_b32 a56, 0
	v_accvgpr_write_b32 a51, 0
	v_accvgpr_write_b32 a50, 0
	v_accvgpr_write_b32 a49, 0
	v_accvgpr_write_b32 a48, 0
	v_accvgpr_write_b32 a47, 0
	v_accvgpr_write_b32 a46, 0
	v_accvgpr_write_b32 a45, 0
	v_accvgpr_write_b32 a44, 0
	v_accvgpr_write_b32 a43, 0
	v_accvgpr_write_b32 a42, 0
	v_accvgpr_write_b32 a41, 0
	v_accvgpr_write_b32 a40, 0
	v_accvgpr_write_b32 a39, 0
	v_accvgpr_write_b32 a38, 0
	v_accvgpr_write_b32 a37, 0
	v_accvgpr_write_b32 a36, 0
	v_accvgpr_write_b32 a35, 0
	v_accvgpr_write_b32 a34, 0
	v_accvgpr_write_b32 a33, 0
	v_accvgpr_write_b32 a32, 0
	v_accvgpr_write_b32 a27, 0
	v_accvgpr_write_b32 a26, 0
	v_accvgpr_write_b32 a25, 0
	v_accvgpr_write_b32 a24, 0
	v_accvgpr_write_b32 a23, 0
	v_accvgpr_write_b32 a22, 0
	v_accvgpr_write_b32 a21, 0
	v_accvgpr_write_b32 a20, 0
	s_mov_b32 s6, 0
	s_mov_b64 s[2:3], 0
	s_mov_b32 s7, 0
	v_readfirstlane_b32 s100, v26
	s_waitcnt vmcnt(12)
	s_barrier
	s_add_u32 s101, s100, 0x18000
	v_lshl_add_u64 v[10:11], v[96:97], 0, s[2:3]
	s_add_u32 m0, s101, 0x0
	v_lshl_add_u64 v[14:15], v[10:11], 0, s[74:75]
	global_load_lds_dwordx4 v[14:15], off
	s_add_u32 m0, s101, 0x1000
	v_lshl_add_u64 v[14:15], v[10:11], 0, s[76:77]
	global_load_lds_dwordx4 v[14:15], off
	s_add_u32 m0, s101, 0x2000
	v_lshl_add_u64 v[14:15], v[10:11], 0, s[86:87]
	global_load_lds_dwordx4 v[14:15], off
	s_add_u32 m0, s101, 0x3000
	v_lshl_add_u64 v[14:15], v[10:11], 0, s[80:81]
	global_load_lds_dwordx4 v[14:15], off
	s_add_u32 m0, s101, 0x4000
	v_lshl_add_u64 v[14:15], v[10:11], 0, s[72:73]
	global_load_lds_dwordx4 v[14:15], off
	s_add_u32 m0, s101, 0x5000
	v_lshl_add_u64 v[14:15], v[10:11], 0, s[96:97]
	global_load_lds_dwordx4 v[14:15], off
	s_add_u32 m0, s101, 0x6000
	v_lshl_add_u64 v[14:15], v[10:11], 0, s[12:13]
	global_load_lds_dwordx4 v[14:15], off
	s_add_u32 m0, s101, 0x7000
	v_lshl_add_u64 v[14:15], v[10:11], 0, s[16:17]
	global_load_lds_dwordx4 v[14:15], off
	v_lshl_add_u64 v[12:13], v[94:95], 0, s[2:3]
	s_add_u32 m0, s101, 0x8000
	v_lshl_add_u64 v[14:15], v[12:13], 0, s[74:75]
	global_load_lds_dwordx4 v[14:15], off
	s_add_u32 m0, s101, 0x9000
	v_lshl_add_u64 v[14:15], v[12:13], 0, s[76:77]
	global_load_lds_dwordx4 v[14:15], off
	s_add_u32 m0, s101, 0xa000
	v_lshl_add_u64 v[14:15], v[12:13], 0, s[86:87]
	global_load_lds_dwordx4 v[14:15], off
	s_add_u32 m0, s101, 0xb000
	v_lshl_add_u64 v[14:15], v[12:13], 0, s[80:81]
	global_load_lds_dwordx4 v[14:15], off
	s_add_u32 s2, s2, 0x80
	s_addc_u32 s3, s3, 0
	ds_read_b128 v[62:65], v25 offset:0
	ds_read_b128 v[66:69], v25 offset:2048
	ds_read_b128 v[70:73], v25 offset:4096
	ds_read_b128 v[74:77], v25 offset:6144
	ds_read_b128 v[30:33], v24 offset:0
	ds_read_b128 v[34:37], v24 offset:2048
	ds_read_b128 v[38:41], v24 offset:4096
	ds_read_b128 v[42:45], v24 offset:6144
	ds_read_b128 v[46:49], v24 offset:8192
	ds_read_b128 v[50:53], v24 offset:10240
	ds_read_b128 v[54:57], v24 offset:12288
	ds_read_b128 v[58:61], v24 offset:14336
; DI f4 mfma16(h8 a, h8 b, f4 c) { return __builtin_amdgcn_mfma_f32_16x16x32_f16(a, b, c, 0, 0, 0); }
; DI h8 lds128(unsigned a) { h8 r; asm volatile("ds_read_b128 %0, %1" : "=v"(r) : "v"(a)); return r; }
; DI void tie(h8& x) { asm volatile("" : "+v"(x)); }
; #define WAIT_LGKM(n) asm volatile("s_waitcnt lgkmcnt(" #n ")" ::: "memory")
; template <bool PRE = false, class AF, class BF>
; DI void gemm256(AF aptr, BF bptr, int nk, char* smem, f4 (&acc)[8][4]) {
;     ...
;     for (int m = 0; m < 8; m++) a0[m] = lds128(base + offA + m * 2048);
; #pragma unroll
;     for (int n = 0; n < 4; n++) b0[n] = lds128(base + offB + n * 2048);
; #pragma unroll
;     for (int m = 0; m < 8; m++) a1[m] = lds128(base + (offA ^ 64) + m * 2048);
; #pragma unroll
;     for (int n = 0; n < 4; n++) b1[n] = lds128(base + (offB ^ 64) + n * 2048);
;     WAIT_LGKM(12);
; #pragma unroll
;     for (int m = 0; m < 8; m++) tie(a0[m]);
; #pragma unroll
;     for (int n = 0; n < 4; n++) tie(b0[n]);
; #pragma unroll
;     for (int m = 0; m < 8; m++)
; #pragma unroll
;       for (int n = 0; n < 4; n++) acc[m][n] = mfma16(a0[m], b0[n], acc[m][n]);
.Lg_gin_loop:
	s_mul_i32 s9, s7, 0xc000
	v_add_u32_e32 v8, s9, v27
	v_add_u32_e32 v9, s9, v28
	s_waitcnt lgkmcnt(0)
	v_mfma_f32_16x16x32_f16 a[0:3], v[30:33], v[62:65], a[0:3]
	ds_read_b128 a[200:203], v9 offset:0
	v_mfma_f32_16x16x32_f16 a[4:7], v[30:33], v[66:69], a[4:7]
	v_mfma_f32_16x16x32_f16 a[8:11], v[30:33], v[70:73], a[8:11]
	ds_read_b128 a[204:207], v9 offset:2048
	v_mfma_f32_16x16x32_f16 a[12:15], v[30:33], v[74:77], a[12:15]
	v_mfma_f32_16x16x32_f16 a[16:19], v[34:37], v[62:65], a[16:19]
	ds_read_b128 a[208:211], v9 offset:4096
	v_mfma_f32_16x16x32_f16 a[28:31], v[34:37], v[66:69], a[28:31]
	v_mfma_f32_16x16x32_f16 a[52:55], v[34:37], v[70:73], a[52:55]
	ds_read_b128 a[212:215], v9 offset:6144
	v_mfma_f32_16x16x32_f16 a[68:71], v[34:37], v[74:77], a[68:71]
	v_mfma_f32_16x16x32_f16 a[88:91], v[38:41], v[62:65], a[88:91]
	ds_read_b128 v[78:81], v8 offset:0
	v_mfma_f32_16x16x32_f16 a[108:111], v[38:41], v[66:69], a[108:111]
	v_mfma_f32_16x16x32_f16 a[124:127], v[38:41], v[70:73], a[124:127]
	ds_read_b128 v[82:85], v8 offset:2048
	v_mfma_f32_16x16x32_f16 a[120:123], v[38:41], v[74:77], a[120:123]
	v_mfma_f32_16x16x32_f16 a[116:119], v[42:45], v[62:65], a[116:119]
	ds_read_b128 v[0:3], v8 offset:4096
	v_mfma_f32_16x16x32_f16 a[112:115], v[42:45], v[66:69], a[112:115]
	v_mfma_f32_16x16x32_f16 a[104:107], v[42:45], v[70:73], a[104:107]
	ds_read_b128 v[4:7], v8 offset:6144
	v_mfma_f32_16x16x32_f16 a[100:103], v[42:45], v[74:77], a[100:103]
	v_mfma_f32_16x16x32_f16 a[96:99], v[46:49], v[62:65], a[96:99]
	ds_read_b128 v[86:89], v8 offset:8192
	v_mfma_f32_16x16x32_f16 a[92:95], v[46:49], v[66:69], a[92:95]
	v_mfma_f32_16x16x32_f16 a[84:87], v[46:49], v[70:73], a[84:87]
	ds_read_b128 v[90:93], v8 offset:10240
	v_mfma_f32_16x16x32_f16 a[80:83], v[46:49], v[74:77], a[80:83]
	v_mfma_f32_16x16x32_f16 a[76:79], v[50:53], v[62:65], a[76:79]
	ds_read_b128 v[100:103], v8 offset:12288
	v_mfma_f32_16x16x32_f16 a[72:75], v[50:53], v[66:69], a[72:75]
	v_mfma_f32_16x16x32_f16 a[64:67], v[50:53], v[70:73], a[64:67]
	ds_read_b128 v[104:107], v8 offset:14336
	v_mfma_f32_16x16x32_f16 a[60:63], v[50:53], v[74:77], a[60:63]
	v_mfma_f32_16x16x32_f16 a[56:59], v[54:57], v[62:65], a[56:59]
	v_mfma_f32_16x16x32_f16 a[48:51], v[54:57], v[66:69], a[48:51]
	v_mfma_f32_16x16x32_f16 a[44:47], v[54:57], v[70:73], a[44:47]
	v_mfma_f32_16x16x32_f16 a[40:43], v[54:57], v[74:77], a[40:43]
	v_mfma_f32_16x16x32_f16 a[36:39], v[58:61], v[62:65], a[36:39]
	v_mfma_f32_16x16x32_f16 a[32:35], v[58:61], v[66:69], a[32:35]
	v_mfma_f32_16x16x32_f16 a[24:27], v[58:61], v[70:73], a[24:27]
	v_mfma_f32_16x16x32_f16 a[20:23], v[58:61], v[74:77], a[20:23]
	s_cmp_eq_u32 s6, 15
	s_cbranch_scc1 .Lg_gin_last
	s_cmp_lt_u32 s6, 14
	s_cbranch_scc1 .Lg_gin_w12
	s_waitcnt vmcnt(0)
	s_branch .Lg_gin_wd
.Lg_gin_w12:
	s_waitcnt vmcnt(12)
.Lg_gin_wd:
	s_waitcnt lgkmcnt(0)
	s_barrier
	s_add_u32 s8, s7, 1
	s_cmp_eq_u32 s8, 3
	s_cselect_b32 s8, 0, s8
	s_mul_i32 s9, s8, 0xc000
	v_add_u32_e32 v8, s9, v24
	v_add_u32_e32 v9, s9, v25
	s_mul_i32 s101, s7, 0xc000
	s_add_u32 s101, s101, s100
	s_cmp_lt_u32 s6, 13
	s_cbranch_scc0 .Lg_gin_noissue
	v_mfma_f32_16x16x32_f16 a[0:3], v[78:81], a[200:203], a[0:3]
	ds_read_b128 v[62:65], v9 offset:0
	v_mfma_f32_16x16x32_f16 a[4:7], v[78:81], a[204:207], a[4:7]
	v_lshl_add_u64 v[10:11], v[96:97], 0, s[2:3]
	s_add_u32 m0, s101, 0x0
	v_lshl_add_u64 v[14:15], v[10:11], 0, s[74:75]
	global_load_lds_dwordx4 v[14:15], off
	v_mfma_f32_16x16x32_f16 a[8:11], v[78:81], a[208:211], a[8:11]
	ds_read_b128 v[66:69], v9 offset:2048
	v_mfma_f32_16x16x32_f16 a[12:15], v[78:81], a[212:215], a[12:15]
	s_add_u32 m0, s101, 0x1000
	v_lshl_add_u64 v[14:15], v[10:11], 0, s[76:77]
	global_load_lds_dwordx4 v[14:15], off
	v_mfma_f32_16x16x32_f16 a[16:19], v[82:85], a[200:203], a[16:19]
	ds_read_b128 v[70:73], v9 offset:4096
	v_mfma_f32_16x16x32_f16 a[28:31], v[82:85], a[204:207], a[28:31]
	s_add_u32 m0, s101, 0x2000
	v_lshl_add_u64 v[14:15], v[10:11], 0, s[86:87]
	global_load_lds_dwordx4 v[14:15], off
	v_mfma_f32_16x16x32_f16 a[52:55], v[82:85], a[208:211], a[52:55]
	ds_read_b128 v[74:77], v9 offset:6144
	v_mfma_f32_16x16x32_f16 a[68:71], v[82:85], a[212:215], a[68:71]
	s_add_u32 m0, s101, 0x3000
	v_lshl_add_u64 v[14:15], v[10:11], 0, s[80:81]
	global_load_lds_dwordx4 v[14:15], off
	v_mfma_f32_16x16x32_f16 a[88:91], v[0:3], a[200:203], a[88:91]
	ds_read_b128 v[30:33], v8 offset:0
	v_mfma_f32_16x16x32_f16 a[108:111], v[0:3], a[204:207], a[108:111]
	s_add_u32 m0, s101, 0x4000
	v_lshl_add_u64 v[14:15], v[10:11], 0, s[72:73]
	global_load_lds_dwordx4 v[14:15], off
	v_mfma_f32_16x16x32_f16 a[124:127], v[0:3], a[208:211], a[124:127]
	ds_read_b128 v[34:37], v8 offset:2048
	v_mfma_f32_16x16x32_f16 a[120:123], v[0:3], a[212:215], a[120:123]
	s_add_u32 m0, s101, 0x5000
	v_lshl_add_u64 v[14:15], v[10:11], 0, s[96:97]
	global_load_lds_dwordx4 v[14:15], off
	v_mfma_f32_16x16x32_f16 a[116:119], v[4:7], a[200:203], a[116:119]
	ds_read_b128 v[38:41], v8 offset:4096
	v_mfma_f32_16x16x32_f16 a[112:115], v[4:7], a[204:207], a[112:115]
	s_add_u32 m0, s101, 0x6000
	v_lshl_add_u64 v[14:15], v[10:11], 0, s[12:13]
	global_load_lds_dwordx4 v[14:15], off
	v_mfma_f32_16x16x32_f16 a[104:107], v[4:7], a[208:211], a[104:107]
	ds_read_b128 v[42:45], v8 offset:6144
	v_mfma_f32_16x16x32_f16 a[100:103], v[4:7], a[212:215], a[100:103]
	s_add_u32 m0, s101, 0x7000
	v_lshl_add_u64 v[14:15], v[10:11], 0, s[16:17]
	global_load_lds_dwordx4 v[14:15], off
	v_mfma_f32_16x16x32_f16 a[96:99], v[86:89], a[200:203], a[96:99]
	ds_read_b128 v[46:49], v8 offset:8192
	v_mfma_f32_16x16x32_f16 a[92:95], v[86:89], a[204:207], a[92:95]
; DI f4 mfma16(h8 a, h8 b, f4 c) { return __builtin_amdgcn_mfma_f32_16x16x32_f16(a, b, c, 0, 0, 0); }
; DI h8 lds128(unsigned a) { h8 r; asm volatile("ds_read_b128 %0, %1" : "=v"(r) : "v"(a)); return r; }
; DI void tie(h8& x) { asm volatile("" : "+v"(x)); }
; #define WAIT_LGKM(n) asm volatile("s_waitcnt lgkmcnt(" #n ")" ::: "memory")
; template <bool PRE = false, class AF, class BF>
; DI void gemm256(AF aptr, BF bptr, int nk, char* smem, f4 (&acc)[8][4]) {
;     ...
;     if (kt + 2 < nk) issue(kt + 2, st == 0 ? 2 : st - 1);
;     const unsigned base = sbase + st * 49152;
;     st = st == 2 ? 0 : st + 1;
;     h8 a0[8], b0[4], a1[8], b1[4];
; #pragma unroll
;     for (int m = 0; m < 8; m++) a0[m] = lds128(base + offA + m * 2048);
; #pragma unroll
;     for (int n = 0; n < 4; n++) b0[n] = lds128(base + offB + n * 2048);
; #pragma unroll
;     for (int m = 0; m < 8; m++) a1[m] = lds128(base + (offA ^ 64) + m * 2048);
; #pragma unroll
;     for (int n = 0; n < 4; n++) b1[n] = lds128(base + (offB ^ 64) + n * 2048);
;     WAIT_LGKM(12);
; #pragma unroll
;     for (int m = 0; m < 8; m++) tie(a0[m]);
; #pragma unroll
;     for (int n = 0; n < 4; n++) tie(b0[n]);
; #pragma unroll
;     for (int m = 0; m < 8; m++)
; #pragma unroll
;       for (int n = 0; n < 4; n++) acc[m][n] = mfma16(a0[m], b0[n], acc[m][n]);
;     WAIT_LGKM(0);
; #pragma unroll
;     for (int m = 0; m < 8; m++) tie(a1[m]);
; #pragma unroll
;     for (int n = 0; n < 4; n++) tie(b1[n]);
; #pragma unroll
;     for (int m = 0; m < 8; m++)
; #pragma unroll
;       for (int n = 0; n < 4; n++) acc[m][n] = mfma16(a1[m], b1[n], acc[m][n]);
;   }
	v_lshl_add_u64 v[12:13], v[94:95], 0, s[2:3]
	s_add_u32 m0, s101, 0x8000
	v_lshl_add_u64 v[14:15], v[12:13], 0, s[74:75]
	global_load_lds_dwordx4 v[14:15], off
	v_mfma_f32_16x16x32_f16 a[84:87], v[86:89], a[208:211], a[84:87]
	ds_read_b128 v[50:53], v8 offset:10240
	v_mfma_f32_16x16x32_f16 a[80:83], v[86:89], a[212:215], a[80:83]
	s_add_u32 m0, s101, 0x9000
	v_lshl_add_u64 v[14:15], v[12:13], 0, s[76:77]
	global_load_lds_dwordx4 v[14:15], off
	v_mfma_f32_16x16x32_f16 a[76:79], v[90:93], a[200:203], a[76:79]
	ds_read_b128 v[54:57], v8 offset:12288
	v_mfma_f32_16x16x32_f16 a[72:75], v[90:93], a[204:207], a[72:75]
	s_add_u32 m0, s101, 0xa000
	v_lshl_add_u64 v[14:15], v[12:13], 0, s[86:87]
	global_load_lds_dwordx4 v[14:15], off
	v_mfma_f32_16x16x32_f16 a[64:67], v[90:93], a[208:211], a[64:67]
	ds_read_b128 v[58:61], v8 offset:14336
	v_mfma_f32_16x16x32_f16 a[60:63], v[90:93], a[212:215], a[60:63]
	s_add_u32 m0, s101, 0xb000
	v_lshl_add_u64 v[14:15], v[12:13], 0, s[80:81]
	global_load_lds_dwordx4 v[14:15], off
	v_mfma_f32_16x16x32_f16 a[56:59], v[100:103], a[200:203], a[56:59]
	v_mfma_f32_16x16x32_f16 a[48:51], v[100:103], a[204:207], a[48:51]
	v_mfma_f32_16x16x32_f16 a[44:47], v[100:103], a[208:211], a[44:47]
	v_mfma_f32_16x16x32_f16 a[40:43], v[100:103], a[212:215], a[40:43]
	v_mfma_f32_16x16x32_f16 a[36:39], v[104:107], a[200:203], a[36:39]
	v_mfma_f32_16x16x32_f16 a[32:35], v[104:107], a[204:207], a[32:35]
	v_mfma_f32_16x16x32_f16 a[24:27], v[104:107], a[208:211], a[24:27]
	v_mfma_f32_16x16x32_f16 a[20:23], v[104:107], a[212:215], a[20:23]
	s_branch .Lg_gin_next
.Lg_gin_noissue:
	v_mfma_f32_16x16x32_f16 a[0:3], v[78:81], a[200:203], a[0:3]
	ds_read_b128 v[62:65], v9 offset:0
	v_mfma_f32_16x16x32_f16 a[4:7], v[78:81], a[204:207], a[4:7]
	v_mfma_f32_16x16x32_f16 a[8:11], v[78:81], a[208:211], a[8:11]
	ds_read_b128 v[66:69], v9 offset:2048
	v_mfma_f32_16x16x32_f16 a[12:15], v[78:81], a[212:215], a[12:15]
	v_mfma_f32_16x16x32_f16 a[16:19], v[82:85], a[200:203], a[16:19]
	ds_read_b128 v[70:73], v9 offset:4096
	v_mfma_f32_16x16x32_f16 a[28:31], v[82:85], a[204:207], a[28:31]
	v_mfma_f32_16x16x32_f16 a[52:55], v[82:85], a[208:211], a[52:55]
	ds_read_b128 v[74:77], v9 offset:6144
	v_mfma_f32_16x16x32_f16 a[68:71], v[82:85], a[212:215], a[68:71]
	v_mfma_f32_16x16x32_f16 a[88:91], v[0:3], a[200:203], a[88:91]
	ds_read_b128 v[30:33], v8 offset:0
	v_mfma_f32_16x16x32_f16 a[108:111], v[0:3], a[204:207], a[108:111]
	v_mfma_f32_16x16x32_f16 a[124:127], v[0:3], a[208:211], a[124:127]
	ds_read_b128 v[34:37], v8 offset:2048
	v_mfma_f32_16x16x32_f16 a[120:123], v[0:3], a[212:215], a[120:123]
	v_mfma_f32_16x16x32_f16 a[116:119], v[4:7], a[200:203], a[116:119]
	ds_read_b128 v[38:41], v8 offset:4096
	v_mfma_f32_16x16x32_f16 a[112:115], v[4:7], a[204:207], a[112:115]
	v_mfma_f32_16x16x32_f16 a[104:107], v[4:7], a[208:211], a[104:107]
	ds_read_b128 v[42:45], v8 offset:6144
	v_mfma_f32_16x16x32_f16 a[100:103], v[4:7], a[212:215], a[100:103]
	v_mfma_f32_16x16x32_f16 a[96:99], v[86:89], a[200:203], a[96:99]
	ds_read_b128 v[46:49], v8 offset:8192
	v_mfma_f32_16x16x32_f16 a[92:95], v[86:89], a[204:207], a[92:95]
	v_mfma_f32_16x16x32_f16 a[84:87], v[86:89], a[208:211], a[84:87]
	ds_read_b128 v[50:53], v8 offset:10240
	v_mfma_f32_16x16x32_f16 a[80:83], v[86:89], a[212:215], a[80:83]
	v_mfma_f32_16x16x32_f16 a[76:79], v[90:93], a[200:203], a[76:79]
	ds_read_b128 v[54:57], v8 offset:12288
	v_mfma_f32_16x16x32_f16 a[72:75], v[90:93], a[204:207], a[72:75]
	v_mfma_f32_16x16x32_f16 a[64:67], v[90:93], a[208:211], a[64:67]
	ds_read_b128 v[58:61], v8 offset:14336
	v_mfma_f32_16x16x32_f16 a[60:63], v[90:93], a[212:215], a[60:63]
	v_mfma_f32_16x16x32_f16 a[56:59], v[100:103], a[200:203], a[56:59]
	v_mfma_f32_16x16x32_f16 a[48:51], v[100:103], a[204:207], a[48:51]
	v_mfma_f32_16x16x32_f16 a[44:47], v[100:103], a[208:211], a[44:47]
	v_mfma_f32_16x16x32_f16 a[40:43], v[100:103], a[212:215], a[40:43]
	v_mfma_f32_16x16x32_f16 a[36:39], v[104:107], a[200:203], a[36:39]
	v_mfma_f32_16x16x32_f16 a[32:35], v[104:107], a[204:207], a[32:35]
	v_mfma_f32_16x16x32_f16 a[24:27], v[104:107], a[208:211], a[24:27]
	v_mfma_f32_16x16x32_f16 a[20:23], v[104:107], a[212:215], a[20:23]
.Lg_gin_next:
	s_mov_b32 s7, s8
	s_add_u32 s6, s6, 1
	s_add_u32 s2, s2, 0x80
	s_addc_u32 s3, s3, 0
	s_branch .Lg_gin_loop
.Lg_gin_last:
	s_waitcnt lgkmcnt(0)
	v_mfma_f32_16x16x32_f16 a[0:3], v[78:81], a[200:203], a[0:3]
	v_mfma_f32_16x16x32_f16 a[4:7], v[78:81], a[204:207], a[4:7]
	v_mfma_f32_16x16x32_f16 a[8:11], v[78:81], a[208:211], a[8:11]
	v_mfma_f32_16x16x32_f16 a[12:15], v[78:81], a[212:215], a[12:15]
	v_mfma_f32_16x16x32_f16 a[16:19], v[82:85], a[200:203], a[16:19]
	v_mfma_f32_16x16x32_f16 a[28:31], v[82:85], a[204:207], a[28:31]
	v_mfma_f32_16x16x32_f16 a[52:55], v[82:85], a[208:211], a[52:55]
	v_mfma_f32_16x16x32_f16 a[68:71], v[82:85], a[212:215], a[68:71]
	v_mfma_f32_16x16x32_f16 a[88:91], v[0:3], a[200:203], a[88:91]
	v_mfma_f32_16x16x32_f16 a[108:111], v[0:3], a[204:207], a[108:111]
	v_mfma_f32_16x16x32_f16 a[124:127], v[0:3], a[208:211], a[124:127]
	v_mfma_f32_16x16x32_f16 a[120:123], v[0:3], a[212:215], a[120:123]
	v_mfma_f32_16x16x32_f16 a[116:119], v[4:7], a[200:203], a[116:119]
	v_mfma_f32_16x16x32_f16 a[112:115], v[4:7], a[204:207], a[112:115]
	v_mfma_f32_16x16x32_f16 a[104:107], v[4:7], a[208:211], a[104:107]
	v_mfma_f32_16x16x32_f16 a[100:103], v[4:7], a[212:215], a[100:103]
	v_mfma_f32_16x16x32_f16 a[96:99], v[86:89], a[200:203], a[96:99]
	v_mfma_f32_16x16x32_f16 a[92:95], v[86:89], a[204:207], a[92:95]
	v_mfma_f32_16x16x32_f16 a[84:87], v[86:89], a[208:211], a[84:87]
	v_mfma_f32_16x16x32_f16 a[80:83], v[86:89], a[212:215], a[80:83]
	v_mfma_f32_16x16x32_f16 a[76:79], v[90:93], a[200:203], a[76:79]
	v_mfma_f32_16x16x32_f16 a[72:75], v[90:93], a[204:207], a[72:75]
	v_mfma_f32_16x16x32_f16 a[64:67], v[90:93], a[208:211], a[64:67]
	v_mfma_f32_16x16x32_f16 a[60:63], v[90:93], a[212:215], a[60:63]
	v_mfma_f32_16x16x32_f16 a[56:59], v[100:103], a[200:203], a[56:59]
	v_mfma_f32_16x16x32_f16 a[48:51], v[100:103], a[204:207], a[48:51]
	v_mfma_f32_16x16x32_f16 a[44:47], v[100:103], a[208:211], a[44:47]
	v_mfma_f32_16x16x32_f16 a[40:43], v[100:103], a[212:215], a[40:43]
	v_mfma_f32_16x16x32_f16 a[36:39], v[104:107], a[200:203], a[36:39]
	v_mfma_f32_16x16x32_f16 a[32:35], v[104:107], a[204:207], a[32:35]
	v_mfma_f32_16x16x32_f16 a[24:27], v[104:107], a[208:211], a[24:27]
	v_mfma_f32_16x16x32_f16 a[20:23], v[104:107], a[212:215], a[20:23]
	s_nop 7
	s_nop 7

; #define TIDX tid_opaque()
; DI void wait_vm0() { asm volatile("s_waitcnt vmcnt(0)" ::: "memory"); }
; DI h8 lds128(unsigned a) { h8 r; asm volatile("ds_read_b128 %0, %1" : "=v"(r) : "v"(a)); return r; }
; DI unsigned lds_addr(const void* p) { return (unsigned)(size_t)p; }
; DI void raw_barrier() { asm volatile("" ::: "memory"); __builtin_amdgcn_s_barrier(); asm volatile("" ::: "memory"); }
; template <bool PRE = false, class AF, class BF>
; DI void gemm256(AF aptr, BF bptr, int nk, char* smem, f4 (&acc)[8][4]) {
;   const int tid = TIDX, lane = tid & 63, wave = tid >> 6, fr = lane & 15, fq = lane >> 4, wr = wave >> 1, wc = wave & 1;
; #pragma unroll
;   for (int m = 0; m < 8; m++)
; #pragma unroll
;     for (int n = 0; n < 4; n++) acc[m][n] = (f4){0.f, 0.f, 0.f, 0.f};
;   auto issue = [&](int kt, int st) {
;     char* d = smem + st * 49152 + tid * 16;
; #pragma unroll
;     for (int i = 0; i < 8; i++) glds16(aptr(i) + kt * 64, d + i * 4096);
; #pragma unroll
;     for (int i = 0; i < 4; i++) glds16(bptr(i) + kt * 64, d + 32768 + i * 4096);
;   };
;   const unsigned sw = (unsigned)((fq ^ (fr >> 1)) << 4);
;   const unsigned offA = (wr * 128 + fr) * 128 + sw, offB = 32768 + (wc * 64 + fr) * 128 + sw;
;   const unsigned sbase = lds_addr(smem);
;   if (!PRE) { issue(0, 0); if (nk > 1) issue(1, 1); }
;   int st = 0;
; #pragma unroll 1
;   for (int kt = 0; kt < nk; kt++) {
;     if (kt + 1 < nk) asm volatile("s_waitcnt vmcnt(12)" ::: "memory"); else wait_vm0();
;     raw_barrier();
;     if (kt + 2 < nk) issue(kt + 2, st == 0 ? 2 : st - 1);
;     const unsigned base = sbase + st * 49152;
;     st = st == 2 ? 0 : st + 1;
;     h8 a0[8], b0[4], a1[8], b1[4];
; #pragma unroll
;     for (int m = 0; m < 8; m++) a0[m] = lds128(base + offA + m * 2048);
; #pragma unroll
;     for (int n = 0; n < 4; n++) b0[n] = lds128(base + offB + n * 2048);
; #pragma unroll
;     for (int m = 0; m < 8; m++) a1[m] = lds128(base + (offA ^ 64) + m * 2048);
; #pragma unroll
;     for (int n = 0; n < 4; n++) b1[n] = lds128(base + (offB ^ 64) + n * 2048);
.LBB0_513:
	s_nop 0
	v_mov_b32_e32 v2, v172
	s_mov_b32 s0, 0x8040
	v_lshlrev_b32_e32 v0, 3, v2
	v_and_b32_e32 v1, 48, v2
	v_bitop3_b32 v4, v0, v1, s37 bitop3:0x6c
	v_lshlrev_b32_e32 v1, 7, v2
	v_and_b32_e32 v5, 0x2780, v1
	v_and_b32_e32 v3, 0xffffc780, v1
	v_or_b32_e32 v1, v4, v5
	v_or_b32_e32 v0, v4, v3
	v_or_b32_e32 v1, 0x8000, v1
	v_lshlrev_b32_e32 v2, 4, v2
	v_bitop3_b32 v3, v4, 64, v3 bitop3:0x36
	v_bitop3_b32 v4, v4, s0, v5 bitop3:0x36
	v_accvgpr_write_b32 a127, 0
	v_accvgpr_write_b32 a126, 0
	v_accvgpr_write_b32 a125, 0
	v_accvgpr_write_b32 a124, 0
	v_accvgpr_write_b32 a123, 0
	v_accvgpr_write_b32 a122, 0
	v_accvgpr_write_b32 a121, 0
	v_accvgpr_write_b32 a120, 0
	v_accvgpr_write_b32 a119, 0
	v_accvgpr_write_b32 a118, 0
	v_accvgpr_write_b32 a117, 0
	v_accvgpr_write_b32 a116, 0
	v_accvgpr_write_b32 a115, 0
	v_accvgpr_write_b32 a114, 0
	v_accvgpr_write_b32 a113, 0
	v_accvgpr_write_b32 a112, 0
	v_accvgpr_write_b32 a111, 0
	v_accvgpr_write_b32 a110, 0
	v_accvgpr_write_b32 a109, 0
	v_accvgpr_write_b32 a108, 0
	v_accvgpr_write_b32 a107, 0
	v_accvgpr_write_b32 a106, 0
	v_accvgpr_write_b32 a105, 0
	v_accvgpr_write_b32 a104, 0
	v_accvgpr_write_b32 a103, 0
	v_accvgpr_write_b32 a102, 0
	v_accvgpr_write_b32 a101, 0
	v_accvgpr_write_b32 a100, 0
	v_accvgpr_write_b32 a99, 0
	v_accvgpr_write_b32 a98, 0
	v_accvgpr_write_b32 a97, 0
	v_accvgpr_write_b32 a96, 0
	v_accvgpr_write_b32 a95, 0
	v_accvgpr_write_b32 a94, 0
	v_accvgpr_write_b32 a93, 0
	v_accvgpr_write_b32 a92, 0
	v_accvgpr_write_b32 a91, 0
	v_accvgpr_write_b32 a90, 0
	v_accvgpr_write_b32 a89, 0
	v_accvgpr_write_b32 a88, 0
	v_accvgpr_write_b32 a87, 0
	v_accvgpr_write_b32 a86, 0
	v_accvgpr_write_b32 a85, 0
	v_accvgpr_write_b32 a84, 0
	v_accvgpr_write_b32 a83, 0
	v_accvgpr_write_b32 a82, 0
	v_accvgpr_write_b32 a81, 0
	v_accvgpr_write_b32 a80, 0
	v_accvgpr_write_b32 a79, 0
	v_accvgpr_write_b32 a78, 0
	v_accvgpr_write_b32 a77, 0
	v_accvgpr_write_b32 a76, 0
	v_accvgpr_write_b32 a75, 0
	v_accvgpr_write_b32 a74, 0
	v_accvgpr_write_b32 a73, 0
	v_accvgpr_write_b32 a72, 0
	v_accvgpr_write_b32 a71, 0
	v_accvgpr_write_b32 a70, 0
	v_accvgpr_write_b32 a69, 0
	v_accvgpr_write_b32 a68, 0
	v_accvgpr_write_b32 a67, 0
	v_accvgpr_write_b32 a66, 0
	v_accvgpr_write_b32 a65, 0
	v_accvgpr_write_b32 a64, 0
	v_accvgpr_write_b32 a63, 0
	v_accvgpr_write_b32 a62, 0
	v_accvgpr_write_b32 a61, 0
	v_accvgpr_write_b32 a60, 0
	v_accvgpr_write_b32 a59, 0
	v_accvgpr_write_b32 a58, 0
	v_accvgpr_write_b32 a57, 0
	v_accvgpr_write_b32 a56, 0
	v_accvgpr_write_b32 a55, 0
	v_accvgpr_write_b32 a54, 0
	v_accvgpr_write_b32 a53, 0
	v_accvgpr_write_b32 a52, 0
	v_accvgpr_write_b32 a51, 0
	v_accvgpr_write_b32 a50, 0
	v_accvgpr_write_b32 a49, 0
	v_accvgpr_write_b32 a48, 0
	v_accvgpr_write_b32 a47, 0
	v_accvgpr_write_b32 a46, 0
	v_accvgpr_write_b32 a45, 0
	v_accvgpr_write_b32 a44, 0
	v_accvgpr_write_b32 a43, 0
	v_accvgpr_write_b32 a42, 0
	v_accvgpr_write_b32 a41, 0
	v_accvgpr_write_b32 a40, 0
	v_accvgpr_write_b32 a39, 0
	v_accvgpr_write_b32 a38, 0
	v_accvgpr_write_b32 a37, 0
	v_accvgpr_write_b32 a36, 0
	v_accvgpr_write_b32 a35, 0
	v_accvgpr_write_b32 a34, 0
	v_accvgpr_write_b32 a33, 0
	v_accvgpr_write_b32 a32, 0
	v_accvgpr_write_b32 a31, 0
	v_accvgpr_write_b32 a30, 0
	v_accvgpr_write_b32 a29, 0
	v_accvgpr_write_b32 a28, 0
	v_accvgpr_write_b32 a27, 0
	v_accvgpr_write_b32 a26, 0
	v_accvgpr_write_b32 a25, 0
	v_accvgpr_write_b32 a24, 0
	v_accvgpr_write_b32 a23, 0
	v_accvgpr_write_b32 a22, 0
	v_accvgpr_write_b32 a21, 0
	v_accvgpr_write_b32 a20, 0
	v_accvgpr_write_b32 a19, 0
	v_accvgpr_write_b32 a18, 0
	v_accvgpr_write_b32 a17, 0
	v_accvgpr_write_b32 a16, 0
	v_accvgpr_write_b32 a11, 0
	v_accvgpr_write_b32 a10, 0
	v_accvgpr_write_b32 a9, 0
	v_accvgpr_write_b32 a8, 0
	v_accvgpr_write_b32 a3, 0
	v_accvgpr_write_b32 a2, 0
	v_accvgpr_write_b32 a1, 0
	v_accvgpr_write_b32 a0, 0
	v_accvgpr_write_b32 a7, 0
	v_accvgpr_write_b32 a6, 0
	v_accvgpr_write_b32 a5, 0
	v_accvgpr_write_b32 a4, 0
	v_accvgpr_write_b32 a15, 0
	v_accvgpr_write_b32 a14, 0
	v_accvgpr_write_b32 a13, 0
	v_accvgpr_write_b32 a12, 0
	s_mov_b32 s10, 0
	s_mov_b64 s[0:1], 0
	s_mov_b32 s11, 0
	v_readfirstlane_b32 s100, v2
	s_waitcnt vmcnt(12)
	s_barrier
	s_add_u32 s101, s100, 0x18000
	v_lshl_add_u64 v[88:89], v[132:133], 0, s[0:1]
	s_add_u32 m0, s101, 0x0
	v_lshl_add_u64 v[92:93], v[88:89], 0, s[74:75]
	global_load_lds_dwordx4 v[92:93], off
	s_add_u32 m0, s101, 0x1000
	v_lshl_add_u64 v[92:93], v[88:89], 0, s[76:77]
	global_load_lds_dwordx4 v[92:93], off
	s_add_u32 m0, s101, 0x2000
	v_lshl_add_u64 v[92:93], v[88:89], 0, s[86:87]
	global_load_lds_dwordx4 v[92:93], off
	s_add_u32 m0, s101, 0x3000
	v_lshl_add_u64 v[92:93], v[88:89], 0, s[80:81]
	global_load_lds_dwordx4 v[92:93], off
	s_add_u32 m0, s101, 0x4000
	v_lshl_add_u64 v[92:93], v[88:89], 0, s[72:73]
	global_load_lds_dwordx4 v[92:93], off
	s_add_u32 m0, s101, 0x5000
	v_lshl_add_u64 v[92:93], v[88:89], 0, s[96:97]
	global_load_lds_dwordx4 v[92:93], off
	s_add_u32 m0, s101, 0x6000
	v_lshl_add_u64 v[92:93], v[88:89], 0, s[12:13]
	global_load_lds_dwordx4 v[92:93], off
	s_add_u32 m0, s101, 0x7000
	v_lshl_add_u64 v[92:93], v[88:89], 0, s[16:17]
	global_load_lds_dwordx4 v[92:93], off
	v_lshl_add_u64 v[90:91], v[134:135], 0, s[0:1]
	s_add_u32 m0, s101, 0x8000
	v_lshl_add_u64 v[92:93], v[90:91], 0, s[74:75]
	global_load_lds_dwordx4 v[92:93], off
	s_add_u32 m0, s101, 0x9000
	v_lshl_add_u64 v[92:93], v[90:91], 0, s[76:77]
	global_load_lds_dwordx4 v[92:93], off
	s_add_u32 m0, s101, 0xa000
	v_lshl_add_u64 v[92:93], v[90:91], 0, s[86:87]
	global_load_lds_dwordx4 v[92:93], off
	s_add_u32 m0, s101, 0xb000
	v_lshl_add_u64 v[92:93], v[90:91], 0, s[80:81]
	global_load_lds_dwordx4 v[92:93], off
	s_add_u32 s0, s0, 0x80
	s_addc_u32 s1, s1, 0
	ds_read_b128 v[38:41], v1 offset:0
	ds_read_b128 v[42:45], v1 offset:2048
	ds_read_b128 v[46:49], v1 offset:4096
	ds_read_b128 v[50:53], v1 offset:6144
	ds_read_b128 v[6:9], v0 offset:0
	ds_read_b128 v[10:13], v0 offset:2048
	ds_read_b128 v[14:17], v0 offset:4096
	ds_read_b128 v[18:21], v0 offset:6144
	ds_read_b128 v[22:25], v0 offset:8192
	ds_read_b128 v[26:29], v0 offset:10240
	ds_read_b128 v[30:33], v0 offset:12288
	ds_read_b128 v[34:37], v0 offset:14336
; DI f4 mfma16(h8 a, h8 b, f4 c) { return __builtin_amdgcn_mfma_f32_16x16x32_f16(a, b, c, 0, 0, 0); }
; DI h8 lds128(unsigned a) { h8 r; asm volatile("ds_read_b128 %0, %1" : "=v"(r) : "v"(a)); return r; }
; DI void tie(h8& x) { asm volatile("" : "+v"(x)); }
; #define WAIT_LGKM(n) asm volatile("s_waitcnt lgkmcnt(" #n ")" ::: "memory")
; template <bool PRE = false, class AF, class BF>
; DI void gemm256(AF aptr, BF bptr, int nk, char* smem, f4 (&acc)[8][4]) {
;     ...
;     for (int m = 0; m < 8; m++) a0[m] = lds128(base + offA + m * 2048);
; #pragma unroll
;     for (int n = 0; n < 4; n++) b0[n] = lds128(base + offB + n * 2048);
; #pragma unroll
;     for (int m = 0; m < 8; m++) a1[m] = lds128(base + (offA ^ 64) + m * 2048);
; #pragma unroll
;     for (int n = 0; n < 4; n++) b1[n] = lds128(base + (offB ^ 64) + n * 2048);
;     WAIT_LGKM(12);
; #pragma unroll
;     for (int m = 0; m < 8; m++) tie(a0[m]);
; #pragma unroll
;     for (int n = 0; n < 4; n++) tie(b0[n]);
; #pragma unroll
;     for (int m = 0; m < 8; m++)
; #pragma unroll
;       for (int n = 0; n < 4; n++) acc[m][n] = mfma16(a0[m], b0[n], acc[m][n]);
.Lg_gout_loop:
	s_mul_i32 s21, s11, 0xc000
	v_add_u32_e32 v86, s21, v3
	v_add_u32_e32 v87, s21, v4
	s_waitcnt lgkmcnt(0)
	v_mfma_f32_16x16x32_f16 a[124:127], v[6:9], v[38:41], a[124:127]
	ds_read_b128 a[200:203], v87 offset:0
	v_mfma_f32_16x16x32_f16 a[120:123], v[6:9], v[42:45], a[120:123]
	v_mfma_f32_16x16x32_f16 a[116:119], v[6:9], v[46:49], a[116:119]
	ds_read_b128 a[204:207], v87 offset:2048
	v_mfma_f32_16x16x32_f16 a[112:115], v[6:9], v[50:53], a[112:115]
	v_mfma_f32_16x16x32_f16 a[108:111], v[10:13], v[38:41], a[108:111]
	ds_read_b128 a[208:211], v87 offset:4096
	v_mfma_f32_16x16x32_f16 a[104:107], v[10:13], v[42:45], a[104:107]
	v_mfma_f32_16x16x32_f16 a[100:103], v[10:13], v[46:49], a[100:103]
	ds_read_b128 a[212:215], v87 offset:6144
	v_mfma_f32_16x16x32_f16 a[96:99], v[10:13], v[50:53], a[96:99]
	v_mfma_f32_16x16x32_f16 a[92:95], v[14:17], v[38:41], a[92:95]
	ds_read_b128 v[54:57], v86 offset:0
	v_mfma_f32_16x16x32_f16 a[88:91], v[14:17], v[42:45], a[88:91]
	v_mfma_f32_16x16x32_f16 a[84:87], v[14:17], v[46:49], a[84:87]
	ds_read_b128 v[58:61], v86 offset:2048
	v_mfma_f32_16x16x32_f16 a[80:83], v[14:17], v[50:53], a[80:83]
	v_mfma_f32_16x16x32_f16 a[76:79], v[18:21], v[38:41], a[76:79]
	ds_read_b128 v[62:65], v86 offset:4096
	v_mfma_f32_16x16x32_f16 a[72:75], v[18:21], v[42:45], a[72:75]
	v_mfma_f32_16x16x32_f16 a[68:71], v[18:21], v[46:49], a[68:71]
	ds_read_b128 v[66:69], v86 offset:6144
	v_mfma_f32_16x16x32_f16 a[64:67], v[18:21], v[50:53], a[64:67]
	v_mfma_f32_16x16x32_f16 a[60:63], v[22:25], v[38:41], a[60:63]
	ds_read_b128 v[70:73], v86 offset:8192
	v_mfma_f32_16x16x32_f16 a[56:59], v[22:25], v[42:45], a[56:59]
	v_mfma_f32_16x16x32_f16 a[52:55], v[22:25], v[46:49], a[52:55]
	ds_read_b128 v[74:77], v86 offset:10240
	v_mfma_f32_16x16x32_f16 a[48:51], v[22:25], v[50:53], a[48:51]
	v_mfma_f32_16x16x32_f16 a[44:47], v[26:29], v[38:41], a[44:47]
	ds_read_b128 v[78:81], v86 offset:12288
	v_mfma_f32_16x16x32_f16 a[40:43], v[26:29], v[42:45], a[40:43]
	v_mfma_f32_16x16x32_f16 a[36:39], v[26:29], v[46:49], a[36:39]
	ds_read_b128 v[82:85], v86 offset:14336
	v_mfma_f32_16x16x32_f16 a[32:35], v[26:29], v[50:53], a[32:35]
	v_mfma_f32_16x16x32_f16 a[28:31], v[30:33], v[38:41], a[28:31]
	v_mfma_f32_16x16x32_f16 a[24:27], v[30:33], v[42:45], a[24:27]
	v_mfma_f32_16x16x32_f16 a[20:23], v[30:33], v[46:49], a[20:23]
	v_mfma_f32_16x16x32_f16 a[16:19], v[30:33], v[50:53], a[16:19]
	v_mfma_f32_16x16x32_f16 a[8:11], v[34:37], v[38:41], a[8:11]
	v_mfma_f32_16x16x32_f16 a[0:3], v[34:37], v[42:45], a[0:3]
	v_mfma_f32_16x16x32_f16 a[4:7], v[34:37], v[46:49], a[4:7]
	v_mfma_f32_16x16x32_f16 a[12:15], v[34:37], v[50:53], a[12:15]
	s_cmp_eq_u32 s10, 15
	s_cbranch_scc1 .Lg_gout_last
	s_cmp_lt_u32 s10, 14
	s_cbranch_scc1 .Lg_gout_w12
	s_waitcnt vmcnt(0)
	s_branch .Lg_gout_wd

; DI f4 mfma16(h8 a, h8 b, f4 c) { return __builtin_amdgcn_mfma_f32_16x16x32_f16(a, b, c, 0, 0, 0); }
; DI h8 lds128(unsigned a) { h8 r; asm volatile("ds_read_b128 %0, %1" : "=v"(r) : "v"(a)); return r; }
; DI void tie(h8& x) { asm volatile("" : "+v"(x)); }
; #define WAIT_LGKM(n) asm volatile("s_waitcnt lgkmcnt(" #n ")" ::: "memory")
; template <bool PRE = false, class AF, class BF>
; DI void gemm256(AF aptr, BF bptr, int nk, char* smem, f4 (&acc)[8][4]) {
;     ...
;     if (kt + 2 < nk) issue(kt + 2, st == 0 ? 2 : st - 1);
;     const unsigned base = sbase + st * 49152;
;     st = st == 2 ? 0 : st + 1;
;     h8 a0[8], b0[4], a1[8], b1[4];
; #pragma unroll
;     for (int m = 0; m < 8; m++) a0[m] = lds128(base + offA + m * 2048);
; #pragma unroll
;     for (int n = 0; n < 4; n++) b0[n] = lds128(base + offB + n * 2048);
; #pragma unroll
;     for (int m = 0; m < 8; m++) a1[m] = lds128(base + (offA ^ 64) + m * 2048);
; #pragma unroll
;     for (int n = 0; n < 4; n++) b1[n] = lds128(base + (offB ^ 64) + n * 2048);
;     WAIT_LGKM(12);
; #pragma unroll
;     for (int m = 0; m < 8; m++) tie(a0[m]);
; #pragma unroll
;     for (int n = 0; n < 4; n++) tie(b0[n]);
; #pragma unroll
;     for (int m = 0; m < 8; m++)
; #pragma unroll
;       for (int n = 0; n < 4; n++) acc[m][n] = mfma16(a0[m], b0[n], acc[m][n]);
;     WAIT_LGKM(0);
; #pragma unroll
;     for (int m = 0; m < 8; m++) tie(a1[m]);
; #pragma unroll
;     for (int n = 0; n < 4; n++) tie(b1[n]);
; #pragma unroll
;     for (int m = 0; m < 8; m++)
; #pragma unroll
;       for (int n = 0; n < 4; n++) acc[m][n] = mfma16(a1[m], b1[n], acc[m][n]);
.Lg_gout_wd:
	s_waitcnt lgkmcnt(0)
	s_barrier
	s_add_u32 s20, s11, 1
	s_cmp_eq_u32 s20, 3
	s_cselect_b32 s20, 0, s20
	s_mul_i32 s21, s20, 0xc000
	v_add_u32_e32 v86, s21, v0
	v_add_u32_e32 v87, s21, v1
	s_mul_i32 s101, s11, 0xc000
	s_add_u32 s101, s101, s100
	s_cmp_lt_u32 s10, 13
	s_cbranch_scc0 .Lg_gout_noissue
	v_mfma_f32_16x16x32_f16 a[124:127], v[54:57], a[200:203], a[124:127]
	ds_read_b128 v[38:41], v87 offset:0
	v_mfma_f32_16x16x32_f16 a[120:123], v[54:57], a[204:207], a[120:123]
	v_lshl_add_u64 v[88:89], v[132:133], 0, s[0:1]
	s_add_u32 m0, s101, 0x0
	v_lshl_add_u64 v[92:93], v[88:89], 0, s[74:75]
	global_load_lds_dwordx4 v[92:93], off
	v_mfma_f32_16x16x32_f16 a[116:119], v[54:57], a[208:211], a[116:119]
	ds_read_b128 v[42:45], v87 offset:2048
	v_mfma_f32_16x16x32_f16 a[112:115], v[54:57], a[212:215], a[112:115]
	s_add_u32 m0, s101, 0x1000
	v_lshl_add_u64 v[92:93], v[88:89], 0, s[76:77]
	global_load_lds_dwordx4 v[92:93], off
	v_mfma_f32_16x16x32_f16 a[108:111], v[58:61], a[200:203], a[108:111]
	ds_read_b128 v[46:49], v87 offset:4096
	v_mfma_f32_16x16x32_f16 a[104:107], v[58:61], a[204:207], a[104:107]
	s_add_u32 m0, s101, 0x2000
	v_lshl_add_u64 v[92:93], v[88:89], 0, s[86:87]
	global_load_lds_dwordx4 v[92:93], off
	v_mfma_f32_16x16x32_f16 a[100:103], v[58:61], a[208:211], a[100:103]
	ds_read_b128 v[50:53], v87 offset:6144
	v_mfma_f32_16x16x32_f16 a[96:99], v[58:61], a[212:215], a[96:99]
	s_add_u32 m0, s101, 0x3000
	v_lshl_add_u64 v[92:93], v[88:89], 0, s[80:81]
	global_load_lds_dwordx4 v[92:93], off
	v_mfma_f32_16x16x32_f16 a[92:95], v[62:65], a[200:203], a[92:95]
	ds_read_b128 v[6:9], v86 offset:0
	v_mfma_f32_16x16x32_f16 a[88:91], v[62:65], a[204:207], a[88:91]
	s_add_u32 m0, s101, 0x4000
	v_lshl_add_u64 v[92:93], v[88:89], 0, s[72:73]
	global_load_lds_dwordx4 v[92:93], off
	v_mfma_f32_16x16x32_f16 a[84:87], v[62:65], a[208:211], a[84:87]
	ds_read_b128 v[10:13], v86 offset:2048
	v_mfma_f32_16x16x32_f16 a[80:83], v[62:65], a[212:215], a[80:83]
	s_add_u32 m0, s101, 0x5000
	v_lshl_add_u64 v[92:93], v[88:89], 0, s[96:97]
	global_load_lds_dwordx4 v[92:93], off
	v_mfma_f32_16x16x32_f16 a[76:79], v[66:69], a[200:203], a[76:79]
	ds_read_b128 v[14:17], v86 offset:4096
	v_mfma_f32_16x16x32_f16 a[72:75], v[66:69], a[204:207], a[72:75]
	s_add_u32 m0, s101, 0x6000
	v_lshl_add_u64 v[92:93], v[88:89], 0, s[12:13]
	global_load_lds_dwordx4 v[92:93], off
	v_mfma_f32_16x16x32_f16 a[68:71], v[66:69], a[208:211], a[68:71]
	ds_read_b128 v[18:21], v86 offset:6144
	v_mfma_f32_16x16x32_f16 a[64:67], v[66:69], a[212:215], a[64:67]
	s_add_u32 m0, s101, 0x7000
	v_lshl_add_u64 v[92:93], v[88:89], 0, s[16:17]
	global_load_lds_dwordx4 v[92:93], off
	v_mfma_f32_16x16x32_f16 a[60:63], v[70:73], a[200:203], a[60:63]
	ds_read_b128 v[22:25], v86 offset:8192
	v_mfma_f32_16x16x32_f16 a[56:59], v[70:73], a[204:207], a[56:59]
	v_lshl_add_u64 v[90:91], v[134:135], 0, s[0:1]
	s_add_u32 m0, s101, 0x8000
	v_lshl_add_u64 v[92:93], v[90:91], 0, s[74:75]
	global_load_lds_dwordx4 v[92:93], off
	v_mfma_f32_16x16x32_f16 a[52:55], v[70:73], a[208:211], a[52:55]
	ds_read_b128 v[26:29], v86 offset:10240
	v_mfma_f32_16x16x32_f16 a[48:51], v[70:73], a[212:215], a[48:51]
	s_add_u32 m0, s101, 0x9000
	v_lshl_add_u64 v[92:93], v[90:91], 0, s[76:77]
	global_load_lds_dwordx4 v[92:93], off
	v_mfma_f32_16x16x32_f16 a[44:47], v[74:77], a[200:203], a[44:47]
	ds_read_b128 v[30:33], v86 offset:12288
	v_mfma_f32_16x16x32_f16 a[40:43], v[74:77], a[204:207], a[40:43]
	s_add_u32 m0, s101, 0xa000
	v_lshl_add_u64 v[92:93], v[90:91], 0, s[86:87]
	global_load_lds_dwordx4 v[92:93], off
	v_mfma_f32_16x16x32_f16 a[36:39], v[74:77], a[208:211], a[36:39]
	ds_read_b128 v[34:37], v86 offset:14336
	v_mfma_f32_16x16x32_f16 a[32:35], v[74:77], a[212:215], a[32:35]
	s_add_u32 m0, s101, 0xb000
	v_lshl_add_u64 v[92:93], v[90:91], 0, s[80:81]
	global_load_lds_dwordx4 v[92:93], off
	v_mfma_f32_16x16x32_f16 a[28:31], v[78:81], a[200:203], a[28:31]
	v_mfma_f32_16x16x32_f16 a[24:27], v[78:81], a[204:207], a[24:27]
	v_mfma_f32_16x16x32_f16 a[20:23], v[78:81], a[208:211], a[20:23]
	v_mfma_f32_16x16x32_f16 a[16:19], v[78:81], a[212:215], a[16:19]
	v_mfma_f32_16x16x32_f16 a[8:11], v[82:85], a[200:203], a[8:11]
	v_mfma_f32_16x16x32_f16 a[0:3], v[82:85], a[204:207], a[0:3]
	v_mfma_f32_16x16x32_f16 a[4:7], v[82:85], a[208:211], a[4:7]
	v_mfma_f32_16x16x32_f16 a[12:15], v[82:85], a[212:215], a[12:15]
	s_branch .Lg_gout_next
; DI f4 mfma16(h8 a, h8 b, f4 c) { return __builtin_amdgcn_mfma_f32_16x16x32_f16(a, b, c, 0, 0, 0); }
; DI h8 lds128(unsigned a) { h8 r; asm volatile("ds_read_b128 %0, %1" : "=v"(r) : "v"(a)); return r; }
; DI void tie(h8& x) { asm volatile("" : "+v"(x)); }
; #define WAIT_LGKM(n) asm volatile("s_waitcnt lgkmcnt(" #n ")" ::: "memory")
; template <bool PRE = false, class AF, class BF>
; DI void gemm256(AF aptr, BF bptr, int nk, char* smem, f4 (&acc)[8][4]) {
;     ...
;     if (kt + 2 < nk) issue(kt + 2, st == 0 ? 2 : st - 1);
;     const unsigned base = sbase + st * 49152;
;     st = st == 2 ? 0 : st + 1;
;     h8 a0[8], b0[4], a1[8], b1[4];
; #pragma unroll
;     for (int m = 0; m < 8; m++) a0[m] = lds128(base + offA + m * 2048);
; #pragma unroll
;     for (int n = 0; n < 4; n++) b0[n] = lds128(base + offB + n * 2048);
; #pragma unroll
;     for (int m = 0; m < 8; m++) a1[m] = lds128(base + (offA ^ 64) + m * 2048);
; #pragma unroll
;     for (int n = 0; n < 4; n++) b1[n] = lds128(base + (offB ^ 64) + n * 2048);
;     WAIT_LGKM(12);
; #pragma unroll
;     for (int m = 0; m < 8; m++) tie(a0[m]);
; #pragma unroll
;     for (int n = 0; n < 4; n++) tie(b0[n]);
; #pragma unroll
;     for (int m = 0; m < 8; m++)
; #pragma unroll
;       for (int n = 0; n < 4; n++) acc[m][n] = mfma16(a0[m], b0[n], acc[m][n]);
;     WAIT_LGKM(0);
; #pragma unroll
;     for (int m = 0; m < 8; m++) tie(a1[m]);
; #pragma unroll
;     for (int n = 0; n < 4; n++) tie(b1[n]);
; #pragma unroll
;     for (int m = 0; m < 8; m++)
; #pragma unroll
;       for (int n = 0; n < 4; n++) acc[m][n] = mfma16(a1[m], b1[n], acc[m][n]);
;   }
.Lg_gout_noissue:
	v_mfma_f32_16x16x32_f16 a[124:127], v[54:57], a[200:203], a[124:127]
	ds_read_b128 v[38:41], v87 offset:0
	v_mfma_f32_16x16x32_f16 a[120:123], v[54:57], a[204:207], a[120:123]
	v_mfma_f32_16x16x32_f16 a[116:119], v[54:57], a[208:211], a[116:119]
	ds_read_b128 v[42:45], v87 offset:2048
	v_mfma_f32_16x16x32_f16 a[112:115], v[54:57], a[212:215], a[112:115]
	v_mfma_f32_16x16x32_f16 a[108:111], v[58:61], a[200:203], a[108:111]
	ds_read_b128 v[46:49], v87 offset:4096
	v_mfma_f32_16x16x32_f16 a[104:107], v[58:61], a[204:207], a[104:107]
	v_mfma_f32_16x16x32_f16 a[100:103], v[58:61], a[208:211], a[100:103]
	ds_read_b128 v[50:53], v87 offset:6144
	v_mfma_f32_16x16x32_f16 a[96:99], v[58:61], a[212:215], a[96:99]
	v_mfma_f32_16x16x32_f16 a[92:95], v[62:65], a[200:203], a[92:95]
	ds_read_b128 v[6:9], v86 offset:0
	v_mfma_f32_16x16x32_f16 a[88:91], v[62:65], a[204:207], a[88:91]
	v_mfma_f32_16x16x32_f16 a[84:87], v[62:65], a[208:211], a[84:87]
	ds_read_b128 v[10:13], v86 offset:2048
	v_mfma_f32_16x16x32_f16 a[80:83], v[62:65], a[212:215], a[80:83]
	v_mfma_f32_16x16x32_f16 a[76:79], v[66:69], a[200:203], a[76:79]
	ds_read_b128 v[14:17], v86 offset:4096
	v_mfma_f32_16x16x32_f16 a[72:75], v[66:69], a[204:207], a[72:75]
	v_mfma_f32_16x16x32_f16 a[68:71], v[66:69], a[208:211], a[68:71]
	ds_read_b128 v[18:21], v86 offset:6144
	v_mfma_f32_16x16x32_f16 a[64:67], v[66:69], a[212:215], a[64:67]
	v_mfma_f32_16x16x32_f16 a[60:63], v[70:73], a[200:203], a[60:63]
	ds_read_b128 v[22:25], v86 offset:8192
	v_mfma_f32_16x16x32_f16 a[56:59], v[70:73], a[204:207], a[56:59]
	v_mfma_f32_16x16x32_f16 a[52:55], v[70:73], a[208:211], a[52:55]
	ds_read_b128 v[26:29], v86 offset:10240
	v_mfma_f32_16x16x32_f16 a[48:51], v[70:73], a[212:215], a[48:51]
	v_mfma_f32_16x16x32_f16 a[44:47], v[74:77], a[200:203], a[44:47]
	ds_read_b128 v[30:33], v86 offset:12288
	v_mfma_f32_16x16x32_f16 a[40:43], v[74:77], a[204:207], a[40:43]
	v_mfma_f32_16x16x32_f16 a[36:39], v[74:77], a[208:211], a[36:39]
	ds_read_b128 v[34:37], v86 offset:14336
	v_mfma_f32_16x16x32_f16 a[32:35], v[74:77], a[212:215], a[32:35]
	v_mfma_f32_16x16x32_f16 a[28:31], v[78:81], a[200:203], a[28:31]
	v_mfma_f32_16x16x32_f16 a[24:27], v[78:81], a[204:207], a[24:27]
	v_mfma_f32_16x16x32_f16 a[20:23], v[78:81], a[208:211], a[20:23]
	v_mfma_f32_16x16x32_f16 a[16:19], v[78:81], a[212:215], a[16:19]
	v_mfma_f32_16x16x32_f16 a[8:11], v[82:85], a[200:203], a[8:11]
	v_mfma_f32_16x16x32_f16 a[0:3], v[82:85], a[204:207], a[0:3]
	v_mfma_f32_16x16x32_f16 a[4:7], v[82:85], a[208:211], a[4:7]
	v_mfma_f32_16x16x32_f16 a[12:15], v[82:85], a[212:215], a[12:15]
.Lg_gout_next:
	s_mov_b32 s11, s20
	s_add_u32 s10, s10, 1
	s_add_u32 s0, s0, 0x80
	s_addc_u32 s1, s1, 0
	s_branch .Lg_gout_loop
.Lg_gout_last:
	s_waitcnt lgkmcnt(0)
	v_mfma_f32_16x16x32_f16 a[124:127], v[54:57], a[200:203], a[124:127]
	v_mfma_f32_16x16x32_f16 a[120:123], v[54:57], a[204:207], a[120:123]
	v_mfma_f32_16x16x32_f16 a[116:119], v[54:57], a[208:211], a[116:119]
	v_mfma_f32_16x16x32_f16 a[112:115], v[54:57], a[212:215], a[112:115]
	v_mfma_f32_16x16x32_f16 a[108:111], v[58:61], a[200:203], a[108:111]
	v_mfma_f32_16x16x32_f16 a[104:107], v[58:61], a[204:207], a[104:107]
	v_mfma_f32_16x16x32_f16 a[100:103], v[58:61], a[208:211], a[100:103]
	v_mfma_f32_16x16x32_f16 a[96:99], v[58:61], a[212:215], a[96:99]
	v_mfma_f32_16x16x32_f16 a[92:95], v[62:65], a[200:203], a[92:95]
	v_mfma_f32_16x16x32_f16 a[88:91], v[62:65], a[204:207], a[88:91]
	v_mfma_f32_16x16x32_f16 a[84:87], v[62:65], a[208:211], a[84:87]
	v_mfma_f32_16x16x32_f16 a[80:83], v[62:65], a[212:215], a[80:83]
	v_mfma_f32_16x16x32_f16 a[76:79], v[66:69], a[200:203], a[76:79]
	v_mfma_f32_16x16x32_f16 a[72:75], v[66:69], a[204:207], a[72:75]
	v_mfma_f32_16x16x32_f16 a[68:71], v[66:69], a[208:211], a[68:71]
	v_mfma_f32_16x16x32_f16 a[64:67], v[66:69], a[212:215], a[64:67]
	v_mfma_f32_16x16x32_f16 a[60:63], v[70:73], a[200:203], a[60:63]
	v_mfma_f32_16x16x32_f16 a[56:59], v[70:73], a[204:207], a[56:59]
	v_mfma_f32_16x16x32_f16 a[52:55], v[70:73], a[208:211], a[52:55]
	v_mfma_f32_16x16x32_f16 a[48:51], v[70:73], a[212:215], a[48:51]
	v_mfma_f32_16x16x32_f16 a[44:47], v[74:77], a[200:203], a[44:47]
	v_mfma_f32_16x16x32_f16 a[40:43], v[74:77], a[204:207], a[40:43]
	v_mfma_f32_16x16x32_f16 a[36:39], v[74:77], a[208:211], a[36:39]
	v_mfma_f32_16x16x32_f16 a[32:35], v[74:77], a[212:215], a[32:35]
	v_mfma_f32_16x16x32_f16 a[28:31], v[78:81], a[200:203], a[28:31]
	v_mfma_f32_16x16x32_f16 a[24:27], v[78:81], a[204:207], a[24:27]
	v_mfma_f32_16x16x32_f16 a[20:23], v[78:81], a[208:211], a[20:23]
	v_mfma_f32_16x16x32_f16 a[16:19], v[78:81], a[212:215], a[16:19]
	v_mfma_f32_16x16x32_f16 a[8:11], v[82:85], a[200:203], a[8:11]
	v_mfma_f32_16x16x32_f16 a[0:3], v[82:85], a[204:207], a[0:3]
	v_mfma_f32_16x16x32_f16 a[4:7], v[82:85], a[208:211], a[4:7]
	v_mfma_f32_16x16x32_f16 a[12:15], v[82:85], a[212:215], a[12:15]
	s_nop 7
	s_nop 7

; #define TIDX tid_opaque()
; DI void row2_phase(const Params& P, int l, int r_begin, char* smem) {
;   const int tid = TIDX, lane = tid & 63, wave = tid >> 6, fr = lane & 15, fq = lane >> 4;
;   float* lg = (float*)smem + wave * 16 * 48;
;   const half_t* Whi = P.WrH + (size_t)(l * 2) * 49152; const half_t* Wlo = Whi + 49152;
;   const int ngroups = (TA - r_begin) >> 4, gw = blockIdx.x * 4 + wave, nw = gridDim.x * 4;
;   const float* gam = P.norm2_g + l * 1024;
;   const int gper = (ngroups + nw - 1) / nw;
; #pragma unroll 1
;   for (int grp = gw * gper; grp < min((gw + 1) * gper, ngroups); grp++) {
;     const int r0 = r_begin + grp * 16, row = r0 + fr, n = row_mod(r0);
;     const float* xm = (row < TC ? P.xcbuf + (size_t)row * D : P.out + (size_t)(row - TC) * D) + fq * 8;
.LBB0_542:
	s_or_b64 exec, exec, s[0:1]
	v_readlane_b32 s0, v255, 48
	v_readlane_b32 s1, v255, 49
	s_and_b64 s[0:1], s[0:1], exec
	s_cselect_b32 s22, 0, 0x800
	v_mov_b32_e32 v1, v172
	s_lshr_b32 s0, s22, 4
	s_barrier
	v_accvgpr_write_b32 a200, v82
	v_accvgpr_write_b32 a201, v83
	v_accvgpr_write_b32 a202, v84
	v_accvgpr_write_b32 a203, v85
	v_accvgpr_write_b32 a204, v86
	v_accvgpr_write_b32 a205, v87
	v_accvgpr_write_b32 a206, v88
	v_accvgpr_write_b32 a207, v89
	v_accvgpr_write_b32 a208, v90
	v_accvgpr_write_b32 a209, v91
	v_accvgpr_write_b32 a210, v92
	v_accvgpr_write_b32 a211, v93
	v_accvgpr_write_b32 a212, v94
	v_accvgpr_write_b32 a213, v95
	v_readlane_b32 s100, v255, 26
	v_and_b32_e32 v82, 15, v172
	v_bfe_u32 v83, v172, 4, 2
	v_lshlrev_b32_e32 v82, 11, v82
	v_lshl_or_b32 v82, v83, 4, v82
	v_mov_b32_e32 v83, 0
	s_mul_i32 s100, s100, 0x30000
	s_add_u32 s100, s100, 0xf85c700
	s_mov_b32 s101, 0
	v_lshl_add_u64 v[82:83], s[90:91], 0, v[82:83]
	v_lshl_add_u64 v[82:83], v[82:83], 0, s[100:101]
	s_xor_b32 s1, s0, 0x1080
	v_ashrrev_i32_e32 v2, 6, v1
	v_readlane_b32 s0, v254, 20
	v_readlane_b32 s3, v254, 22
	v_readlane_b32 s6, v254, 25
	v_add_u32_e32 v0, s0, v2
	v_readlane_b32 s0, v254, 21
	s_add_i32 s0, s0, s1
	s_ashr_i32 s2, s0, 31
	s_xor_b32 s2, s2, s3
	s_abs_i32 s0, s0
	v_readlane_b32 s3, v254, 26
	s_mul_hi_u32 s3, s0, s3
	s_mul_i32 s4, s3, s6
	s_sub_i32 s0, s0, s4
	s_add_i32 s4, s3, 1
	s_sub_i32 s5, s0, s6
	s_cmp_ge_u32 s0, s6
	s_cselect_b32 s3, s4, s3
	s_cselect_b32 s0, s5, s0
	s_add_i32 s4, s3, 1
	s_cmp_ge_u32 s0, s6
	s_cselect_b32 s0, s4, s3
	s_xor_b32 s0, s0, s2
	s_sub_i32 s0, s0, s2
	v_mul_lo_u32 v17, v0, s0
	v_add_u32_e32 v3, s0, v17
	v_min_i32_e32 v52, s1, v3
	v_cmp_lt_i32_e32 vcc, v17, v52
	s_and_saveexec_b64 s[10:11], vcc
	s_cbranch_execz .LBB0_551
	v_readlane_b32 s2, v254, 39
	v_readlane_b32 s48, v255, 3
	v_readlane_b32 s3, v254, 40
	v_readlane_b32 s56, v255, 11
	v_readlane_b32 s57, v255, 12
	v_readlane_b32 s58, v255, 13
	v_readlane_b32 s59, v255, 14
	v_readlane_b32 s60, v255, 15
	v_readlane_b32 s61, v255, 16
	s_mov_b32 s3, s85
	v_readlane_b32 s62, v255, 17
	v_readlane_b32 s63, v255, 18
	s_mov_b64 s[56:57], s[60:61]
	s_lshl_b64 s[2:3], s[2:3], 2
	s_mov_b64 s[58:59], s[62:63]
	v_readlane_b32 s49, v255, 4
	v_readlane_b32 s50, v255, 5
	v_readlane_b32 s51, v255, 6
	v_readlane_b32 s52, v255, 7
	v_readlane_b32 s53, v255, 8
	v_readlane_b32 s54, v255, 9
	v_readlane_b32 s55, v255, 10
	s_add_u32 s2, s58, s2
	s_addc_u32 s3, s59, s3
	s_movk_i32 s1, 0xc00
	v_bfe_u32 v4, v1, 4, 2
	v_readlane_b32 s4, v255, 26
	v_readlane_b32 s48, v253, 35
	v_and_b32_e32 v53, 63, v1
	v_and_b32_e32 v54, 15, v1
	v_mul_lo_u32 v3, v2, s1
	v_lshlrev_b32_e32 v12, 5, v4
	v_mov_b32_e32 v13, v149
	s_movk_i32 s1, 0xc0
	s_lshl_b32 s23, s4, 5
	v_readlane_b32 s50, v253, 37
	v_readlane_b32 s6, v254, 41
	v_mul_lo_u32 v0, v0, s0
	v_lshlrev_b32_e32 v2, 3, v4
	v_lshl_add_u64 v[14:15], s[2:3], 0, v[12:13]
	v_lshl_or_b32 v5, v54, 2, v3
	v_mad_u32_u24 v13, v53, s1, v3
	v_mul_u32_u24_e32 v3, 0x300, v4
	v_readlane_b32 s51, v253, 38
	v_readlane_b32 s7, v254, 42
	s_add_u32 s8, s50, s6
	s_mul_hi_u32 s1, s4, 0x30000
	s_mul_i32 s4, s4, 0x30000
	v_lshlrev_b32_e32 v4, 11, v54
	v_and_b32_e32 v16, 48, v1
	v_lshlrev_b32_e32 v0, 4, v0
	v_cmp_gt_u32_e64 s[2:3], 16, v53
	s_addc_u32 s9, s51, s7
	v_or3_b32 v18, s4, v4, v16
	v_mov_b32_e32 v19, s1
	v_add3_u32 v20, s22, v0, v54
	s_mov_b64 s[20:21], 0
	v_lshlrev_b32_e32 v148, 2, v2
	v_add_u32_e32 v55, v5, v3
	v_readlane_b32 s5, v255, 27
	v_readlane_b32 s49, v253, 36
	v_readlane_b32 s52, v253, 39
	v_readlane_b32 s53, v253, 40
	v_readlane_b32 s54, v253, 41
	v_readlane_b32 s55, v253, 42
	v_readlane_b32 s56, v253, 43
	v_readlane_b32 s57, v253, 44
	v_readlane_b32 s58, v253, 45
	v_readlane_b32 s59, v253, 46
	v_readlane_b32 s60, v253, 47
	v_readlane_b32 s61, v253, 48
	v_readlane_b32 s62, v253, 49
	v_readlane_b32 s63, v253, 50
	s_branch .LBB0_545

; DI f4 mfma16(h8 a, h8 b, f4 c) { return __builtin_amdgcn_mfma_f32_16x16x32_f16(a, b, c, 0, 0, 0); }
; DI void row2_phase(const Params& P, int l, int r_begin, char* smem) {
;     ...
;     for (int kk = 0; kk < 32; kk++) {
;       const int k0 = kk * 32;
;       float x[8], g[8], s1[8], s0[8];
;       *(float4*)&x[0] = *(const float4*)(xm + k0); *(float4*)&x[4] = *(const float4*)(xm + k0 + 4);
;       *(float4*)&g[0] = *(const float4*)(gam + fq * 8 + k0); *(float4*)&g[4] = *(const float4*)(gam + fq * 8 + k0 + 4);
;       *(float4*)&s1[0] = *(const float4*)(sc + k0); *(float4*)&s1[4] = *(const float4*)(sc + k0 + 4);
;       *(float4*)&s0[0] = *(const float4*)(sh + k0); *(float4*)&s0[4] = *(const float4*)(sh + k0 + 4);
;       h8 hi, lo;
; #pragma unroll
;       for (int i = 0; i < 8; i++) {
;         float v = x[i] * rstd * g[i] * (1.f + s1[i]) + s0[i];
;         hi[i] = (half_t)v; lo[i] = (half_t)(v - (float)hi[i]);
;       }
;       *(h8*)(hxo + k0) = hi;
; #pragma unroll
;       for (int n3 = 0; n3 < 3; n3++) {
;         h8 bh = *(const h8*)(Whi + (size_t)(n3 * 16 + fr) * 1024 + k0 + fq * 8);
;         h8 bl = *(const h8*)(Wlo + (size_t)(n3 * 16 + fr) * 1024 + k0 + fq * 8);
;         acc[n3] = mfma16(hi, bh, acc[n3]); acc[n3] = mfma16(lo, bh, acc[n3]); acc[n3] = mfma16(hi, bl, acc[n3]);
;       }
;     }
.LBB0_548:
	s_lshr_b32 s100, s0, 1
	s_mov_b32 s101, 0
	v_lshl_add_u64 v[84:85], v[82:83], 0, s[100:101]
	s_add_u32 s100, s100, 0x18000
	v_lshl_add_u64 v[86:87], v[82:83], 0, s[100:101]
	s_sub_u32 s100, s100, 0x10000
	v_lshl_add_u64 v[88:89], v[82:83], 0, s[100:101]
	s_add_u32 s100, s100, 0x18000
	v_lshl_add_u64 v[90:91], v[82:83], 0, s[100:101]
	s_sub_u32 s100, s100, 0x10000
	v_lshl_add_u64 v[92:93], v[82:83], 0, s[100:101]
	s_add_u32 s100, s100, 0x18000
	v_lshl_add_u64 v[94:95], v[82:83], 0, s[100:101]
	v_lshl_add_u64 v[50:51], s[90:91], 0, v[26:27]
	s_mov_b64 s[4:5], 0xce04000
	v_lshl_add_u64 v[32:33], v[50:51], 0, s[4:5]
	s_mov_b64 s[4:5], 0xce03000
	v_lshl_add_u64 v[36:37], v[50:51], 0, s[4:5]
	s_mov_b32 s4, 0xce04000
	v_add_co_u32_e32 v38, vcc, s4, v50
	v_lshl_add_u64 v[10:11], v[22:23], 0, s[0:1]
	s_nop 0
	v_addc_co_u32_e32 v39, vcc, 0, v51, vcc
	s_mov_b32 s4, 0xce03000
	v_lshl_add_u64 v[8:9], v[14:15], 0, s[0:1]
	global_load_dwordx4 v[40:43], v[10:11], off offset:16
	global_load_dwordx4 v[0:3], v[10:11], off
	global_load_dwordx4 v[44:47], v[8:9], off offset:16
	global_load_dwordx4 v[4:7], v[8:9], off
	v_add_co_u32_e32 v34, vcc, s4, v50
	global_load_dwordx4 v[58:61], v[38:39], off
	global_load_dwordx4 v[62:65], v[32:33], off offset:16
	v_addc_co_u32_e32 v35, vcc, 0, v51, vcc
	global_load_dwordx4 v[66:69], v[34:35], off
	global_load_dwordx4 v[70:73], v[36:37], off offset:16
	global_load_dwordx4 a[16:19], v[84:85], off offset:0
	global_load_dwordx4 a[20:23], v[86:87], off offset:0
	global_load_dwordx4 a[24:27], v[88:89], off offset:0
	global_load_dwordx4 a[28:31], v[90:91], off offset:0
	global_load_dwordx4 a[32:35], v[92:93], off offset:0
	global_load_dwordx4 a[36:39], v[94:95], off offset:0
	s_mov_b32 s4, 0xf8bc000
	v_accvgpr_read_b32 v77, a3
	v_accvgpr_read_b32 v76, a2
	v_accvgpr_read_b32 v75, a1
	v_accvgpr_read_b32 v74, a0
	v_accvgpr_mov_b32 a0, a8
	v_accvgpr_mov_b32 a1, a9
	v_accvgpr_mov_b32 a2, a10
	v_accvgpr_mov_b32 a3, a11
	v_accvgpr_write_b32 a8, v74
	v_accvgpr_write_b32 a9, v75
	v_accvgpr_write_b32 a10, v76
	v_accvgpr_write_b32 a11, v77
	s_add_u32 s0, s0, 0x200
	s_addc_u32 s1, s1, 0
	s_cmpk_eq_i32 s0, 0x1000
	s_waitcnt vmcnt(12)
	v_pk_mul_f32 v[0:1], v[28:29], v[0:1]
	v_pk_mul_f32 v[2:3], v[28:29], v[2:3]
	s_waitcnt vmcnt(10)
	v_pk_mul_f32 v[0:1], v[0:1], v[4:5]
	v_pk_mul_f32 v[2:3], v[2:3], v[6:7]
	s_waitcnt vmcnt(9)
	v_pk_add_f32 v[4:5], v[58:59], 1.0 op_sel_hi:[1,0]
	v_pk_add_f32 v[6:7], v[60:61], 1.0 op_sel_hi:[1,0]
	s_waitcnt vmcnt(8)
	v_pk_add_f32 v[36:37], v[64:65], 1.0 op_sel_hi:[1,0]
	s_waitcnt vmcnt(7)
	v_pk_fma_f32 v[4:5], v[0:1], v[4:5], v[66:67]
	v_pk_fma_f32 v[2:3], v[2:3], v[6:7], v[68:69]
	v_cvt_pk_f16_f32 v0, v4, v5
	v_cvt_pk_f16_f32 v1, v2, v3
	v_cvt_f32_f16_e32 v32, v0
	v_cvt_f32_f16_sdwa v33, v0 dst_sel:DWORD dst_unused:UNUSED_PAD src0_sel:WORD_1
	v_cvt_f32_f16_e32 v6, v1
	v_cvt_f32_f16_sdwa v7, v1 dst_sel:DWORD dst_unused:UNUSED_PAD src0_sel:WORD_1
	v_pk_add_f32 v[4:5], v[4:5], v[32:33] neg_lo:[0,1] neg_hi:[0,1]
	s_nop 0
	v_cvt_pk_f16_f32 v4, v4, v5
	v_pk_add_f32 v[2:3], v[2:3], v[6:7] neg_lo:[0,1] neg_hi:[0,1]
	v_pk_add_f32 v[6:7], v[62:63], 1.0 op_sel_hi:[1,0]
	v_cvt_pk_f16_f32 v5, v2, v3
	v_pk_mul_f32 v[2:3], v[28:29], v[40:41]
	v_lshl_add_u64 v[62:63], s[90:91], 0, v[30:31]
	v_pk_mul_f32 v[2:3], v[2:3], v[44:45]
	v_lshl_add_u64 v[30:31], v[30:31], 0, s[74:75]
	s_waitcnt vmcnt(6)
	v_pk_fma_f32 v[6:7], v[2:3], v[6:7], v[70:71]
	s_nop 0
	v_cvt_pk_f16_f32 v2, v6, v7
	v_cvt_f32_f16_e32 v32, v2
	v_cvt_f32_f16_sdwa v33, v2 dst_sel:DWORD dst_unused:UNUSED_PAD src0_sel:WORD_1
	v_pk_add_f32 v[6:7], v[6:7], v[32:33] neg_lo:[0,1] neg_hi:[0,1]
	v_pk_mul_f32 v[32:33], v[28:29], v[42:43]
	v_cvt_pk_f16_f32 v6, v6, v7
	v_pk_mul_f32 v[32:33], v[32:33], v[46:47]
	s_nop 0
	v_pk_fma_f32 v[32:33], v[32:33], v[36:37], v[72:73]
	s_nop 0
	v_cvt_pk_f16_f32 v3, v32, v33
	v_cvt_f32_f16_e32 v36, v3
	v_cvt_f32_f16_sdwa v37, v3 dst_sel:DWORD dst_unused:UNUSED_PAD src0_sel:WORD_1
	v_pk_add_f32 v[32:33], v[32:33], v[36:37] neg_lo:[0,1] neg_hi:[0,1]
	s_nop 0
	v_cvt_pk_f16_f32 v7, v32, v33
	v_lshl_add_u64 v[32:33], s[90:91], 0, v[24:25]
	v_add_co_u32_e32 v32, vcc, s4, v32
	s_mov_b32 s4, 0xf85c000
	s_nop 0
	v_addc_co_u32_e32 v33, vcc, 0, v33, vcc
	v_add_co_u32_e32 v36, vcc, s4, v62
	global_store_dwordx4 v[32:33], v[0:3], off offset:1792
	s_nop 0
	v_addc_co_u32_e32 v37, vcc, 0, v63, vcc
	s_mov_b32 s4, 0xf874000
	v_add_co_u32_e32 v40, vcc, s4, v62
	s_mov_b32 s4, 0xf864000
	s_nop 0
	v_addc_co_u32_e32 v41, vcc, 0, v63, vcc
	v_lshl_add_u64 v[24:25], v[24:25], 0, s[74:75]
	s_waitcnt vmcnt(6)
	v_mfma_f32_16x16x32_f16 a[0:3], v[0:3], a[16:19], a[0:3]
	v_mfma_f32_16x16x32_f16 a[0:3], v[4:7], a[16:19], a[0:3]
	v_add_co_u32_e32 v42, vcc, s4, v62
	s_mov_b32 s4, 0xf87c000
	s_nop 0
	v_addc_co_u32_e32 v43, vcc, 0, v63, vcc
	s_waitcnt vmcnt(5)
	v_mfma_f32_16x16x32_f16 a[0:3], v[0:3], a[20:23], a[0:3]
	v_add_co_u32_e32 v44, vcc, s4, v62
	s_mov_b32 s4, 0xf86c000
	s_nop 0
	v_addc_co_u32_e32 v45, vcc, 0, v63, vcc
	s_waitcnt vmcnt(4)
	v_mfma_f32_16x16x32_f16 a[4:7], v[0:3], a[24:27], a[4:7]
	v_mfma_f32_16x16x32_f16 a[4:7], v[4:7], a[24:27], a[4:7]
	v_add_co_u32_e32 v46, vcc, s4, v62
	s_mov_b32 s4, 0xf884000
	s_nop 0
	v_addc_co_u32_e32 v47, vcc, 0, v63, vcc
	s_waitcnt vmcnt(3)
	v_mfma_f32_16x16x32_f16 a[4:7], v[0:3], a[28:31], a[4:7]
	v_add_co_u32_e32 v48, vcc, s4, v62
	s_mov_b64 s[4:5], 0xce04080
	s_nop 0
	v_addc_co_u32_e32 v49, vcc, 0, v63, vcc
	v_lshl_add_u64 v[70:71], v[50:51], 0, s[4:5]
	s_mov_b64 s[4:5], 0xce03080
	v_lshl_add_u64 v[78:79], v[50:51], 0, s[4:5]
	s_mov_b64 s[4:5], 0xce04100
	s_waitcnt vmcnt(2)
; DI f4 mfma16(h8 a, h8 b, f4 c) { return __builtin_amdgcn_mfma_f32_16x16x32_f16(a, b, c, 0, 0, 0); }
; DI void row2_phase(const Params& P, int l, int r_begin, char* smem) {
;     ...
;     for (int kk = 0; kk < 32; kk++) {
;       const int k0 = kk * 32;
;       float x[8], g[8], s1[8], s0[8];
;       *(float4*)&x[0] = *(const float4*)(xm + k0); *(float4*)&x[4] = *(const float4*)(xm + k0 + 4);
;       *(float4*)&g[0] = *(const float4*)(gam + fq * 8 + k0); *(float4*)&g[4] = *(const float4*)(gam + fq * 8 + k0 + 4);
;       *(float4*)&s1[0] = *(const float4*)(sc + k0); *(float4*)&s1[4] = *(const float4*)(sc + k0 + 4);
;       *(float4*)&s0[0] = *(const float4*)(sh + k0); *(float4*)&s0[4] = *(const float4*)(sh + k0 + 4);
;       h8 hi, lo;
; #pragma unroll
;       for (int i = 0; i < 8; i++) {
;         float v = x[i] * rstd * g[i] * (1.f + s1[i]) + s0[i];
;         hi[i] = (half_t)v; lo[i] = (half_t)(v - (float)hi[i]);
;       }
;       *(h8*)(hxo + k0) = hi;
; #pragma unroll
;       for (int n3 = 0; n3 < 3; n3++) {
;         h8 bh = *(const h8*)(Whi + (size_t)(n3 * 16 + fr) * 1024 + k0 + fq * 8);
;         h8 bl = *(const h8*)(Wlo + (size_t)(n3 * 16 + fr) * 1024 + k0 + fq * 8);
;         acc[n3] = mfma16(hi, bh, acc[n3]); acc[n3] = mfma16(lo, bh, acc[n3]); acc[n3] = mfma16(hi, bl, acc[n3]);
;       }
;     }
	v_mfma_f32_16x16x32_f16 a[8:11], v[0:3], a[32:35], a[8:11]
	v_mfma_f32_16x16x32_f16 a[8:11], v[4:7], a[32:35], a[8:11]
	s_waitcnt vmcnt(1)
	v_mfma_f32_16x16x32_f16 a[8:11], v[0:3], a[36:39], a[8:11]
	global_load_dwordx4 v[0:3], v[10:11], off offset:144
	global_load_dwordx4 v[4:7], v[10:11], off offset:128
	global_load_dwordx4 v[58:61], v[8:9], off offset:144
	global_load_dwordx4 v[62:65], v[8:9], off offset:128
	global_load_dwordx4 v[66:69], v[38:39], off offset:128
	s_nop 0
	global_load_dwordx4 v[70:73], v[70:71], off offset:16
	s_nop 0
	global_load_dwordx4 v[74:77], v[34:35], off offset:128
	s_nop 0
	global_load_dwordx4 v[78:81], v[78:79], off offset:16
	global_load_dwordx4 a[40:43], v[84:85], off offset:64
	global_load_dwordx4 a[44:47], v[86:87], off offset:64
	global_load_dwordx4 a[48:51], v[88:89], off offset:64
	global_load_dwordx4 a[52:55], v[90:91], off offset:64
	global_load_dwordx4 a[56:59], v[92:93], off offset:64
	global_load_dwordx4 a[60:63], v[94:95], off offset:64
	s_waitcnt vmcnt(13)
	v_pk_mul_f32 v[0:1], v[28:29], v[0:1]
	s_waitcnt vmcnt(12)
	v_pk_mul_f32 v[4:5], v[28:29], v[4:5]
	v_pk_mul_f32 v[6:7], v[28:29], v[6:7]
	s_waitcnt vmcnt(10)
	v_pk_mul_f32 v[4:5], v[4:5], v[62:63]
	s_waitcnt vmcnt(9)
	v_pk_add_f32 v[62:63], v[66:67], 1.0 op_sel_hi:[1,0]
	v_pk_mul_f32 v[6:7], v[6:7], v[64:65]
	v_pk_add_f32 v[64:65], v[68:69], 1.0 op_sel_hi:[1,0]
	s_waitcnt vmcnt(7)
	v_pk_fma_f32 v[62:63], v[4:5], v[62:63], v[74:75]
	v_pk_fma_f32 v[6:7], v[6:7], v[64:65], v[76:77]
	v_cvt_pk_f16_f32 v4, v62, v63
	v_cvt_pk_f16_f32 v5, v6, v7
	v_cvt_f32_f16_e32 v66, v4
	v_cvt_f32_f16_sdwa v67, v4 dst_sel:DWORD dst_unused:UNUSED_PAD src0_sel:WORD_1
	v_cvt_f32_f16_e32 v64, v5
	v_cvt_f32_f16_sdwa v65, v5 dst_sel:DWORD dst_unused:UNUSED_PAD src0_sel:WORD_1
	v_pk_mul_f32 v[0:1], v[0:1], v[58:59]
	v_pk_add_f32 v[62:63], v[62:63], v[66:67] neg_lo:[0,1] neg_hi:[0,1]
	v_pk_add_f32 v[6:7], v[6:7], v[64:65] neg_lo:[0,1] neg_hi:[0,1]
	v_cvt_pk_f16_f32 v62, v62, v63
	v_cvt_pk_f16_f32 v63, v6, v7
	v_pk_add_f32 v[6:7], v[70:71], 1.0 op_sel_hi:[1,0]
	v_lshl_add_u64 v[70:71], v[50:51], 0, s[4:5]
	s_waitcnt vmcnt(6)
	v_pk_fma_f32 v[0:1], v[0:1], v[6:7], v[78:79]
	s_mov_b64 s[4:5], 0xce03100
	v_cvt_pk_f16_f32 v6, v0, v1
	v_cvt_f32_f16_e32 v58, v6
	v_cvt_f32_f16_sdwa v59, v6 dst_sel:DWORD dst_unused:UNUSED_PAD src0_sel:WORD_1
	v_lshl_add_u64 v[78:79], v[50:51], 0, s[4:5]
	s_mov_b64 s[4:5], 0xce04180
	v_pk_add_f32 v[0:1], v[0:1], v[58:59] neg_lo:[0,1] neg_hi:[0,1]
	s_nop 0
	v_cvt_pk_f16_f32 v64, v0, v1
	v_pk_mul_f32 v[0:1], v[28:29], v[2:3]
	v_pk_add_f32 v[2:3], v[72:73], 1.0 op_sel_hi:[1,0]
	v_pk_mul_f32 v[0:1], v[0:1], v[60:61]
	s_nop 0
	v_pk_fma_f32 v[0:1], v[0:1], v[2:3], v[80:81]
	s_nop 0
	v_cvt_pk_f16_f32 v7, v0, v1
	v_cvt_f32_f16_e32 v2, v7
	v_cvt_f32_f16_sdwa v3, v7 dst_sel:DWORD dst_unused:UNUSED_PAD src0_sel:WORD_1
	global_store_dwordx4 v[32:33], v[4:7], off offset:1856
	v_pk_add_f32 v[0:1], v[0:1], v[2:3] neg_lo:[0,1] neg_hi:[0,1]
	s_nop 0
	v_cvt_pk_f16_f32 v65, v0, v1
	s_waitcnt vmcnt(6)
	v_mfma_f32_16x16x32_f16 a[0:3], v[4:7], a[40:43], a[0:3]
	v_mfma_f32_16x16x32_f16 a[0:3], v[62:65], a[40:43], a[0:3]
	s_waitcnt vmcnt(5)
	v_mfma_f32_16x16x32_f16 a[0:3], v[4:7], a[44:47], a[0:3]
	s_waitcnt vmcnt(4)
	v_mfma_f32_16x16x32_f16 a[4:7], v[4:7], a[48:51], a[4:7]
	v_mfma_f32_16x16x32_f16 a[4:7], v[62:65], a[48:51], a[4:7]
	s_waitcnt vmcnt(3)
	v_mfma_f32_16x16x32_f16 a[4:7], v[4:7], a[52:55], a[4:7]
	s_waitcnt vmcnt(2)
	v_mfma_f32_16x16x32_f16 a[8:11], v[4:7], a[56:59], a[8:11]
	v_mfma_f32_16x16x32_f16 a[8:11], v[62:65], a[56:59], a[8:11]
	s_waitcnt vmcnt(1)
	v_mfma_f32_16x16x32_f16 a[12:15], v[4:7], a[60:63], a[8:11]
	global_load_dwordx4 v[0:3], v[10:11], off offset:272
	global_load_dwordx4 v[4:7], v[10:11], off offset:256
	global_load_dwordx4 v[58:61], v[8:9], off offset:272
	global_load_dwordx4 v[62:65], v[8:9], off offset:256
	global_load_dwordx4 v[66:69], v[38:39], off offset:256
	s_nop 0
	global_load_dwordx4 v[70:73], v[70:71], off offset:16
	s_nop 0
	global_load_dwordx4 v[74:77], v[34:35], off offset:256
	s_nop 0
	global_load_dwordx4 v[78:81], v[78:79], off offset:16
	global_load_dwordx4 a[64:67], v[84:85], off offset:128
	global_load_dwordx4 a[68:71], v[86:87], off offset:128
	global_load_dwordx4 a[72:75], v[88:89], off offset:128
	global_load_dwordx4 a[76:79], v[90:91], off offset:128
	global_load_dwordx4 a[80:83], v[92:93], off offset:128
	global_load_dwordx4 a[84:87], v[94:95], off offset:128
	s_waitcnt vmcnt(13)
	v_pk_mul_f32 v[0:1], v[28:29], v[0:1]
	s_waitcnt vmcnt(12)
	v_pk_mul_f32 v[4:5], v[28:29], v[4:5]
	v_pk_mul_f32 v[6:7], v[28:29], v[6:7]
	s_waitcnt vmcnt(10)
	v_pk_mul_f32 v[4:5], v[4:5], v[62:63]
	s_waitcnt vmcnt(9)
	v_pk_add_f32 v[62:63], v[66:67], 1.0 op_sel_hi:[1,0]
	v_pk_mul_f32 v[6:7], v[6:7], v[64:65]
	v_pk_add_f32 v[64:65], v[68:69], 1.0 op_sel_hi:[1,0]
	s_waitcnt vmcnt(7)
	v_pk_fma_f32 v[62:63], v[4:5], v[62:63], v[74:75]
	v_pk_fma_f32 v[6:7], v[6:7], v[64:65], v[76:77]
	v_cvt_pk_f16_f32 v4, v62, v63
	v_cvt_pk_f16_f32 v5, v6, v7
	v_cvt_f32_f16_e32 v66, v4
	v_cvt_f32_f16_sdwa v67, v4 dst_sel:DWORD dst_unused:UNUSED_PAD src0_sel:WORD_1
	v_cvt_f32_f16_e32 v64, v5
	v_cvt_f32_f16_sdwa v65, v5 dst_sel:DWORD dst_unused:UNUSED_PAD src0_sel:WORD_1
	v_pk_mul_f32 v[0:1], v[0:1], v[58:59]
	v_pk_add_f32 v[62:63], v[62:63], v[66:67] neg_lo:[0,1] neg_hi:[0,1]
	v_pk_add_f32 v[6:7], v[6:7], v[64:65] neg_lo:[0,1] neg_hi:[0,1]
	v_cvt_pk_f16_f32 v62, v62, v63
	v_cvt_pk_f16_f32 v63, v6, v7
	v_pk_add_f32 v[6:7], v[70:71], 1.0 op_sel_hi:[1,0]
	s_waitcnt vmcnt(6)
; DI f4 mfma16(h8 a, h8 b, f4 c) { return __builtin_amdgcn_mfma_f32_16x16x32_f16(a, b, c, 0, 0, 0); }
; DI void row2_phase(const Params& P, int l, int r_begin, char* smem) {
;     ...
;     for (int kk = 0; kk < 32; kk++) {
;       const int k0 = kk * 32;
;       float x[8], g[8], s1[8], s0[8];
;       *(float4*)&x[0] = *(const float4*)(xm + k0); *(float4*)&x[4] = *(const float4*)(xm + k0 + 4);
;       *(float4*)&g[0] = *(const float4*)(gam + fq * 8 + k0); *(float4*)&g[4] = *(const float4*)(gam + fq * 8 + k0 + 4);
;       *(float4*)&s1[0] = *(const float4*)(sc + k0); *(float4*)&s1[4] = *(const float4*)(sc + k0 + 4);
;       *(float4*)&s0[0] = *(const float4*)(sh + k0); *(float4*)&s0[4] = *(const float4*)(sh + k0 + 4);
;       h8 hi, lo;
; #pragma unroll
;       for (int i = 0; i < 8; i++) {
;         float v = x[i] * rstd * g[i] * (1.f + s1[i]) + s0[i];
;         hi[i] = (half_t)v; lo[i] = (half_t)(v - (float)hi[i]);
;       }
;       *(h8*)(hxo + k0) = hi;
; #pragma unroll
;       for (int n3 = 0; n3 < 3; n3++) {
;         h8 bh = *(const h8*)(Whi + (size_t)(n3 * 16 + fr) * 1024 + k0 + fq * 8);
;         h8 bl = *(const h8*)(Wlo + (size_t)(n3 * 16 + fr) * 1024 + k0 + fq * 8);
;         acc[n3] = mfma16(hi, bh, acc[n3]); acc[n3] = mfma16(lo, bh, acc[n3]); acc[n3] = mfma16(hi, bl, acc[n3]);
;       }
;     }
;     __builtin_amdgcn_wave_barrier();
; #pragma unroll
;     for (int n3 = 0; n3 < 3; n3++)
; #pragma unroll
;       for (int j = 0; j < 4; j++) lg[(fq * 4 + j) * 48 + n3 * 16 + fr] = acc[n3][j];
;     __builtin_amdgcn_wave_barrier();
;     if (lane < 16) {
	v_pk_fma_f32 v[0:1], v[0:1], v[6:7], v[78:79]
	s_nop 0
	v_cvt_pk_f16_f32 v6, v0, v1
	v_cvt_f32_f16_e32 v58, v6
	v_cvt_f32_f16_sdwa v59, v6 dst_sel:DWORD dst_unused:UNUSED_PAD src0_sel:WORD_1
	v_pk_add_f32 v[0:1], v[0:1], v[58:59] neg_lo:[0,1] neg_hi:[0,1]
	s_nop 0
	v_cvt_pk_f16_f32 v64, v0, v1
	v_pk_mul_f32 v[0:1], v[28:29], v[2:3]
	v_pk_add_f32 v[2:3], v[72:73], 1.0 op_sel_hi:[1,0]
	v_pk_mul_f32 v[0:1], v[0:1], v[60:61]
	s_nop 0
	v_pk_fma_f32 v[0:1], v[0:1], v[2:3], v[80:81]
	s_nop 0
	v_cvt_pk_f16_f32 v7, v0, v1
	v_cvt_f32_f16_e32 v2, v7
	v_cvt_f32_f16_sdwa v3, v7 dst_sel:DWORD dst_unused:UNUSED_PAD src0_sel:WORD_1
	global_store_dwordx4 v[32:33], v[4:7], off offset:1920
	v_pk_add_f32 v[0:1], v[0:1], v[2:3] neg_lo:[0,1] neg_hi:[0,1]
	s_nop 0
	v_cvt_pk_f16_f32 v65, v0, v1
	s_waitcnt vmcnt(6)
	v_mfma_f32_16x16x32_f16 a[0:3], v[4:7], a[64:67], a[0:3]
	v_mfma_f32_16x16x32_f16 a[0:3], v[62:65], a[64:67], a[0:3]
	s_waitcnt vmcnt(5)
	v_mfma_f32_16x16x32_f16 a[8:11], v[4:7], a[68:71], a[0:3]
	s_waitcnt vmcnt(4)
	v_mfma_f32_16x16x32_f16 a[0:3], v[4:7], a[72:75], a[4:7]
	v_mfma_f32_16x16x32_f16 a[0:3], v[62:65], a[72:75], a[0:3]
	s_waitcnt vmcnt(3)
	v_mfma_f32_16x16x32_f16 a[4:7], v[4:7], a[76:79], a[0:3]
	s_waitcnt vmcnt(2)
	v_mfma_f32_16x16x32_f16 a[0:3], v[4:7], a[80:83], a[12:15]
	v_mfma_f32_16x16x32_f16 a[0:3], v[62:65], a[80:83], a[0:3]
	s_waitcnt vmcnt(1)
	v_mfma_f32_16x16x32_f16 a[0:3], v[4:7], a[84:87], a[0:3]
	v_lshl_add_u64 v[4:5], v[50:51], 0, s[4:5]
	s_mov_b64 s[4:5], 0xce03180
	v_lshl_add_u64 v[6:7], v[50:51], 0, s[4:5]
	global_load_dwordx4 v[0:3], v[10:11], off offset:400
	global_load_dwordx4 v[58:61], v[10:11], off offset:384
	global_load_dwordx4 v[62:65], v[8:9], off offset:400
	s_nop 0
	global_load_dwordx4 v[8:11], v[8:9], off offset:384
	s_nop 0
	global_load_dwordx4 v[66:69], v[38:39], off offset:384
	global_load_dwordx4 v[70:73], v[4:5], off offset:16
	global_load_dwordx4 v[74:77], v[34:35], off offset:384
	global_load_dwordx4 v[78:81], v[6:7], off offset:16
	global_load_dwordx4 a[88:91], v[84:85], off offset:192
	global_load_dwordx4 a[92:95], v[86:87], off offset:192
	global_load_dwordx4 a[96:99], v[88:89], off offset:192
	global_load_dwordx4 a[100:103], v[90:91], off offset:192
	global_load_dwordx4 a[104:107], v[92:93], off offset:192
	global_load_dwordx4 a[108:111], v[94:95], off offset:192
	s_mov_b64 s[4:5], 0x200
	v_lshl_add_u64 v[26:27], v[26:27], 0, s[4:5]
	s_waitcnt vmcnt(13)
	v_pk_mul_f32 v[0:1], v[28:29], v[0:1]
	s_waitcnt vmcnt(12)
	v_pk_mul_f32 v[4:5], v[28:29], v[58:59]
	s_waitcnt vmcnt(11)
	v_pk_mul_f32 v[0:1], v[0:1], v[62:63]
	s_waitcnt vmcnt(10)
	v_pk_mul_f32 v[4:5], v[4:5], v[8:9]
	s_waitcnt vmcnt(9)
	v_pk_add_f32 v[6:7], v[66:67], 1.0 op_sel_hi:[1,0]
	s_waitcnt vmcnt(7)
	v_pk_fma_f32 v[6:7], v[4:5], v[6:7], v[74:75]
	s_nop 0
	v_cvt_pk_f16_f32 v4, v6, v7
	v_cvt_f32_f16_e32 v8, v4
	v_cvt_f32_f16_sdwa v9, v4 dst_sel:DWORD dst_unused:UNUSED_PAD src0_sel:WORD_1
	v_pk_add_f32 v[6:7], v[6:7], v[8:9] neg_lo:[0,1] neg_hi:[0,1]
	s_nop 0
	v_cvt_pk_f16_f32 v8, v6, v7
	v_pk_mul_f32 v[6:7], v[28:29], v[60:61]
	s_nop 0
	v_pk_mul_f32 v[6:7], v[6:7], v[10:11]
	v_pk_add_f32 v[10:11], v[68:69], 1.0 op_sel_hi:[1,0]
	s_nop 0
	v_pk_fma_f32 v[6:7], v[6:7], v[10:11], v[76:77]
	s_nop 0
	v_cvt_pk_f16_f32 v5, v6, v7
	v_cvt_f32_f16_e32 v10, v5
	v_cvt_f32_f16_sdwa v11, v5 dst_sel:DWORD dst_unused:UNUSED_PAD src0_sel:WORD_1
	v_pk_add_f32 v[6:7], v[6:7], v[10:11] neg_lo:[0,1] neg_hi:[0,1]
	s_nop 0
	v_cvt_pk_f16_f32 v9, v6, v7
	v_pk_add_f32 v[6:7], v[70:71], 1.0 op_sel_hi:[1,0]
	s_waitcnt vmcnt(6)
	v_pk_fma_f32 v[0:1], v[0:1], v[6:7], v[78:79]
	s_nop 0
	v_cvt_pk_f16_f32 v6, v0, v1
	v_cvt_f32_f16_e32 v10, v6
	v_cvt_f32_f16_sdwa v11, v6 dst_sel:DWORD dst_unused:UNUSED_PAD src0_sel:WORD_1
	v_pk_add_f32 v[0:1], v[0:1], v[10:11] neg_lo:[0,1] neg_hi:[0,1]
	s_nop 0
	v_cvt_pk_f16_f32 v10, v0, v1
	v_pk_mul_f32 v[0:1], v[28:29], v[2:3]
	v_pk_add_f32 v[2:3], v[72:73], 1.0 op_sel_hi:[1,0]
	v_pk_mul_f32 v[0:1], v[0:1], v[64:65]
	s_nop 0
	v_pk_fma_f32 v[0:1], v[0:1], v[2:3], v[80:81]
	s_nop 0
	v_cvt_pk_f16_f32 v7, v0, v1
	v_cvt_f32_f16_e32 v2, v7
	v_cvt_f32_f16_sdwa v3, v7 dst_sel:DWORD dst_unused:UNUSED_PAD src0_sel:WORD_1
	global_store_dwordx4 v[32:33], v[4:7], off offset:1984
	v_pk_add_f32 v[0:1], v[0:1], v[2:3] neg_lo:[0,1] neg_hi:[0,1]
	s_nop 0
	v_cvt_pk_f16_f32 v11, v0, v1
	s_waitcnt vmcnt(6)
	v_mfma_f32_16x16x32_f16 a[8:11], v[4:7], a[88:91], a[8:11]
	v_mfma_f32_16x16x32_f16 a[8:11], v[8:11], a[88:91], a[8:11]
	s_waitcnt vmcnt(5)
	v_mfma_f32_16x16x32_f16 a[8:11], v[4:7], a[92:95], a[8:11]
	s_waitcnt vmcnt(4)
	v_mfma_f32_16x16x32_f16 a[4:7], v[4:7], a[96:99], a[4:7]
	v_mfma_f32_16x16x32_f16 a[4:7], v[8:11], a[96:99], a[4:7]
	s_waitcnt vmcnt(3)
	v_mfma_f32_16x16x32_f16 a[4:7], v[4:7], a[100:103], a[4:7]
	s_waitcnt vmcnt(2)
	v_mfma_f32_16x16x32_f16 a[0:3], v[4:7], a[104:107], a[0:3]
	v_mfma_f32_16x16x32_f16 a[0:3], v[8:11], a[104:107], a[0:3]
	s_waitcnt vmcnt(1)
	v_mfma_f32_16x16x32_f16 a[0:3], v[4:7], a[108:111], a[0:3]
	s_cbranch_scc0 .LBB0_548
	s_nop 6
	v_accvgpr_read_b32 v0, a0
	v_accvgpr_read_b32 v4, a4
	v_accvgpr_read_b32 v8, a8
	v_accvgpr_read_b32 v1, a1
	v_accvgpr_read_b32 v2, a2
	v_accvgpr_read_b32 v3, a3
	v_accvgpr_read_b32 v5, a5
	v_accvgpr_read_b32 v6, a6
	v_accvgpr_read_b32 v7, a7
	v_accvgpr_read_b32 v9, a9
	v_accvgpr_read_b32 v10, a10
	v_accvgpr_read_b32 v11, a11
	ds_write2_b32 v55, v8, v4 offset1:16
	ds_write2_b32 v55, v10, v6 offset0:96 offset1:112
	ds_write2_b32 v55, v0, v9 offset0:32 offset1:48
	ds_write2_b32 v55, v5, v1 offset0:64 offset1:80
	ds_write2_b32 v55, v2, v11 offset0:128 offset1:144
	ds_write2_b32 v55, v7, v3 offset0:160 offset1:176
	s_and_saveexec_b64 s[34:35], s[2:3]
	s_cbranch_execz .LBB0_544
; DI void row2_phase(const Params& P, int l, int r_begin, char* smem) {
;     ...
;     if (lane < 16) {
;       const int r = r0 + lane;
;       const float* L = lg + lane * 48;
;       float gl[4]; int gi = 0;
; #pragma unroll
;       for (int j = 0; j < 4; j++) gl[j] = L[j] + P.b_group[l * 4 + j];
;       float gm = gl[0];
; #pragma unroll
;       for (int j = 1; j < 4; j++) if (gl[j] > gm) { gm = gl[j]; gi = j; }
;       float gs = 0.f;
; #pragma unroll
;       for (int j = 0; j < 4; j++) gs += expf(gl[j] - gm);
;       const float pg = 1.f / gs;
;       float el[8];
; #pragma unroll
;       for (int j = 0; j < 8; j++) el[j] = L[4 + gi * 8 + j] + P.b_router[l * 32 + gi * 8 + j];
;       int i0 = 0; float v0 = el[0];
; #pragma unroll
;       for (int j = 1; j < 8; j++) if (el[j] > v0) { v0 = el[j]; i0 = j; }
	global_load_dwordx4 v[4:7], v149, s[8:9]
	ds_read_b128 v[0:3], v13
	s_mov_b32 s28, 0x3fb8aa3b
	s_mov_b32 s38, 0xc2ce8ed0
	s_mov_b32 s39, 0x42b17218
	v_mov_b32_e32 v33, 0x7f800000
	v_readlane_b32 s48, v253, 35
	v_readlane_b32 s54, v253, 41
	v_readlane_b32 s55, v253, 42
	v_readlane_b32 s49, v253, 36
	v_readlane_b32 s50, v253, 37
	v_readlane_b32 s51, v253, 38
	v_readlane_b32 s52, v253, 39
	v_readlane_b32 s53, v253, 40
	v_readlane_b32 s56, v253, 43
	v_readlane_b32 s57, v253, 44
	v_readlane_b32 s58, v253, 45
	v_readlane_b32 s59, v253, 46
	v_readlane_b32 s60, v253, 47
	v_readlane_b32 s61, v253, 48
	v_readlane_b32 s62, v253, 49
	v_readlane_b32 s63, v253, 50
	s_waitcnt vmcnt(0) lgkmcnt(0)
	v_pk_add_f32 v[0:1], v[0:1], v[4:5]
	s_nop 0
	v_cmp_gt_f32_e32 vcc, v1, v0
	v_add_f32_e32 v2, v2, v6
	v_add_f32_e32 v3, v3, v7
	v_cndmask_b32_e32 v4, v0, v1, vcc
	v_cmp_gt_f32_e64 s[0:1], v2, v4
	s_nop 1
	v_cndmask_b32_e64 v4, v4, v2, s[0:1]
	v_cmp_gt_f32_e64 s[4:5], v3, v4
	s_nop 1
	v_cndmask_b32_e64 v4, v4, v3, s[4:5]
	v_sub_f32_e32 v5, v0, v4
	v_sub_f32_e32 v0, v1, v4
	v_mul_f32_e32 v1, 0x3fb8aa3b, v0
	v_fma_f32 v6, v0, s28, -v1
	v_rndne_f32_e32 v7, v1
	v_fmac_f32_e32 v6, 0x32a5705f, v0
	v_sub_f32_e32 v1, v1, v7
	v_add_f32_e32 v1, v1, v6
	v_exp_f32_e32 v1, v1
	v_cvt_i32_f32_e32 v6, v7
	v_cmp_ngt_f32_e64 s[6:7], s38, v0
	v_ldexp_f32 v1, v1, v6
	s_nop 0
	v_cndmask_b32_e64 v1, 0, v1, s[6:7]
	v_cmp_nlt_f32_e64 s[6:7], s39, v0
	v_sub_f32_e32 v0, v2, v4
	s_nop 0
	v_cndmask_b32_e64 v21, v33, v1, s[6:7]
	v_mul_f32_e32 v1, 0x3fb8aa3b, v0
	v_fma_f32 v2, v0, s28, -v1
	v_rndne_f32_e32 v6, v1
	v_fmac_f32_e32 v2, 0x32a5705f, v0
	v_sub_f32_e32 v1, v1, v6
	v_add_f32_e32 v1, v1, v2
	v_exp_f32_e32 v1, v1
	v_cvt_i32_f32_e32 v2, v6
	v_cmp_ngt_f32_e64 s[6:7], s38, v0
	v_ldexp_f32 v1, v1, v2
	s_nop 0
	v_cndmask_b32_e64 v1, 0, v1, s[6:7]
	v_cmp_nlt_f32_e64 s[6:7], s39, v0
	v_sub_f32_e32 v0, v3, v4
	v_or_b32_e32 v4, v56, v53
	v_cndmask_b32_e64 v30, v33, v1, s[6:7]
	v_mul_f32_e32 v1, 0x3fb8aa3b, v0
	v_fma_f32 v2, v0, s28, -v1
	v_rndne_f32_e32 v3, v1
	v_fmac_f32_e32 v2, 0x32a5705f, v0
	v_sub_f32_e32 v1, v1, v3
	v_add_f32_e32 v1, v1, v2
	v_exp_f32_e32 v1, v1
	v_cvt_i32_f32_e32 v2, v3
	v_cmp_ngt_f32_e64 s[6:7], s38, v0
	v_ldexp_f32 v1, v1, v2
	s_nop 0
	v_cndmask_b32_e64 v1, 0, v1, s[6:7]
	v_cmp_nlt_f32_e64 s[6:7], s39, v0
	v_cndmask_b32_e64 v0, 0, 8, vcc
	v_cndmask_b32_e64 v0, v0, 16, s[0:1]
	v_cndmask_b32_e64 v32, v0, 24, s[4:5]
	v_cndmask_b32_e64 v31, v33, v1, s[6:7]
	v_or_b32_e32 v0, s23, v32
	v_mov_b32_e32 v1, v149
	v_lshl_add_u32 v6, v32, 2, v13
	v_lshl_add_u64 v[10:11], v[0:1], 2, s[54:55]
	ds_read_b128 v[0:3], v6 offset:16
	ds_read_b128 v[6:9], v6 offset:32
	global_load_dwordx4 v[22:25], v[10:11], off offset:16
	global_load_dwordx4 v[26:29], v[10:11], off
	v_mul_f32_e32 v10, 0x3fb8aa3b, v5
	v_fma_f32 v11, v5, s28, -v10
	v_fmac_f32_e32 v11, 0x32a5705f, v5
	v_cmp_ngt_f32_e32 vcc, s38, v5
	s_mov_b32 s6, 0xff61b1e6
	s_waitcnt vmcnt(1) lgkmcnt(0)
	v_add_f32_e32 v6, v6, v22
	v_rndne_f32_e32 v22, v10
	v_sub_f32_e32 v10, v10, v22
	v_add_f32_e32 v10, v10, v11
	v_exp_f32_e32 v10, v10
	v_cvt_i32_f32_e32 v11, v22
	s_waitcnt vmcnt(0)
; DI void row2_phase(const Params& P, int l, int r_begin, char* smem) {
;     ...
;       int i0 = 0; float v0 = el[0];
; #pragma unroll
;       for (int j = 1; j < 8; j++) if (el[j] > v0) { v0 = el[j]; i0 = j; }
;       int i1 = -1; float v1 = -3.0e38f;
; #pragma unroll
;       for (int j = 0; j < 8; j++) if (j != i0 && el[j] > v1) { v1 = el[j]; i1 = j; }
;       const float ex = expf(v1 - v0);
;       const float w0 = pg / (1.f + ex), w1 = pg * ex / (1.f + ex);
;       const int e0 = gi * 8 + i0, e1 = gi * 8 + i1;
;       int p0 = atomicAdd(&P.cnt[l * 32 + e0], 1); P.list[(size_t)e0 * LCAP + p0] = 2 * r; P.listW[(size_t)e0 * LCAP + p0] = w0;
;       int p1 = atomicAdd(&P.cnt[l * 32 + e1], 1); P.list[(size_t)e1 * LCAP + p1] = 2 * r + 1; P.listW[(size_t)e1 * LCAP + p1] = w1;
;     }
	v_pk_add_f32 v[0:1], v[0:1], v[26:27]
	v_add_f32_e32 v2, v2, v28
	v_add_f32_e32 v3, v3, v29
	v_ldexp_f32 v10, v10, v11
	v_cndmask_b32_e32 v10, 0, v10, vcc
	v_cmp_nlt_f32_e32 vcc, s39, v5
	v_add_f32_e32 v7, v7, v23
	v_add_f32_e32 v8, v8, v24
	v_cndmask_b32_e32 v5, v33, v10, vcc
	v_cmp_gt_f32_e32 vcc, v1, v0
	v_add_f32_e32 v9, v9, v25
	v_cmp_nlt_f32_e64 s[6:7], s6, v0
	v_cndmask_b32_e32 v11, v0, v1, vcc
	v_cndmask_b32_e64 v10, 0, 1, vcc
	v_cmp_gt_f32_e32 vcc, v2, v11
	v_mov_b32_e32 v22, 0xff61b1e6
	v_add_f32_e32 v5, v5, v21
	v_cndmask_b32_e32 v11, v11, v2, vcc
	v_cndmask_b32_e64 v10, v10, 2, vcc
	v_cmp_gt_f32_e32 vcc, v3, v11
	v_add_f32_e32 v5, v30, v5
	v_add_f32_e32 v5, v31, v5
	v_cndmask_b32_e32 v11, v11, v3, vcc
	v_cndmask_b32_e64 v10, v10, 3, vcc
	v_cmp_gt_f32_e32 vcc, v6, v11
	s_nop 1
	v_cndmask_b32_e32 v11, v11, v6, vcc
	v_cndmask_b32_e64 v10, v10, 4, vcc
	v_cmp_gt_f32_e32 vcc, v7, v11
	s_nop 1
	v_cndmask_b32_e32 v11, v11, v7, vcc
	v_cndmask_b32_e64 v10, v10, 5, vcc
	v_cmp_gt_f32_e32 vcc, v8, v11
	s_nop 1
	v_cndmask_b32_e32 v11, v11, v8, vcc
	v_cndmask_b32_e64 v10, v10, 6, vcc
	v_cmp_ngt_f32_e64 s[0:1], v9, v11
	s_nop 1
	v_cndmask_b32_e64 v10, 7, v10, s[0:1]
	v_cmp_eq_u32_e64 s[4:5], 0, v10
	s_or_b64 s[4:5], s[4:5], s[6:7]
	v_cndmask_b32_e64 v11, v9, v11, s[0:1]
	v_cndmask_b32_e64 v0, v0, v22, s[4:5]
	v_cndmask_b32_e64 v21, 0, -1, s[4:5]
	v_cmp_ne_u32_e64 s[4:5], 1, v10
	v_cmp_gt_f32_e64 s[6:7], v1, v0
	s_and_b64 s[4:5], s[4:5], s[6:7]
	v_cndmask_b32_e64 v0, v0, v1, s[4:5]
	v_cndmask_b32_e64 v21, v21, 1, s[4:5]
	v_cmp_ne_u32_e64 s[4:5], 2, v10
	v_cmp_gt_f32_e64 s[6:7], v2, v0
	s_and_b64 s[4:5], s[4:5], s[6:7]
	v_cndmask_b32_e64 v0, v0, v2, s[4:5]
	v_cndmask_b32_e64 v1, v21, 2, s[4:5]
	v_cmp_ne_u32_e64 s[4:5], 3, v10
	v_cmp_gt_f32_e64 s[6:7], v3, v0
	s_and_b64 s[4:5], s[4:5], s[6:7]
	v_cndmask_b32_e64 v0, v0, v3, s[4:5]
	v_cndmask_b32_e64 v1, v1, 3, s[4:5]
	v_cmp_ne_u32_e64 s[4:5], 4, v10
	v_cmp_gt_f32_e64 s[6:7], v6, v0
	s_and_b64 s[4:5], s[4:5], s[6:7]
	v_cndmask_b32_e64 v0, v0, v6, s[4:5]
	v_cndmask_b32_e64 v1, v1, 4, s[4:5]
	v_cmp_ne_u32_e64 s[4:5], 5, v10
	v_cmp_gt_f32_e64 s[6:7], v7, v0
	s_and_b64 s[4:5], s[4:5], s[6:7]
	v_cndmask_b32_e64 v0, v0, v7, s[4:5]
	v_cndmask_b32_e64 v1, v1, 5, s[4:5]
	s_and_b64 s[4:5], vcc, s[0:1]
	v_cmp_ngt_f32_e32 vcc, v8, v0
	s_or_b64 vcc, s[4:5], vcc
	v_readlane_b32 s4, v255, 24
	v_cndmask_b32_e32 v0, v8, v0, vcc
	v_cndmask_b32_e32 v1, 6, v1, vcc
	v_cmp_gt_f32_e32 vcc, v9, v0
	s_and_b64 vcc, s[0:1], vcc
	v_div_scale_f32 v2, s[0:1], v5, v5, 1.0
	v_rcp_f32_e32 v3, v2
	v_cndmask_b32_e64 v1, v1, 7, vcc
	v_cndmask_b32_e32 v0, v0, v9, vcc
	v_sub_f32_e32 v0, v0, v11
	v_fma_f32 v6, -v2, v3, 1.0
	v_fmac_f32_e32 v3, v6, v3
	v_div_scale_f32 v6, vcc, 1.0, v5, 1.0
	v_mul_f32_e32 v7, v6, v3
	v_fma_f32 v8, -v2, v7, v6
	v_fmac_f32_e32 v7, v8, v3
	v_fma_f32 v2, -v2, v7, v6
	v_div_fmas_f32 v2, v2, v3, v7
	v_mul_f32_e32 v3, 0x3fb8aa3b, v0
	v_div_fixup_f32 v2, v2, v5, 1.0
	v_fma_f32 v5, v0, s28, -v3
	v_rndne_f32_e32 v6, v3
	v_fmac_f32_e32 v5, 0x32a5705f, v0
	v_sub_f32_e32 v3, v3, v6
	v_add_f32_e32 v3, v3, v5
	v_exp_f32_e32 v3, v3
	v_cvt_i32_f32_e32 v5, v6
	v_cmp_ngt_f32_e32 vcc, s38, v0
	s_mov_b32 s28, 0x21000
	v_readlane_b32 s6, v254, 0
	v_ldexp_f32 v3, v3, v5
	v_cndmask_b32_e32 v3, 0, v3, vcc
	v_cmp_nlt_f32_e32 vcc, s39, v0
	v_readlane_b32 s5, v255, 25
	v_readlane_b32 s7, v254, 1
	v_cndmask_b32_e32 v0, v33, v3, vcc
	v_add_f32_e32 v3, 1.0, v0
	v_div_scale_f32 v5, s[0:1], v3, v3, v2
	v_rcp_f32_e32 v6, v5
	v_mul_f32_e32 v0, v2, v0
	v_fma_f32 v7, -v5, v6, 1.0
	v_fmac_f32_e32 v6, v7, v6
	v_div_scale_f32 v7, vcc, v2, v3, v2
	v_mul_f32_e32 v8, v7, v6
	v_fma_f32 v9, -v5, v8, v7
	v_fmac_f32_e32 v8, v9, v6
	v_fma_f32 v5, -v5, v8, v7
	v_div_fmas_f32 v5, v5, v6, v8
	v_div_fixup_f32 v8, v5, v3, v2
	v_div_scale_f32 v2, s[0:1], v3, v3, v0
	v_rcp_f32_e32 v5, v2
	v_readlane_b32 s0, v253, 63
	v_readlane_b32 s1, v255, 0
	v_fma_f32 v6, -v2, v5, 1.0
	v_fmac_f32_e32 v5, v6, v5
	v_div_scale_f32 v6, vcc, v0, v3, v0
	v_mul_f32_e32 v7, v6, v5
	v_fma_f32 v9, -v2, v7, v6
	v_fmac_f32_e32 v7, v9, v5
	v_fma_f32 v2, -v2, v7, v6
	v_div_fmas_f32 v2, v2, v5, v7
	v_or_b32_e32 v5, v10, v32
	v_div_fixup_f32 v2, v2, v3, v0
	v_add_u32_e32 v3, v1, v32
	v_or_b32_e32 v0, s23, v5
	v_mov_b32_e32 v1, v149
	v_lshl_add_u64 v[0:1], v[0:1], 2, s[0:1]
	v_mov_b32_e32 v9, 1
	global_atomic_add v6, v[0:1], v9, off sc0
	v_lshlrev_b32_e32 v0, 1, v4
	v_mul_lo_u32 v4, v5, s28
	v_mov_b32_e32 v5, v149
	s_waitcnt vmcnt(0)
	v_ashrrev_i32_e32 v7, 31, v6
	v_lshl_add_u64 v[4:5], v[4:5], 0, v[6:7]
	v_lshlrev_b64 v[4:5], 2, v[4:5]
	v_lshl_add_u64 v[6:7], s[4:5], 0, v[4:5]
	v_lshl_add_u64 v[4:5], s[6:7], 0, v[4:5]
	global_store_dword v[4:5], v8, off
	v_add_u32_e32 v4, s23, v3
	v_ashrrev_i32_e32 v5, 31, v4
	global_store_dword v[6:7], v0, off
	v_lshl_add_u64 v[4:5], v[4:5], 2, s[0:1]
	global_atomic_add v4, v[4:5], v9, off sc0
	v_or_b32_e32 v6, 1, v0
	s_waitcnt vmcnt(0)
	v_ashrrev_i32_e32 v5, 31, v4
	v_mad_i64_i32 v[0:1], s[0:1], v3, s28, v[4:5]
	v_lshlrev_b64 v[0:1], 2, v[0:1]
	v_lshl_add_u64 v[4:5], s[4:5], 0, v[0:1]
	v_lshl_add_u64 v[0:1], s[6:7], 0, v[0:1]
	global_store_dword v[4:5], v6, off
	global_store_dword v[0:1], v2, off
	s_branch .LBB0_544
.LBB0_551:
	s_or_b64 exec, exec, s[10:11]
	s_waitcnt vmcnt(0)
	s_waitcnt lgkmcnt(0)
	s_barrier
	v_accvgpr_read_b32 v82, a200
	v_accvgpr_read_b32 v83, a201
	v_accvgpr_read_b32 v84, a202
	v_accvgpr_read_b32 v85, a203
	v_accvgpr_read_b32 v86, a204
	v_accvgpr_read_b32 v87, a205
	v_accvgpr_read_b32 v88, a206
	v_accvgpr_read_b32 v89, a207
	v_accvgpr_read_b32 v90, a208
	v_accvgpr_read_b32 v91, a209
	v_accvgpr_read_b32 v92, a210
	v_accvgpr_read_b32 v93, a211
	v_accvgpr_read_b32 v94, a212
	v_accvgpr_read_b32 v95, a213
	s_mov_b64 s[0:1], exec
	v_readlane_b32 s2, v253, 17
	v_readlane_b32 s3, v253, 18
	s_and_b64 s[2:3], s[0:1], s[2:3]
	v_readlane_b32 s22, v255, 26
	v_readlane_b32 s23, v255, 27
	s_mov_b64 exec, s[2:3]
	s_cbranch_execz .LBB0_560
	s_mov_b64 s[4:5], exec
	v_mbcnt_lo_u32_b32 v0, s4, 0
	v_mbcnt_hi_u32_b32 v0, s5, v0
	s_getreg_b32 s6, hwreg(HW_REG_XCC_ID, 0, 4)
	v_cmp_eq_u32_e32 vcc, 0, v0
	s_and_saveexec_b64 s[2:3], vcc
	s_cbranch_execz .LBB0_554
	s_lshl_b32 s6, s6, 6
	s_bcnt1_i32_b64 s4, s[4:5]
	s_and_b32 s6, s6, 0x1c0
	v_mov_b32_e32 v2, s4
	v_readlane_b32 s4, v254, 6
	v_mov_b32_e32 v1, s6
	v_readlane_b32 s5, v254, 7
	s_nop 4
	global_atomic_add v1, v1, v2, s[4:5] sc0

; #define TIDX tid_opaque()
; DI void wait_vm0() { asm volatile("s_waitcnt vmcnt(0)" ::: "memory"); }
; DI unsigned lds_addr(const void* p) { return (unsigned)(size_t)p; }
; DI void raw_barrier() { asm volatile("" ::: "memory"); __builtin_amdgcn_s_barrier(); asm volatile("" ::: "memory"); }
; template <bool PRE = false, class AF, class BF>
; DI void gemm256(AF aptr, BF bptr, int nk, char* smem, f4 (&acc)[8][4]) {
;   const int tid = TIDX, lane = tid & 63, wave = tid >> 6, fr = lane & 15, fq = lane >> 4, wr = wave >> 1, wc = wave & 1;
; #pragma unroll
;   for (int m = 0; m < 8; m++)
; #pragma unroll
;     for (int n = 0; n < 4; n++) acc[m][n] = (f4){0.f, 0.f, 0.f, 0.f};
;   auto issue = [&](int kt, int st) {
;     char* d = smem + st * 49152 + tid * 16;
; #pragma unroll
;     for (int i = 0; i < 8; i++) glds16(aptr(i) + kt * 64, d + i * 4096);
; #pragma unroll
;     for (int i = 0; i < 4; i++) glds16(bptr(i) + kt * 64, d + 32768 + i * 4096);
;   };
;   const unsigned sw = (unsigned)((fq ^ (fr >> 1)) << 4);
;   const unsigned offA = (wr * 128 + fr) * 128 + sw, offB = 32768 + (wc * 64 + fr) * 128 + sw;
;   const unsigned sbase = lds_addr(smem);
;   if (!PRE) { issue(0, 0); if (nk > 1) issue(1, 1); }
;   int st = 0;
; #pragma unroll 1
;   for (int kt = 0; kt < nk; kt++) {
;     if (kt + 1 < nk) asm volatile("s_waitcnt vmcnt(12)" ::: "memory"); else wait_vm0();
;     raw_barrier();
; DI void moe_e1_phase(const Params& P, int l, char* smem, int* tb) {
;     ...
;   auto setup = [&](int rt, int nt, int (&tok)[8], const half_t*& w1, const half_t*& w3) {
;     int e = 0;
;     while (tb[e + 1] <= rt) e++;
;     const int rl = rt - tb[e], cnt = P.cnt[l * 32 + e];
;     const int* lst = P.list + (size_t)e * LCAP;
;     w1 = P.Wt1 + ((size_t)(l * 32 + e) * 512 + nt * 64) * 1024 + sc;
;     w3 = P.Wt3 + ((size_t)(l * 32 + e) * 512 + nt * 64) * 1024 + sc;
; #pragma unroll
;     for (int i = 0; i < 8; i++) tok[i] = lst[min(rl * 256 + i * 32 + srow, cnt - 1)] >> 1;
;   };
;   int it = 0, rt, nt;
;   bool have = next_tile(it, MT, 8, rt, nt);
;   int tok[8]; const half_t* w1 = nullptr; const half_t* w3 = nullptr;
;   if (have) {
;     asm volatile("" : "+s"(rt), "+s"(nt));
;     setup(rt, nt, tok, w1, w3);
;     gemm_prologue([&](int i) { return P.hx + (size_t)tok[i] * D + sc; }, [&](int i) { return ((i & 1) ? w3 : w1) + (size_t)((i >> 1) * 32 + srow) * 1024; }, 16, smem);
.LBB0_578:
	v_mov_b32_e32 v5, v172
	s_mov_b32 s5, 0x8040
	v_lshlrev_b32_e32 v7, 3, v5
	v_and_b32_e32 v9, 48, v5
	v_bitop3_b32 v7, v7, v9, s37 bitop3:0x6c
	v_lshlrev_b32_e32 v9, 7, v5
	v_and_b32_e32 v11, 0xffffc780, v9
	v_and_b32_e32 v9, 0x2780, v9
	v_or_b32_e32 v13, v7, v9
	v_or_b32_e32 v33, v7, v11
	v_or_b32_e32 v35, 0x8000, v13
	v_lshlrev_b32_e32 v37, 4, v5
	v_bitop3_b32 v39, v7, 64, v11 bitop3:0x36
	v_bitop3_b32 v41, v7, s5, v9 bitop3:0x36
	v_ashrrev_i32_e32 v19, 31, v18
	v_ashrrev_i32_e32 v17, 31, v16
	v_ashrrev_i32_e32 v15, 31, v14
	v_ashrrev_i32_e32 v13, 31, v12
	v_ashrrev_i32_e32 v11, 31, v10
	v_ashrrev_i32_e32 v9, 31, v8
	v_ashrrev_i32_e32 v7, 31, v6
	v_ashrrev_i32_e32 v5, 31, v4
	v_lshlrev_b64 v[18:19], 11, v[18:19]
	v_lshlrev_b64 v[16:17], 11, v[16:17]
	v_lshlrev_b64 v[14:15], 11, v[14:15]
	v_lshlrev_b64 v[12:13], 11, v[12:13]
	v_lshlrev_b64 v[10:11], 11, v[10:11]
	v_lshlrev_b64 v[8:9], 11, v[8:9]
	v_lshlrev_b64 v[6:7], 11, v[6:7]
	v_lshlrev_b64 v[4:5], 11, v[4:5]
	v_lshl_add_u64 v[58:59], v[2:3], 0, v[48:49]
	v_lshl_add_u64 v[60:61], v[0:1], 0, v[48:49]
	v_lshl_add_u64 v[62:63], v[54:55], 0, v[4:5]
	v_lshl_add_u64 v[64:65], v[54:55], 0, v[6:7]
	v_lshl_add_u64 v[66:67], v[54:55], 0, v[8:9]
	v_lshl_add_u64 v[68:69], v[54:55], 0, v[10:11]
	v_lshl_add_u64 v[70:71], v[54:55], 0, v[12:13]
	v_lshl_add_u64 v[72:73], v[54:55], 0, v[14:15]
	v_lshl_add_u64 v[74:75], v[54:55], 0, v[16:17]
	v_lshl_add_u64 v[76:77], v[54:55], 0, v[18:19]
	v_accvgpr_write_b32 a3, 0
	v_accvgpr_write_b32 a2, 0
	v_accvgpr_write_b32 a1, 0
	v_accvgpr_write_b32 a0, 0
	v_accvgpr_write_b32 a7, 0
	v_accvgpr_write_b32 a6, 0
	v_accvgpr_write_b32 a5, 0
	v_accvgpr_write_b32 a4, 0
	v_accvgpr_write_b32 a11, 0
	v_accvgpr_write_b32 a10, 0
	v_accvgpr_write_b32 a9, 0
	v_accvgpr_write_b32 a8, 0
	v_accvgpr_write_b32 a19, 0
	v_accvgpr_write_b32 a18, 0
	v_accvgpr_write_b32 a17, 0
	v_accvgpr_write_b32 a16, 0
	v_accvgpr_write_b32 a35, 0
	v_accvgpr_write_b32 a34, 0
	v_accvgpr_write_b32 a33, 0
	v_accvgpr_write_b32 a32, 0
	v_accvgpr_write_b32 a51, 0
	v_accvgpr_write_b32 a50, 0
	v_accvgpr_write_b32 a49, 0
	v_accvgpr_write_b32 a48, 0
	v_accvgpr_write_b32 a67, 0
	v_accvgpr_write_b32 a66, 0
	v_accvgpr_write_b32 a65, 0
	v_accvgpr_write_b32 a64, 0
	v_accvgpr_write_b32 a83, 0
	v_accvgpr_write_b32 a82, 0
	v_accvgpr_write_b32 a81, 0
	v_accvgpr_write_b32 a80, 0
	v_accvgpr_write_b32 a99, 0
	v_accvgpr_write_b32 a98, 0
	v_accvgpr_write_b32 a97, 0
	v_accvgpr_write_b32 a96, 0
	v_accvgpr_write_b32 a115, 0
	v_accvgpr_write_b32 a114, 0
	v_accvgpr_write_b32 a113, 0
	v_accvgpr_write_b32 a112, 0
	v_accvgpr_write_b32 a127, 0
	v_accvgpr_write_b32 a126, 0
	v_accvgpr_write_b32 a125, 0
	v_accvgpr_write_b32 a124, 0
	v_accvgpr_write_b32 a123, 0
	v_accvgpr_write_b32 a122, 0
	v_accvgpr_write_b32 a121, 0
	v_accvgpr_write_b32 a120, 0
	v_accvgpr_write_b32 a119, 0
	v_accvgpr_write_b32 a118, 0
	v_accvgpr_write_b32 a117, 0
	v_accvgpr_write_b32 a116, 0
	v_accvgpr_write_b32 a111, 0
	v_accvgpr_write_b32 a110, 0
	v_accvgpr_write_b32 a109, 0
	v_accvgpr_write_b32 a108, 0
	v_accvgpr_write_b32 a107, 0
	v_accvgpr_write_b32 a106, 0
	v_accvgpr_write_b32 a105, 0
	v_accvgpr_write_b32 a104, 0
	v_accvgpr_write_b32 a103, 0
	v_accvgpr_write_b32 a102, 0
	v_accvgpr_write_b32 a101, 0
	v_accvgpr_write_b32 a100, 0
	v_accvgpr_write_b32 a95, 0
	v_accvgpr_write_b32 a94, 0
	v_accvgpr_write_b32 a93, 0
	v_accvgpr_write_b32 a92, 0
	v_accvgpr_write_b32 a91, 0
	v_accvgpr_write_b32 a90, 0
	v_accvgpr_write_b32 a89, 0
	v_accvgpr_write_b32 a88, 0
	v_accvgpr_write_b32 a87, 0
	v_accvgpr_write_b32 a86, 0
	v_accvgpr_write_b32 a85, 0
	v_accvgpr_write_b32 a84, 0
	v_accvgpr_write_b32 a79, 0
	v_accvgpr_write_b32 a78, 0
	v_accvgpr_write_b32 a77, 0
	v_accvgpr_write_b32 a76, 0
	v_accvgpr_write_b32 a75, 0
	v_accvgpr_write_b32 a74, 0
	v_accvgpr_write_b32 a73, 0
	v_accvgpr_write_b32 a72, 0
	v_accvgpr_write_b32 a71, 0
	v_accvgpr_write_b32 a70, 0
	v_accvgpr_write_b32 a69, 0
	v_accvgpr_write_b32 a68, 0
	v_accvgpr_write_b32 a63, 0
	v_accvgpr_write_b32 a62, 0
	v_accvgpr_write_b32 a61, 0
	v_accvgpr_write_b32 a60, 0
	v_accvgpr_write_b32 a59, 0
	v_accvgpr_write_b32 a58, 0
	v_accvgpr_write_b32 a57, 0
	v_accvgpr_write_b32 a56, 0
	v_accvgpr_write_b32 a55, 0
	v_accvgpr_write_b32 a54, 0
	v_accvgpr_write_b32 a53, 0
	v_accvgpr_write_b32 a52, 0
	v_accvgpr_write_b32 a47, 0
	v_accvgpr_write_b32 a46, 0
	v_accvgpr_write_b32 a45, 0
	v_accvgpr_write_b32 a44, 0
	v_accvgpr_write_b32 a43, 0
	v_accvgpr_write_b32 a42, 0
	v_accvgpr_write_b32 a41, 0
	v_accvgpr_write_b32 a40, 0
	v_accvgpr_write_b32 a39, 0
	v_accvgpr_write_b32 a38, 0
	v_accvgpr_write_b32 a37, 0
	v_accvgpr_write_b32 a36, 0
	v_accvgpr_write_b32 a31, 0
	v_accvgpr_write_b32 a30, 0
	v_accvgpr_write_b32 a29, 0
	v_accvgpr_write_b32 a28, 0
	v_accvgpr_write_b32 a27, 0
	v_accvgpr_write_b32 a26, 0
	v_accvgpr_write_b32 a25, 0
	v_accvgpr_write_b32 a24, 0
	v_accvgpr_write_b32 a23, 0
	v_accvgpr_write_b32 a22, 0
	v_accvgpr_write_b32 a21, 0
	v_accvgpr_write_b32 a20, 0
	v_accvgpr_write_b32 a15, 0
	v_accvgpr_write_b32 a14, 0
	v_accvgpr_write_b32 a13, 0
	v_accvgpr_write_b32 a12, 0
	s_mov_b32 s5, 0
	s_mov_b64 s[6:7], 0
	s_mov_b32 s29, 0
	v_readfirstlane_b32 s100, v37
	s_waitcnt vmcnt(12)
	s_barrier
; DI void wait_vm0() { asm volatile("s_waitcnt vmcnt(0)" ::: "memory"); }
; DI f4 mfma16(h8 a, h8 b, f4 c) { return __builtin_amdgcn_mfma_f32_16x16x32_f16(a, b, c, 0, 0, 0); }
; DI h8 lds128(unsigned a) { h8 r; asm volatile("ds_read_b128 %0, %1" : "=v"(r) : "v"(a)); return r; }
; DI void tie(h8& x) { asm volatile("" : "+v"(x)); }
; DI unsigned lds_addr(const void* p) { return (unsigned)(size_t)p; }
; #define WAIT_LGKM(n) asm volatile("s_waitcnt lgkmcnt(" #n ")" ::: "memory")
; DI void raw_barrier() { asm volatile("" ::: "memory"); __builtin_amdgcn_s_barrier(); asm volatile("" ::: "memory"); }
; template <bool PRE = false, class AF, class BF>
; DI void gemm256(AF aptr, BF bptr, int nk, char* smem, f4 (&acc)[8][4]) {
;     ...
;   auto issue = [&](int kt, int st) {
;     char* d = smem + st * 49152 + tid * 16;
; #pragma unroll
;     for (int i = 0; i < 8; i++) glds16(aptr(i) + kt * 64, d + i * 4096);
; #pragma unroll
;     for (int i = 0; i < 4; i++) glds16(bptr(i) + kt * 64, d + 32768 + i * 4096);
;   };
;   const unsigned sw = (unsigned)((fq ^ (fr >> 1)) << 4);
;   const unsigned offA = (wr * 128 + fr) * 128 + sw, offB = 32768 + (wc * 64 + fr) * 128 + sw;
;   const unsigned sbase = lds_addr(smem);
;   if (!PRE) { issue(0, 0); if (nk > 1) issue(1, 1); }
;   int st = 0;
; #pragma unroll 1
;   for (int kt = 0; kt < nk; kt++) {
;     if (kt + 1 < nk) asm volatile("s_waitcnt vmcnt(12)" ::: "memory"); else wait_vm0();
;     raw_barrier();
;     if (kt + 2 < nk) issue(kt + 2, st == 0 ? 2 : st - 1);
;     const unsigned base = sbase + st * 49152;
;     st = st == 2 ? 0 : st + 1;
;     h8 a0[8], b0[4], a1[8], b1[4];
; #pragma unroll
;     for (int m = 0; m < 8; m++) a0[m] = lds128(base + offA + m * 2048);
; #pragma unroll
;     for (int n = 0; n < 4; n++) b0[n] = lds128(base + offB + n * 2048);
; #pragma unroll
;     for (int m = 0; m < 8; m++) a1[m] = lds128(base + (offA ^ 64) + m * 2048);
; #pragma unroll
;     for (int n = 0; n < 4; n++) b1[n] = lds128(base + (offB ^ 64) + n * 2048);
;     WAIT_LGKM(12);
; #pragma unroll
;     for (int m = 0; m < 8; m++) tie(a0[m]);
; #pragma unroll
;     for (int n = 0; n < 4; n++) tie(b0[n]);
; #pragma unroll
;     for (int m = 0; m < 8; m++)
; #pragma unroll
;       for (int n = 0; n < 4; n++) acc[m][n] = mfma16(a0[m], b0[n], acc[m][n]);
	s_add_u32 s101, s100, 0x18000
	s_add_u32 m0, s101, 0x0
	v_lshl_add_u64 v[14:15], v[76:77], 0, s[6:7]
	global_load_lds_dwordx4 v[14:15], off
	s_add_u32 m0, s101, 0x1000
	v_lshl_add_u64 v[14:15], v[74:75], 0, s[6:7]
	global_load_lds_dwordx4 v[14:15], off
	s_add_u32 m0, s101, 0x2000
	v_lshl_add_u64 v[14:15], v[72:73], 0, s[6:7]
	global_load_lds_dwordx4 v[14:15], off
	s_add_u32 m0, s101, 0x3000
	v_lshl_add_u64 v[14:15], v[70:71], 0, s[6:7]
	global_load_lds_dwordx4 v[14:15], off
	s_add_u32 m0, s101, 0x4000
	v_lshl_add_u64 v[14:15], v[68:69], 0, s[6:7]
	global_load_lds_dwordx4 v[14:15], off
	s_add_u32 m0, s101, 0x5000
	v_lshl_add_u64 v[14:15], v[66:67], 0, s[6:7]
	global_load_lds_dwordx4 v[14:15], off
	s_add_u32 m0, s101, 0x6000
	v_lshl_add_u64 v[14:15], v[64:65], 0, s[6:7]
	global_load_lds_dwordx4 v[14:15], off
	s_add_u32 m0, s101, 0x7000
	v_lshl_add_u64 v[14:15], v[62:63], 0, s[6:7]
	global_load_lds_dwordx4 v[14:15], off
	v_lshl_add_u64 v[10:11], v[58:59], 0, s[6:7]
	s_add_u32 m0, s101, 0x8000
	v_lshl_add_u64 v[14:15], v[10:11], 0, s[74:75]
	global_load_lds_dwordx4 v[14:15], off
	v_lshl_add_u64 v[12:13], v[60:61], 0, s[6:7]
	s_add_u32 m0, s101, 0x9000
	v_lshl_add_u64 v[14:15], v[12:13], 0, s[74:75]
	global_load_lds_dwordx4 v[14:15], off
	s_add_u32 m0, s101, 0xa000
	v_lshl_add_u64 v[14:15], v[10:11], 0, s[76:77]
	global_load_lds_dwordx4 v[14:15], off
	s_add_u32 m0, s101, 0xb000
	v_lshl_add_u64 v[14:15], v[12:13], 0, s[76:77]
	global_load_lds_dwordx4 v[14:15], off
	s_add_u32 s6, s6, 0x80
	s_addc_u32 s7, s7, 0
	ds_read_b128 v[116:119], v35 offset:0
	ds_read_b128 v[120:123], v35 offset:2048
	ds_read_b128 v[124:127], v35 offset:4096
	ds_read_b128 v[128:131], v35 offset:6144
	ds_read_b128 v[84:87], v33 offset:0
	ds_read_b128 v[88:91], v33 offset:2048
	ds_read_b128 v[92:95], v33 offset:4096
	ds_read_b128 v[96:99], v33 offset:6144
	ds_read_b128 v[100:103], v33 offset:8192
	ds_read_b128 v[104:107], v33 offset:10240
	ds_read_b128 v[108:111], v33 offset:12288
	ds_read_b128 v[112:115], v33 offset:14336
.Lg_e1_loop:
	s_mul_i32 s35, s29, 0xc000
	v_add_u32_e32 v8, s35, v39
	v_add_u32_e32 v9, s35, v41
	s_waitcnt lgkmcnt(0)
	v_mfma_f32_16x16x32_f16 a[0:3], v[84:87], v[116:119], a[0:3]
	ds_read_b128 a[200:203], v9 offset:0
	v_mfma_f32_16x16x32_f16 a[4:7], v[84:87], v[120:123], a[4:7]
	v_mfma_f32_16x16x32_f16 a[8:11], v[84:87], v[124:127], a[8:11]
	ds_read_b128 a[204:207], v9 offset:2048
	v_mfma_f32_16x16x32_f16 a[16:19], v[84:87], v[128:131], a[16:19]
	v_mfma_f32_16x16x32_f16 a[32:35], v[88:91], v[116:119], a[32:35]
	ds_read_b128 a[208:211], v9 offset:4096
	v_mfma_f32_16x16x32_f16 a[48:51], v[88:91], v[120:123], a[48:51]
	v_mfma_f32_16x16x32_f16 a[64:67], v[88:91], v[124:127], a[64:67]
	ds_read_b128 a[212:215], v9 offset:6144
	v_mfma_f32_16x16x32_f16 a[80:83], v[88:91], v[128:131], a[80:83]
	v_mfma_f32_16x16x32_f16 a[96:99], v[92:95], v[116:119], a[96:99]
	ds_read_b128 v[132:135], v8 offset:0
	v_mfma_f32_16x16x32_f16 a[112:115], v[92:95], v[120:123], a[112:115]
	v_mfma_f32_16x16x32_f16 a[124:127], v[92:95], v[124:127], a[124:127]
	ds_read_b128 v[136:139], v8 offset:2048
	v_mfma_f32_16x16x32_f16 a[120:123], v[92:95], v[128:131], a[120:123]
	v_mfma_f32_16x16x32_f16 a[116:119], v[96:99], v[116:119], a[116:119]
	ds_read_b128 v[0:3], v8 offset:4096
	v_mfma_f32_16x16x32_f16 a[108:111], v[96:99], v[120:123], a[108:111]
	v_mfma_f32_16x16x32_f16 a[104:107], v[96:99], v[124:127], a[104:107]
	ds_read_b128 v[4:7], v8 offset:6144
	v_mfma_f32_16x16x32_f16 a[100:103], v[96:99], v[128:131], a[100:103]
	v_mfma_f32_16x16x32_f16 a[92:95], v[100:103], v[116:119], a[92:95]
	ds_read_b128 v[144:147], v8 offset:8192
	v_mfma_f32_16x16x32_f16 a[88:91], v[100:103], v[120:123], a[88:91]
	v_mfma_f32_16x16x32_f16 a[84:87], v[100:103], v[124:127], a[84:87]
	ds_read_b128 v[140:143], v8 offset:10240
	v_mfma_f32_16x16x32_f16 a[76:79], v[100:103], v[128:131], a[76:79]
	v_mfma_f32_16x16x32_f16 a[72:75], v[104:107], v[116:119], a[72:75]
	ds_read_b128 v[150:153], v8 offset:12288
	v_mfma_f32_16x16x32_f16 a[68:71], v[104:107], v[120:123], a[68:71]
	v_mfma_f32_16x16x32_f16 a[60:63], v[104:107], v[124:127], a[60:63]
	ds_read_b128 v[154:157], v8 offset:14336
	v_mfma_f32_16x16x32_f16 a[56:59], v[104:107], v[128:131], a[56:59]
	v_mfma_f32_16x16x32_f16 a[52:55], v[108:111], v[116:119], a[52:55]
	v_mfma_f32_16x16x32_f16 a[44:47], v[108:111], v[120:123], a[44:47]
	v_mfma_f32_16x16x32_f16 a[40:43], v[108:111], v[124:127], a[40:43]
	v_mfma_f32_16x16x32_f16 a[36:39], v[108:111], v[128:131], a[36:39]
	v_mfma_f32_16x16x32_f16 a[28:31], v[112:115], v[116:119], a[28:31]
	v_mfma_f32_16x16x32_f16 a[24:27], v[112:115], v[120:123], a[24:27]
	v_mfma_f32_16x16x32_f16 a[20:23], v[112:115], v[124:127], a[20:23]
	v_mfma_f32_16x16x32_f16 a[12:15], v[112:115], v[128:131], a[12:15]
	s_cmp_eq_u32 s5, 15
	s_cbranch_scc1 .Lg_e1_last
	s_cmp_lt_u32 s5, 14
	s_cbranch_scc1 .Lg_e1_w12
	s_waitcnt vmcnt(0)
	s_branch .Lg_e1_wd

; DI f4 mfma16(h8 a, h8 b, f4 c) { return __builtin_amdgcn_mfma_f32_16x16x32_f16(a, b, c, 0, 0, 0); }
; DI h8 lds128(unsigned a) { h8 r; asm volatile("ds_read_b128 %0, %1" : "=v"(r) : "v"(a)); return r; }
; DI void tie(h8& x) { asm volatile("" : "+v"(x)); }
; #define WAIT_LGKM(n) asm volatile("s_waitcnt lgkmcnt(" #n ")" ::: "memory")
; template <bool PRE = false, class AF, class BF>
; DI void gemm256(AF aptr, BF bptr, int nk, char* smem, f4 (&acc)[8][4]) {
;     ...
;     if (kt + 2 < nk) issue(kt + 2, st == 0 ? 2 : st - 1);
;     const unsigned base = sbase + st * 49152;
;     st = st == 2 ? 0 : st + 1;
;     h8 a0[8], b0[4], a1[8], b1[4];
; #pragma unroll
;     for (int m = 0; m < 8; m++) a0[m] = lds128(base + offA + m * 2048);
; #pragma unroll
;     for (int n = 0; n < 4; n++) b0[n] = lds128(base + offB + n * 2048);
; #pragma unroll
;     for (int m = 0; m < 8; m++) a1[m] = lds128(base + (offA ^ 64) + m * 2048);
; #pragma unroll
;     for (int n = 0; n < 4; n++) b1[n] = lds128(base + (offB ^ 64) + n * 2048);
;     WAIT_LGKM(12);
; #pragma unroll
;     for (int m = 0; m < 8; m++) tie(a0[m]);
; #pragma unroll
;     for (int n = 0; n < 4; n++) tie(b0[n]);
; #pragma unroll
;     for (int m = 0; m < 8; m++)
; #pragma unroll
;       for (int n = 0; n < 4; n++) acc[m][n] = mfma16(a0[m], b0[n], acc[m][n]);
.Lg_e1_wd:
	s_waitcnt lgkmcnt(0)
	s_barrier
	s_add_u32 s34, s29, 1
	s_cmp_eq_u32 s34, 3
	s_cselect_b32 s34, 0, s34
	s_mul_i32 s35, s34, 0xc000
	v_add_u32_e32 v8, s35, v33
	v_add_u32_e32 v9, s35, v35
	s_mul_i32 s101, s29, 0xc000
	s_add_u32 s101, s101, s100
	s_cmp_lt_u32 s5, 13
	s_cbranch_scc0 .Lg_e1_noissue
	v_mfma_f32_16x16x32_f16 a[0:3], v[132:135], a[200:203], a[0:3]
	ds_read_b128 v[116:119], v9 offset:0
	v_mfma_f32_16x16x32_f16 a[4:7], v[132:135], a[204:207], a[4:7]
	s_add_u32 m0, s101, 0x0
	v_lshl_add_u64 v[14:15], v[76:77], 0, s[6:7]
	global_load_lds_dwordx4 v[14:15], off
	v_mfma_f32_16x16x32_f16 a[8:11], v[132:135], a[208:211], a[8:11]
	ds_read_b128 v[120:123], v9 offset:2048
	v_mfma_f32_16x16x32_f16 a[16:19], v[132:135], a[212:215], a[16:19]
	s_add_u32 m0, s101, 0x1000
	v_lshl_add_u64 v[14:15], v[74:75], 0, s[6:7]
	global_load_lds_dwordx4 v[14:15], off
	v_mfma_f32_16x16x32_f16 a[32:35], v[136:139], a[200:203], a[32:35]
	ds_read_b128 v[124:127], v9 offset:4096
	v_mfma_f32_16x16x32_f16 a[48:51], v[136:139], a[204:207], a[48:51]
	s_add_u32 m0, s101, 0x2000
	v_lshl_add_u64 v[14:15], v[72:73], 0, s[6:7]
	global_load_lds_dwordx4 v[14:15], off
	v_mfma_f32_16x16x32_f16 a[64:67], v[136:139], a[208:211], a[64:67]
	ds_read_b128 v[128:131], v9 offset:6144
	v_mfma_f32_16x16x32_f16 a[80:83], v[136:139], a[212:215], a[80:83]
	s_add_u32 m0, s101, 0x3000
	v_lshl_add_u64 v[14:15], v[70:71], 0, s[6:7]
	global_load_lds_dwordx4 v[14:15], off
	v_mfma_f32_16x16x32_f16 a[96:99], v[0:3], a[200:203], a[96:99]
	ds_read_b128 v[84:87], v8 offset:0
	v_mfma_f32_16x16x32_f16 a[112:115], v[0:3], a[204:207], a[112:115]
	s_add_u32 m0, s101, 0x4000
	v_lshl_add_u64 v[14:15], v[68:69], 0, s[6:7]
	global_load_lds_dwordx4 v[14:15], off
	v_mfma_f32_16x16x32_f16 a[124:127], v[0:3], a[208:211], a[124:127]
	ds_read_b128 v[88:91], v8 offset:2048
	v_mfma_f32_16x16x32_f16 a[120:123], v[0:3], a[212:215], a[120:123]
	s_add_u32 m0, s101, 0x5000
	v_lshl_add_u64 v[14:15], v[66:67], 0, s[6:7]
	global_load_lds_dwordx4 v[14:15], off
	v_mfma_f32_16x16x32_f16 a[116:119], v[4:7], a[200:203], a[116:119]
	ds_read_b128 v[92:95], v8 offset:4096
	v_mfma_f32_16x16x32_f16 a[108:111], v[4:7], a[204:207], a[108:111]
	s_add_u32 m0, s101, 0x6000
	v_lshl_add_u64 v[14:15], v[64:65], 0, s[6:7]
	global_load_lds_dwordx4 v[14:15], off
	v_mfma_f32_16x16x32_f16 a[104:107], v[4:7], a[208:211], a[104:107]
	ds_read_b128 v[96:99], v8 offset:6144
	v_mfma_f32_16x16x32_f16 a[100:103], v[4:7], a[212:215], a[100:103]
	s_add_u32 m0, s101, 0x7000
	v_lshl_add_u64 v[14:15], v[62:63], 0, s[6:7]
	global_load_lds_dwordx4 v[14:15], off
	v_mfma_f32_16x16x32_f16 a[92:95], v[144:147], a[200:203], a[92:95]
	ds_read_b128 v[100:103], v8 offset:8192
	v_mfma_f32_16x16x32_f16 a[88:91], v[144:147], a[204:207], a[88:91]
	v_lshl_add_u64 v[10:11], v[58:59], 0, s[6:7]
	s_add_u32 m0, s101, 0x8000
	v_lshl_add_u64 v[14:15], v[10:11], 0, s[74:75]
	global_load_lds_dwordx4 v[14:15], off
	v_mfma_f32_16x16x32_f16 a[84:87], v[144:147], a[208:211], a[84:87]
	ds_read_b128 v[104:107], v8 offset:10240
	v_mfma_f32_16x16x32_f16 a[76:79], v[144:147], a[212:215], a[76:79]
	v_lshl_add_u64 v[12:13], v[60:61], 0, s[6:7]
	s_add_u32 m0, s101, 0x9000
	v_lshl_add_u64 v[14:15], v[12:13], 0, s[74:75]
	global_load_lds_dwordx4 v[14:15], off
	v_mfma_f32_16x16x32_f16 a[72:75], v[140:143], a[200:203], a[72:75]
	ds_read_b128 v[108:111], v8 offset:12288
	v_mfma_f32_16x16x32_f16 a[68:71], v[140:143], a[204:207], a[68:71]
	s_add_u32 m0, s101, 0xa000
	v_lshl_add_u64 v[14:15], v[10:11], 0, s[76:77]
	global_load_lds_dwordx4 v[14:15], off
	v_mfma_f32_16x16x32_f16 a[60:63], v[140:143], a[208:211], a[60:63]
	ds_read_b128 v[112:115], v8 offset:14336
	v_mfma_f32_16x16x32_f16 a[56:59], v[140:143], a[212:215], a[56:59]
	s_add_u32 m0, s101, 0xb000
	v_lshl_add_u64 v[14:15], v[12:13], 0, s[76:77]
	global_load_lds_dwordx4 v[14:15], off
	v_mfma_f32_16x16x32_f16 a[52:55], v[150:153], a[200:203], a[52:55]
	v_mfma_f32_16x16x32_f16 a[44:47], v[150:153], a[204:207], a[44:47]
	v_mfma_f32_16x16x32_f16 a[40:43], v[150:153], a[208:211], a[40:43]
	v_mfma_f32_16x16x32_f16 a[36:39], v[150:153], a[212:215], a[36:39]
	v_mfma_f32_16x16x32_f16 a[28:31], v[154:157], a[200:203], a[28:31]
	v_mfma_f32_16x16x32_f16 a[24:27], v[154:157], a[204:207], a[24:27]
	v_mfma_f32_16x16x32_f16 a[20:23], v[154:157], a[208:211], a[20:23]
	v_mfma_f32_16x16x32_f16 a[12:15], v[154:157], a[212:215], a[12:15]
	s_branch .Lg_e1_next
; DI f4 mfma16(h8 a, h8 b, f4 c) { return __builtin_amdgcn_mfma_f32_16x16x32_f16(a, b, c, 0, 0, 0); }
; DI h8 lds128(unsigned a) { h8 r; asm volatile("ds_read_b128 %0, %1" : "=v"(r) : "v"(a)); return r; }
; DI void tie(h8& x) { asm volatile("" : "+v"(x)); }
; #define WAIT_LGKM(n) asm volatile("s_waitcnt lgkmcnt(" #n ")" ::: "memory")
; template <bool PRE = false, class AF, class BF>
; DI void gemm256(AF aptr, BF bptr, int nk, char* smem, f4 (&acc)[8][4]) {
;     ...
;     if (kt + 2 < nk) issue(kt + 2, st == 0 ? 2 : st - 1);
;     const unsigned base = sbase + st * 49152;
;     st = st == 2 ? 0 : st + 1;
;     h8 a0[8], b0[4], a1[8], b1[4];
; #pragma unroll
;     for (int m = 0; m < 8; m++) a0[m] = lds128(base + offA + m * 2048);
; #pragma unroll
;     for (int n = 0; n < 4; n++) b0[n] = lds128(base + offB + n * 2048);
; #pragma unroll
;     for (int m = 0; m < 8; m++) a1[m] = lds128(base + (offA ^ 64) + m * 2048);
; #pragma unroll
;     for (int n = 0; n < 4; n++) b1[n] = lds128(base + (offB ^ 64) + n * 2048);
;     WAIT_LGKM(12);
; #pragma unroll
;     for (int m = 0; m < 8; m++) tie(a0[m]);
; #pragma unroll
;     for (int n = 0; n < 4; n++) tie(b0[n]);
; #pragma unroll
;     for (int m = 0; m < 8; m++)
; #pragma unroll
;       for (int n = 0; n < 4; n++) acc[m][n] = mfma16(a0[m], b0[n], acc[m][n]);
;     WAIT_LGKM(0);
; #pragma unroll
;     for (int m = 0; m < 8; m++) tie(a1[m]);
; #pragma unroll
;     for (int n = 0; n < 4; n++) tie(b1[n]);
; #pragma unroll
;     for (int m = 0; m < 8; m++)
; #pragma unroll
;       for (int n = 0; n < 4; n++) acc[m][n] = mfma16(a1[m], b1[n], acc[m][n]);
;   }
.Lg_e1_noissue:
	v_mfma_f32_16x16x32_f16 a[0:3], v[132:135], a[200:203], a[0:3]
	ds_read_b128 v[116:119], v9 offset:0
	v_mfma_f32_16x16x32_f16 a[4:7], v[132:135], a[204:207], a[4:7]
	v_mfma_f32_16x16x32_f16 a[8:11], v[132:135], a[208:211], a[8:11]
	ds_read_b128 v[120:123], v9 offset:2048
	v_mfma_f32_16x16x32_f16 a[16:19], v[132:135], a[212:215], a[16:19]
	v_mfma_f32_16x16x32_f16 a[32:35], v[136:139], a[200:203], a[32:35]
	ds_read_b128 v[124:127], v9 offset:4096
	v_mfma_f32_16x16x32_f16 a[48:51], v[136:139], a[204:207], a[48:51]
	v_mfma_f32_16x16x32_f16 a[64:67], v[136:139], a[208:211], a[64:67]
	ds_read_b128 v[128:131], v9 offset:6144
	v_mfma_f32_16x16x32_f16 a[80:83], v[136:139], a[212:215], a[80:83]
	v_mfma_f32_16x16x32_f16 a[96:99], v[0:3], a[200:203], a[96:99]
	ds_read_b128 v[84:87], v8 offset:0
	v_mfma_f32_16x16x32_f16 a[112:115], v[0:3], a[204:207], a[112:115]
	v_mfma_f32_16x16x32_f16 a[124:127], v[0:3], a[208:211], a[124:127]
	ds_read_b128 v[88:91], v8 offset:2048
	v_mfma_f32_16x16x32_f16 a[120:123], v[0:3], a[212:215], a[120:123]
	v_mfma_f32_16x16x32_f16 a[116:119], v[4:7], a[200:203], a[116:119]
	ds_read_b128 v[92:95], v8 offset:4096
	v_mfma_f32_16x16x32_f16 a[108:111], v[4:7], a[204:207], a[108:111]
	v_mfma_f32_16x16x32_f16 a[104:107], v[4:7], a[208:211], a[104:107]
	ds_read_b128 v[96:99], v8 offset:6144
	v_mfma_f32_16x16x32_f16 a[100:103], v[4:7], a[212:215], a[100:103]
	v_mfma_f32_16x16x32_f16 a[92:95], v[144:147], a[200:203], a[92:95]
	ds_read_b128 v[100:103], v8 offset:8192
	v_mfma_f32_16x16x32_f16 a[88:91], v[144:147], a[204:207], a[88:91]
	v_mfma_f32_16x16x32_f16 a[84:87], v[144:147], a[208:211], a[84:87]
	ds_read_b128 v[104:107], v8 offset:10240
	v_mfma_f32_16x16x32_f16 a[76:79], v[144:147], a[212:215], a[76:79]
	v_mfma_f32_16x16x32_f16 a[72:75], v[140:143], a[200:203], a[72:75]
	ds_read_b128 v[108:111], v8 offset:12288
	v_mfma_f32_16x16x32_f16 a[68:71], v[140:143], a[204:207], a[68:71]
	v_mfma_f32_16x16x32_f16 a[60:63], v[140:143], a[208:211], a[60:63]
	ds_read_b128 v[112:115], v8 offset:14336
	v_mfma_f32_16x16x32_f16 a[56:59], v[140:143], a[212:215], a[56:59]
	v_mfma_f32_16x16x32_f16 a[52:55], v[150:153], a[200:203], a[52:55]
	v_mfma_f32_16x16x32_f16 a[44:47], v[150:153], a[204:207], a[44:47]
	v_mfma_f32_16x16x32_f16 a[40:43], v[150:153], a[208:211], a[40:43]
	v_mfma_f32_16x16x32_f16 a[36:39], v[150:153], a[212:215], a[36:39]
	v_mfma_f32_16x16x32_f16 a[28:31], v[154:157], a[200:203], a[28:31]
	v_mfma_f32_16x16x32_f16 a[24:27], v[154:157], a[204:207], a[24:27]
	v_mfma_f32_16x16x32_f16 a[20:23], v[154:157], a[208:211], a[20:23]
	v_mfma_f32_16x16x32_f16 a[12:15], v[154:157], a[212:215], a[12:15]
.Lg_e1_next:
	s_mov_b32 s29, s34
	s_add_u32 s5, s5, 1
	s_add_u32 s6, s6, 0x80
	s_addc_u32 s7, s7, 0
	s_branch .Lg_e1_loop
.Lg_e1_last:
	s_waitcnt lgkmcnt(0)
	v_mfma_f32_16x16x32_f16 a[0:3], v[132:135], a[200:203], a[0:3]
	v_mfma_f32_16x16x32_f16 a[4:7], v[132:135], a[204:207], a[4:7]
	v_mfma_f32_16x16x32_f16 a[8:11], v[132:135], a[208:211], a[8:11]
	v_mfma_f32_16x16x32_f16 a[16:19], v[132:135], a[212:215], a[16:19]
	v_mfma_f32_16x16x32_f16 a[32:35], v[136:139], a[200:203], a[32:35]
	v_mfma_f32_16x16x32_f16 a[48:51], v[136:139], a[204:207], a[48:51]
	v_mfma_f32_16x16x32_f16 a[64:67], v[136:139], a[208:211], a[64:67]
	v_mfma_f32_16x16x32_f16 a[80:83], v[136:139], a[212:215], a[80:83]
	v_mfma_f32_16x16x32_f16 a[96:99], v[0:3], a[200:203], a[96:99]
	v_mfma_f32_16x16x32_f16 a[112:115], v[0:3], a[204:207], a[112:115]
	v_mfma_f32_16x16x32_f16 a[124:127], v[0:3], a[208:211], a[124:127]
	v_mfma_f32_16x16x32_f16 a[120:123], v[0:3], a[212:215], a[120:123]
	v_mfma_f32_16x16x32_f16 a[116:119], v[4:7], a[200:203], a[116:119]
	v_mfma_f32_16x16x32_f16 a[108:111], v[4:7], a[204:207], a[108:111]
	v_mfma_f32_16x16x32_f16 a[104:107], v[4:7], a[208:211], a[104:107]
	v_mfma_f32_16x16x32_f16 a[100:103], v[4:7], a[212:215], a[100:103]
	v_mfma_f32_16x16x32_f16 a[92:95], v[144:147], a[200:203], a[92:95]
	v_mfma_f32_16x16x32_f16 a[88:91], v[144:147], a[204:207], a[88:91]
	v_mfma_f32_16x16x32_f16 a[84:87], v[144:147], a[208:211], a[84:87]
	v_mfma_f32_16x16x32_f16 a[76:79], v[144:147], a[212:215], a[76:79]
	v_mfma_f32_16x16x32_f16 a[72:75], v[140:143], a[200:203], a[72:75]
	v_mfma_f32_16x16x32_f16 a[68:71], v[140:143], a[204:207], a[68:71]
	v_mfma_f32_16x16x32_f16 a[60:63], v[140:143], a[208:211], a[60:63]
	v_mfma_f32_16x16x32_f16 a[56:59], v[140:143], a[212:215], a[56:59]
	v_mfma_f32_16x16x32_f16 a[52:55], v[150:153], a[200:203], a[52:55]
	v_mfma_f32_16x16x32_f16 a[44:47], v[150:153], a[204:207], a[44:47]
	v_mfma_f32_16x16x32_f16 a[40:43], v[150:153], a[208:211], a[40:43]
	v_mfma_f32_16x16x32_f16 a[36:39], v[150:153], a[212:215], a[36:39]
	v_mfma_f32_16x16x32_f16 a[28:31], v[154:157], a[200:203], a[28:31]
	v_mfma_f32_16x16x32_f16 a[24:27], v[154:157], a[204:207], a[24:27]
	v_mfma_f32_16x16x32_f16 a[20:23], v[154:157], a[208:211], a[20:23]
	v_mfma_f32_16x16x32_f16 a[12:15], v[154:157], a[212:215], a[12:15]
	s_nop 7
	s_nop 7

; DI void moe_e2_phase(const Params& P, int l, char* smem, int* tb) {
;     ...
;     int e = 0;
;     while (tb[e + 1] <= rt) e++;
;     const int rl = rt - tb[e], cnt = P.cnt[l * 32 + e];
;     const int* lst = P.list + (size_t)e * LCAP; const float* lstw = P.listW + (size_t)e * LCAP;
;     int aa[2][8]; float ww[2][8];
; #pragma unroll
;     for (int h = 0; h < 2; h++)
; #pragma unroll
;       for (int i = 0; i < 8; i++) {
;         const int idx = rl * 256 + wr2 * 128 + h * 64 + ((i * 64 + lane2) >> 3);
;         const int ic = min(idx, cnt - 1);
;         const int av = lst[ic]; const float wv = lstw[ic];
;         aa[h][i] = idx < cnt ? av : -1; ww[h][i] = wv;
.LBB0_612:
	v_mov_b32_e32 v0, s2
	ds_read_b32 v0, v0 offset:8
	s_add_i32 s1, s1, 1
	s_add_i32 s2, s2, 4
	s_waitcnt lgkmcnt(0)
	v_cmp_ge_i32_e32 vcc, s0, v0
	s_cbranch_vccnz .LBB0_612
	s_add_i32 s84, s1, s20
	v_mov_b32_e32 v0, s2
	s_lshl_b64 s[2:3], s[84:85], 2
	v_readlane_b32 s4, v253, 63
	v_readlane_b32 s5, v255, 0
	s_add_u32 s2, s4, s2
	s_addc_u32 s3, s5, s3
	global_load_dword v33, v149, s[2:3]
	ds_read_b32 v0, v0
	v_and_b32_e32 v1, 0xffffff80, v87
	s_mul_hi_u32 s3, s1, 0x84000
	s_mul_i32 s1, s1, 0x84000
	v_readlane_b32 s4, v255, 24
	s_waitcnt lgkmcnt(0)
	v_sub_u32_e32 v0, s0, v0
	v_lshl_add_u32 v1, v0, 8, v1
	v_bfe_u32 v86, v87, 3, 3
	v_readlane_b32 s5, v255, 25
	s_add_u32 s4, s4, s1
	v_or_b32_e32 v88, v1, v86
	s_addc_u32 s5, s5, s3
	v_readlane_b32 s22, v254, 0
	v_readlane_b32 s23, v254, 1
	s_add_u32 s2, s22, s1
	s_addc_u32 s3, s23, s3
	v_or_b32_e32 v83, 8, v86
	v_or_b32_e32 v84, v1, v83
	v_or_b32_e32 v80, 16, v86
	v_or_b32_e32 v81, v1, v80
	v_or_b32_e32 v77, 24, v86
	v_or_b32_e32 v78, v1, v77
	v_or_b32_e32 v74, 32, v86
	v_or_b32_e32 v75, v1, v74
	v_or_b32_e32 v69, 40, v86
	v_or_b32_e32 v70, v1, v69
	v_or_b32_e32 v66, 48, v86
	v_or_b32_e32 v67, v1, v66
	v_or_b32_e32 v63, 56, v86
	v_or_b32_e32 v64, v1, v63
	v_or_b32_e32 v1, 64, v1
	v_or_b32_e32 v72, v1, v86
	v_or_b32_e32 v59, v1, v83
	v_or_b32_e32 v55, v1, v80
	v_or_b32_e32 v51, v1, v77
	v_or_b32_e32 v47, v1, v74
	v_or_b32_e32 v43, v1, v69
	v_or_b32_e32 v39, v1, v66
	v_or_b32_e32 v35, v1, v63
	s_mov_b32 s1, 0x8040
	v_accvgpr_write_b32 a3, 0
	v_accvgpr_write_b32 a2, 0
	v_accvgpr_write_b32 a1, 0
	v_accvgpr_write_b32 a0, 0
	v_accvgpr_write_b32 a7, 0
	v_accvgpr_write_b32 a6, 0
	v_accvgpr_write_b32 a5, 0
	v_accvgpr_write_b32 a4, 0
	v_accvgpr_write_b32 a11, 0
	v_accvgpr_write_b32 a10, 0
	v_accvgpr_write_b32 a9, 0
	v_accvgpr_write_b32 a8, 0
	v_accvgpr_write_b32 a19, 0
	v_accvgpr_write_b32 a18, 0
	v_accvgpr_write_b32 a17, 0
	v_accvgpr_write_b32 a16, 0
	v_accvgpr_write_b32 a35, 0
	v_accvgpr_write_b32 a34, 0
	v_accvgpr_write_b32 a33, 0
	v_accvgpr_write_b32 a32, 0
	v_accvgpr_write_b32 a51, 0
	v_accvgpr_write_b32 a50, 0
	v_accvgpr_write_b32 a49, 0
	v_accvgpr_write_b32 a48, 0
	v_accvgpr_write_b32 a67, 0
	v_accvgpr_write_b32 a66, 0
	v_accvgpr_write_b32 a65, 0
	v_accvgpr_write_b32 a64, 0
	v_accvgpr_write_b32 a83, 0
	v_accvgpr_write_b32 a82, 0
	v_accvgpr_write_b32 a81, 0
	v_accvgpr_write_b32 a80, 0
	v_accvgpr_write_b32 a99, 0
	v_accvgpr_write_b32 a98, 0
	v_accvgpr_write_b32 a97, 0
	v_accvgpr_write_b32 a96, 0
	v_accvgpr_write_b32 a115, 0
	v_accvgpr_write_b32 a114, 0
	v_accvgpr_write_b32 a113, 0
	s_waitcnt vmcnt(0)
	v_add_u32_e32 v0, -1, v33
	v_min_i32_e32 v2, v88, v0
	v_ashrrev_i32_e32 v3, 31, v2
	v_lshlrev_b64 v[2:3], 2, v[2:3]
	v_lshl_add_u64 v[4:5], s[4:5], 0, v[2:3]
	v_lshl_add_u64 v[2:3], s[2:3], 0, v[2:3]
	global_load_dword v89, v[4:5], off
	global_load_dword v62, v[2:3], off
	v_min_i32_e32 v2, v84, v0
	v_ashrrev_i32_e32 v3, 31, v2
	v_lshlrev_b64 v[2:3], 2, v[2:3]
	v_lshl_add_u64 v[4:5], s[4:5], 0, v[2:3]
	v_lshl_add_u64 v[2:3], s[2:3], 0, v[2:3]
	global_load_dword v85, v[4:5], off
	global_load_dword v60, v[2:3], off
	v_min_i32_e32 v2, v81, v0
	v_ashrrev_i32_e32 v3, 31, v2
	v_lshlrev_b64 v[2:3], 2, v[2:3]
	v_lshl_add_u64 v[4:5], s[4:5], 0, v[2:3]
	v_lshl_add_u64 v[2:3], s[2:3], 0, v[2:3]
	global_load_dword v82, v[4:5], off
	global_load_dword v58, v[2:3], off
	v_min_i32_e32 v2, v78, v0
	v_ashrrev_i32_e32 v3, 31, v2
	v_lshlrev_b64 v[2:3], 2, v[2:3]
	v_lshl_add_u64 v[4:5], s[4:5], 0, v[2:3]
	v_lshl_add_u64 v[2:3], s[2:3], 0, v[2:3]
	global_load_dword v79, v[4:5], off
	global_load_dword v56, v[2:3], off
	v_min_i32_e32 v2, v75, v0
	v_ashrrev_i32_e32 v3, 31, v2
	v_lshlrev_b64 v[2:3], 2, v[2:3]
	v_lshl_add_u64 v[4:5], s[4:5], 0, v[2:3]
	v_lshl_add_u64 v[2:3], s[2:3], 0, v[2:3]
	global_load_dword v76, v[4:5], off
	global_load_dword v54, v[2:3], off
	v_min_i32_e32 v2, v70, v0
	v_ashrrev_i32_e32 v3, 31, v2
	v_lshlrev_b64 v[2:3], 2, v[2:3]
	v_lshl_add_u64 v[4:5], s[4:5], 0, v[2:3]
	v_lshl_add_u64 v[2:3], s[2:3], 0, v[2:3]
	global_load_dword v71, v[4:5], off
	global_load_dword v52, v[2:3], off
	v_min_i32_e32 v2, v67, v0
	v_ashrrev_i32_e32 v3, 31, v2
	v_lshlrev_b64 v[2:3], 2, v[2:3]
	v_lshl_add_u64 v[4:5], s[4:5], 0, v[2:3]
	v_lshl_add_u64 v[2:3], s[2:3], 0, v[2:3]
	global_load_dword v68, v[4:5], off
	global_load_dword v50, v[2:3], off
	v_min_i32_e32 v2, v64, v0
	v_ashrrev_i32_e32 v3, 31, v2
	v_lshlrev_b64 v[2:3], 2, v[2:3]
	v_lshl_add_u64 v[4:5], s[4:5], 0, v[2:3]
	v_lshl_add_u64 v[2:3], s[2:3], 0, v[2:3]
	global_load_dword v65, v[4:5], off
	global_load_dword v48, v[2:3], off
	v_min_i32_e32 v2, v72, v0
	v_ashrrev_i32_e32 v3, 31, v2
	v_lshlrev_b64 v[2:3], 2, v[2:3]
	v_lshl_add_u64 v[4:5], s[4:5], 0, v[2:3]
	v_lshl_add_u64 v[2:3], s[2:3], 0, v[2:3]
	global_load_dword v73, v[4:5], off
	global_load_dword v46, v[2:3], off
	v_min_i32_e32 v2, v59, v0
	v_ashrrev_i32_e32 v3, 31, v2
	v_lshlrev_b64 v[2:3], 2, v[2:3]
	v_lshl_add_u64 v[4:5], s[4:5], 0, v[2:3]
	v_lshl_add_u64 v[2:3], s[2:3], 0, v[2:3]
	global_load_dword v61, v[4:5], off
	global_load_dword v44, v[2:3], off
	v_min_i32_e32 v2, v55, v0
	v_ashrrev_i32_e32 v3, 31, v2
	v_lshlrev_b64 v[2:3], 2, v[2:3]
	v_lshl_add_u64 v[4:5], s[4:5], 0, v[2:3]
	v_lshl_add_u64 v[2:3], s[2:3], 0, v[2:3]
	global_load_dword v57, v[4:5], off
	global_load_dword v42, v[2:3], off
	v_min_i32_e32 v2, v51, v0
	v_ashrrev_i32_e32 v3, 31, v2
	v_lshlrev_b64 v[2:3], 2, v[2:3]
	v_lshl_add_u64 v[4:5], s[4:5], 0, v[2:3]
	v_lshl_add_u64 v[2:3], s[2:3], 0, v[2:3]
	global_load_dword v53, v[4:5], off
	global_load_dword v40, v[2:3], off
	v_min_i32_e32 v2, v47, v0
	v_ashrrev_i32_e32 v3, 31, v2
; #define TIDX tid_opaque()
; DI void wait_vm0() { asm volatile("s_waitcnt vmcnt(0)" ::: "memory"); }
; DI h8 lds128(unsigned a) { h8 r; asm volatile("ds_read_b128 %0, %1" : "=v"(r) : "v"(a)); return r; }
; template <bool PRE = false, class AF, class BF>
; DI void gemm256(AF aptr, BF bptr, int nk, char* smem, f4 (&acc)[8][4]) {
;   const int tid = TIDX, lane = tid & 63, wave = tid >> 6, fr = lane & 15, fq = lane >> 4, wr = wave >> 1, wc = wave & 1;
; #pragma unroll
;   for (int m = 0; m < 8; m++)
; #pragma unroll
;     for (int n = 0; n < 4; n++) acc[m][n] = (f4){0.f, 0.f, 0.f, 0.f};
;   auto issue = [&](int kt, int st) {
;     char* d = smem + st * 49152 + tid * 16;
; #pragma unroll
;     for (int i = 0; i < 8; i++) glds16(aptr(i) + kt * 64, d + i * 4096);
; #pragma unroll
;     for (int i = 0; i < 4; i++) glds16(bptr(i) + kt * 64, d + 32768 + i * 4096);
;   };
;   const unsigned sw = (unsigned)((fq ^ (fr >> 1)) << 4);
;   const unsigned offA = (wr * 128 + fr) * 128 + sw, offB = 32768 + (wc * 64 + fr) * 128 + sw;
;   const unsigned sbase = lds_addr(smem);
;   if (!PRE) { issue(0, 0); if (nk > 1) issue(1, 1); }
;   int st = 0;
; #pragma unroll 1
;   for (int kt = 0; kt < nk; kt++) {
;     if (kt + 1 < nk) asm volatile("s_waitcnt vmcnt(12)" ::: "memory"); else wait_vm0();
;     raw_barrier();
;     if (kt + 2 < nk) issue(kt + 2, st == 0 ? 2 : st - 1);
;     const unsigned base = sbase + st * 49152;
;     st = st == 2 ? 0 : st + 1;
;     h8 a0[8], b0[4], a1[8], b1[4];
; #pragma unroll
;     for (int m = 0; m < 8; m++) a0[m] = lds128(base + offA + m * 2048);
; #pragma unroll
;     for (int n = 0; n < 4; n++) b0[n] = lds128(base + offB + n * 2048);
; #pragma unroll
;     for (int m = 0; m < 8; m++) a1[m] = lds128(base + (offA ^ 64) + m * 2048);
; #pragma unroll
;     for (int n = 0; n < 4; n++) b1[n] = lds128(base + (offB ^ 64) + n * 2048);
; DI void moe_e2_phase(const Params& P, int l, char* smem, int* tb) {
;     ...
;     int aa[2][8]; float ww[2][8];
; #pragma unroll
;     for (int h = 0; h < 2; h++)
; #pragma unroll
;       for (int i = 0; i < 8; i++) {
;         const int idx = rl * 256 + wr2 * 128 + h * 64 + ((i * 64 + lane2) >> 3);
;         const int ic = min(idx, cnt - 1);
;         const int av = lst[ic]; const float wv = lstw[ic];
;         aa[h][i] = idx < cnt ? av : -1; ww[h][i] = wv;
;       }
	v_lshlrev_b64 v[2:3], 2, v[2:3]
	v_lshl_add_u64 v[4:5], s[4:5], 0, v[2:3]
	v_lshl_add_u64 v[2:3], s[2:3], 0, v[2:3]
	global_load_dword v49, v[4:5], off
	global_load_dword v38, v[2:3], off
	v_min_i32_e32 v2, v43, v0
	v_ashrrev_i32_e32 v3, 31, v2
	v_lshlrev_b64 v[2:3], 2, v[2:3]
	v_lshl_add_u64 v[4:5], s[4:5], 0, v[2:3]
	v_lshl_add_u64 v[2:3], s[2:3], 0, v[2:3]
	global_load_dword v45, v[4:5], off
	global_load_dword v36, v[2:3], off
	v_min_i32_e32 v2, v39, v0
	v_ashrrev_i32_e32 v3, 31, v2
	v_min_i32_e32 v0, v35, v0
	v_lshlrev_b64 v[2:3], 2, v[2:3]
	v_ashrrev_i32_e32 v1, 31, v0
	v_lshl_add_u64 v[4:5], s[4:5], 0, v[2:3]
	v_lshl_add_u64 v[2:3], s[2:3], 0, v[2:3]
	v_lshlrev_b64 v[0:1], 2, v[0:1]
	global_load_dword v41, v[4:5], off
	global_load_dword v34, v[2:3], off
	v_lshl_add_u64 v[2:3], s[4:5], 0, v[0:1]
	v_lshl_add_u64 v[0:1], s[2:3], 0, v[0:1]
	global_load_dword v37, v[2:3], off
	global_load_dword v32, v[0:1], off
	v_mov_b32_e32 v0, v172
	v_accvgpr_write_b32 a112, 0
	v_lshlrev_b32_e32 v1, 3, v0
	v_and_b32_e32 v2, 48, v0
	v_bitop3_b32 v1, v1, v2, s37 bitop3:0x6c
	v_lshlrev_b32_e32 v2, 7, v0
	v_and_b32_e32 v3, 0xffffc780, v2
	v_and_b32_e32 v2, 0x2780, v2
	v_or_b32_e32 v4, v1, v2
	v_or_b32_e32 v156, v1, v3
	v_or_b32_e32 v157, 0x8000, v4
	v_lshlrev_b32_e32 v158, 4, v0
	v_bitop3_b32 v159, v1, 64, v3 bitop3:0x36
	v_bitop3_b32 v160, v1, s1, v2 bitop3:0x36
	v_accvgpr_write_b32 a127, 0
	v_accvgpr_write_b32 a126, 0
	v_accvgpr_write_b32 a125, 0
	v_accvgpr_write_b32 a124, 0
	v_accvgpr_write_b32 a123, 0
	v_accvgpr_write_b32 a122, 0
	v_accvgpr_write_b32 a121, 0
	v_accvgpr_write_b32 a120, 0
	v_accvgpr_write_b32 a119, 0
	v_accvgpr_write_b32 a118, 0
	v_accvgpr_write_b32 a117, 0
	v_accvgpr_write_b32 a116, 0
	v_accvgpr_write_b32 a111, 0
	v_accvgpr_write_b32 a110, 0
	v_accvgpr_write_b32 a109, 0
	v_accvgpr_write_b32 a108, 0
	v_accvgpr_write_b32 a107, 0
	v_accvgpr_write_b32 a106, 0
	v_accvgpr_write_b32 a105, 0
	v_accvgpr_write_b32 a104, 0
	v_accvgpr_write_b32 a103, 0
	v_accvgpr_write_b32 a102, 0
	v_accvgpr_write_b32 a101, 0
	v_accvgpr_write_b32 a100, 0
	v_accvgpr_write_b32 a95, 0
	v_accvgpr_write_b32 a94, 0
	v_accvgpr_write_b32 a93, 0
	v_accvgpr_write_b32 a92, 0
	v_accvgpr_write_b32 a91, 0
	v_accvgpr_write_b32 a90, 0
	v_accvgpr_write_b32 a89, 0
	v_accvgpr_write_b32 a88, 0
	v_accvgpr_write_b32 a87, 0
	v_accvgpr_write_b32 a86, 0
	v_accvgpr_write_b32 a85, 0
	v_accvgpr_write_b32 a84, 0
	v_accvgpr_write_b32 a79, 0
	v_accvgpr_write_b32 a78, 0
	v_accvgpr_write_b32 a77, 0
	v_accvgpr_write_b32 a76, 0
	v_accvgpr_write_b32 a75, 0
	v_accvgpr_write_b32 a74, 0
	v_accvgpr_write_b32 a73, 0
	v_accvgpr_write_b32 a72, 0
	v_accvgpr_write_b32 a71, 0
	v_accvgpr_write_b32 a70, 0
	v_accvgpr_write_b32 a69, 0
	v_accvgpr_write_b32 a68, 0
	v_accvgpr_write_b32 a63, 0
	v_accvgpr_write_b32 a62, 0
	v_accvgpr_write_b32 a61, 0
	v_accvgpr_write_b32 a60, 0
	v_accvgpr_write_b32 a59, 0
	v_accvgpr_write_b32 a58, 0
	v_accvgpr_write_b32 a57, 0
	v_accvgpr_write_b32 a56, 0
	v_accvgpr_write_b32 a55, 0
	v_accvgpr_write_b32 a54, 0
	v_accvgpr_write_b32 a53, 0
	v_accvgpr_write_b32 a52, 0
	v_accvgpr_write_b32 a47, 0
	v_accvgpr_write_b32 a46, 0
	v_accvgpr_write_b32 a45, 0
	v_accvgpr_write_b32 a44, 0
	v_accvgpr_write_b32 a43, 0
	v_accvgpr_write_b32 a42, 0
	v_accvgpr_write_b32 a41, 0
	v_accvgpr_write_b32 a40, 0
	v_accvgpr_write_b32 a39, 0
	v_accvgpr_write_b32 a38, 0
	v_accvgpr_write_b32 a37, 0
	v_accvgpr_write_b32 a36, 0
	v_accvgpr_write_b32 a31, 0
	v_accvgpr_write_b32 a30, 0
	v_accvgpr_write_b32 a29, 0
	v_accvgpr_write_b32 a28, 0
	v_accvgpr_write_b32 a27, 0
	v_accvgpr_write_b32 a26, 0
	v_accvgpr_write_b32 a25, 0
	v_accvgpr_write_b32 a24, 0
	v_accvgpr_write_b32 a23, 0
	v_accvgpr_write_b32 a22, 0
	v_accvgpr_write_b32 a21, 0
	v_accvgpr_write_b32 a20, 0
	v_accvgpr_write_b32 a15, 0
	v_accvgpr_write_b32 a14, 0
	v_accvgpr_write_b32 a13, 0
	v_accvgpr_write_b32 a12, 0
	s_mov_b32 s1, 0
	s_mov_b64 s[2:3], 0
	s_mov_b32 s7, 0
	v_readfirstlane_b32 s100, v158
	s_waitcnt vmcnt(12)
	s_barrier
	s_add_u32 s101, s100, 0x18000
	v_lshl_add_u64 v[10:11], v[26:27], 0, s[2:3]
	s_add_u32 m0, s101, 0x0
	v_lshl_add_u64 v[14:15], v[10:11], 0, s[74:75]
	global_load_lds_dwordx4 v[14:15], off
	s_add_u32 m0, s101, 0x1000
	v_lshl_add_u64 v[14:15], v[10:11], 0, s[24:25]
	global_load_lds_dwordx4 v[14:15], off
	s_add_u32 m0, s101, 0x2000
	v_lshl_add_u64 v[14:15], v[10:11], 0, s[76:77]
	global_load_lds_dwordx4 v[14:15], off
	s_add_u32 m0, s101, 0x3000
	v_lshl_add_u64 v[14:15], v[10:11], 0, s[26:27]
	global_load_lds_dwordx4 v[14:15], off
	s_add_u32 m0, s101, 0x4000
	v_lshl_add_u64 v[14:15], v[10:11], 0, s[86:87]
	global_load_lds_dwordx4 v[14:15], off
	s_mov_b64 s[4:5], 0x28100
	s_add_u32 m0, s101, 0x5000
	v_lshl_add_u64 v[14:15], v[10:11], 0, s[4:5]
	global_load_lds_dwordx4 v[14:15], off
	s_add_u32 m0, s101, 0x6000
	v_lshl_add_u64 v[14:15], v[10:11], 0, s[80:81]
	global_load_lds_dwordx4 v[14:15], off
	s_mov_b64 s[4:5], 0x38100
	s_add_u32 m0, s101, 0x7000
	v_lshl_add_u64 v[14:15], v[10:11], 0, s[4:5]
	global_load_lds_dwordx4 v[14:15], off
	v_lshl_add_u64 v[12:13], v[28:29], 0, s[2:3]
	s_add_u32 m0, s101, 0x8000
	v_lshl_add_u64 v[14:15], v[12:13], 0, s[74:75]
	global_load_lds_dwordx4 v[14:15], off
	s_add_u32 m0, s101, 0x9000
	v_lshl_add_u64 v[14:15], v[12:13], 0, s[24:25]
	global_load_lds_dwordx4 v[14:15], off
	s_add_u32 m0, s101, 0xa000
	v_lshl_add_u64 v[14:15], v[12:13], 0, s[76:77]
	global_load_lds_dwordx4 v[14:15], off
	s_add_u32 m0, s101, 0xb000
	v_lshl_add_u64 v[14:15], v[12:13], 0, s[26:27]
	global_load_lds_dwordx4 v[14:15], off
	s_add_u32 s2, s2, 0x80
	s_addc_u32 s3, s3, 0
	ds_read_b128 v[122:125], v157 offset:0
	ds_read_b128 v[126:129], v157 offset:2048
	ds_read_b128 v[130:133], v157 offset:4096
	ds_read_b128 v[134:137], v157 offset:6144
	ds_read_b128 v[90:93], v156 offset:0
	ds_read_b128 v[94:97], v156 offset:2048
	ds_read_b128 v[98:101], v156 offset:4096
	ds_read_b128 v[102:105], v156 offset:6144
	ds_read_b128 v[106:109], v156 offset:8192
	ds_read_b128 v[110:113], v156 offset:10240
	ds_read_b128 v[114:117], v156 offset:12288
	ds_read_b128 v[118:121], v156 offset:14336
; DI f4 mfma16(h8 a, h8 b, f4 c) { return __builtin_amdgcn_mfma_f32_16x16x32_f16(a, b, c, 0, 0, 0); }
; DI h8 lds128(unsigned a) { h8 r; asm volatile("ds_read_b128 %0, %1" : "=v"(r) : "v"(a)); return r; }
; DI void tie(h8& x) { asm volatile("" : "+v"(x)); }
; #define WAIT_LGKM(n) asm volatile("s_waitcnt lgkmcnt(" #n ")" ::: "memory")
; template <bool PRE = false, class AF, class BF>
; DI void gemm256(AF aptr, BF bptr, int nk, char* smem, f4 (&acc)[8][4]) {
;     ...
;     for (int m = 0; m < 8; m++) a0[m] = lds128(base + offA + m * 2048);
; #pragma unroll
;     for (int n = 0; n < 4; n++) b0[n] = lds128(base + offB + n * 2048);
; #pragma unroll
;     for (int m = 0; m < 8; m++) a1[m] = lds128(base + (offA ^ 64) + m * 2048);
; #pragma unroll
;     for (int n = 0; n < 4; n++) b1[n] = lds128(base + (offB ^ 64) + n * 2048);
;     WAIT_LGKM(12);
; #pragma unroll
;     for (int m = 0; m < 8; m++) tie(a0[m]);
; #pragma unroll
;     for (int n = 0; n < 4; n++) tie(b0[n]);
; #pragma unroll
;     for (int m = 0; m < 8; m++)
; #pragma unroll
;       for (int n = 0; n < 4; n++) acc[m][n] = mfma16(a0[m], b0[n], acc[m][n]);
.Lg_e2_loop:
	s_mul_i32 s22, s7, 0xc000
	v_add_u32_e32 v8, s22, v159
	v_add_u32_e32 v9, s22, v160
	s_waitcnt lgkmcnt(0)
	v_mfma_f32_16x16x32_f16 a[0:3], v[90:93], v[122:125], a[0:3]
	ds_read_b128 a[200:203], v9 offset:0
	v_mfma_f32_16x16x32_f16 a[4:7], v[90:93], v[126:129], a[4:7]
	v_mfma_f32_16x16x32_f16 a[8:11], v[90:93], v[130:133], a[8:11]
	ds_read_b128 a[204:207], v9 offset:2048
	v_mfma_f32_16x16x32_f16 a[16:19], v[90:93], v[134:137], a[16:19]
	v_mfma_f32_16x16x32_f16 a[32:35], v[94:97], v[122:125], a[32:35]
	ds_read_b128 a[208:211], v9 offset:4096
	v_mfma_f32_16x16x32_f16 a[48:51], v[94:97], v[126:129], a[48:51]
	v_mfma_f32_16x16x32_f16 a[64:67], v[94:97], v[130:133], a[64:67]
	ds_read_b128 a[212:215], v9 offset:6144
	v_mfma_f32_16x16x32_f16 a[80:83], v[94:97], v[134:137], a[80:83]
	v_mfma_f32_16x16x32_f16 a[96:99], v[98:101], v[122:125], a[96:99]
	ds_read_b128 v[138:141], v8 offset:0
	v_mfma_f32_16x16x32_f16 a[112:115], v[98:101], v[126:129], a[112:115]
	v_mfma_f32_16x16x32_f16 a[124:127], v[98:101], v[130:133], a[124:127]
	ds_read_b128 v[142:145], v8 offset:2048
	v_mfma_f32_16x16x32_f16 a[120:123], v[98:101], v[134:137], a[120:123]
	v_mfma_f32_16x16x32_f16 a[116:119], v[102:105], v[122:125], a[116:119]
	ds_read_b128 v[0:3], v8 offset:4096
	v_mfma_f32_16x16x32_f16 a[108:111], v[102:105], v[126:129], a[108:111]
	v_mfma_f32_16x16x32_f16 a[104:107], v[102:105], v[130:133], a[104:107]
	ds_read_b128 v[4:7], v8 offset:6144
	v_mfma_f32_16x16x32_f16 a[100:103], v[102:105], v[134:137], a[100:103]
	v_mfma_f32_16x16x32_f16 a[92:95], v[106:109], v[122:125], a[92:95]
	ds_read_b128 v[152:155], v8 offset:8192
	v_mfma_f32_16x16x32_f16 a[88:91], v[106:109], v[126:129], a[88:91]
	v_mfma_f32_16x16x32_f16 a[84:87], v[106:109], v[130:133], a[84:87]
	ds_read_b128 v[162:165], v8 offset:10240
	v_mfma_f32_16x16x32_f16 a[76:79], v[106:109], v[134:137], a[76:79]
	v_mfma_f32_16x16x32_f16 a[72:75], v[110:113], v[122:125], a[72:75]
	ds_read_b128 v[166:169], v8 offset:12288
	v_mfma_f32_16x16x32_f16 a[68:71], v[110:113], v[126:129], a[68:71]
	v_mfma_f32_16x16x32_f16 a[60:63], v[110:113], v[130:133], a[60:63]
	ds_read_b128 v[180:183], v8 offset:14336
	v_mfma_f32_16x16x32_f16 a[56:59], v[110:113], v[134:137], a[56:59]
	v_mfma_f32_16x16x32_f16 a[52:55], v[114:117], v[122:125], a[52:55]
	v_mfma_f32_16x16x32_f16 a[44:47], v[114:117], v[126:129], a[44:47]
	v_mfma_f32_16x16x32_f16 a[40:43], v[114:117], v[130:133], a[40:43]
	v_mfma_f32_16x16x32_f16 a[36:39], v[114:117], v[134:137], a[36:39]
	v_mfma_f32_16x16x32_f16 a[28:31], v[118:121], v[122:125], a[28:31]
	v_mfma_f32_16x16x32_f16 a[24:27], v[118:121], v[126:129], a[24:27]
	v_mfma_f32_16x16x32_f16 a[20:23], v[118:121], v[130:133], a[20:23]
	v_mfma_f32_16x16x32_f16 a[12:15], v[118:121], v[134:137], a[12:15]
	s_cmp_eq_u32 s1, 7
	s_cbranch_scc1 .Lg_e2_last
	s_cmp_lt_u32 s1, 6
	s_cbranch_scc1 .Lg_e2_w12
	s_waitcnt vmcnt(0)
	s_branch .Lg_e2_wd

; DI void wait_vm0() { asm volatile("s_waitcnt vmcnt(0)" ::: "memory"); }
; DI f4 mfma16(h8 a, h8 b, f4 c) { return __builtin_amdgcn_mfma_f32_16x16x32_f16(a, b, c, 0, 0, 0); }
; DI h8 lds128(unsigned a) { h8 r; asm volatile("ds_read_b128 %0, %1" : "=v"(r) : "v"(a)); return r; }
; DI void tie(h8& x) { asm volatile("" : "+v"(x)); }
; #define WAIT_LGKM(n) asm volatile("s_waitcnt lgkmcnt(" #n ")" ::: "memory")
; DI void raw_barrier() { asm volatile("" ::: "memory"); __builtin_amdgcn_s_barrier(); asm volatile("" ::: "memory"); }
; template <bool PRE = false, class AF, class BF>
; DI void gemm256(AF aptr, BF bptr, int nk, char* smem, f4 (&acc)[8][4]) {
;     ...
;   for (int kt = 0; kt < nk; kt++) {
;     if (kt + 1 < nk) asm volatile("s_waitcnt vmcnt(12)" ::: "memory"); else wait_vm0();
;     raw_barrier();
;     if (kt + 2 < nk) issue(kt + 2, st == 0 ? 2 : st - 1);
;     const unsigned base = sbase + st * 49152;
;     st = st == 2 ? 0 : st + 1;
;     h8 a0[8], b0[4], a1[8], b1[4];
; #pragma unroll
;     for (int m = 0; m < 8; m++) a0[m] = lds128(base + offA + m * 2048);
; #pragma unroll
;     for (int n = 0; n < 4; n++) b0[n] = lds128(base + offB + n * 2048);
; #pragma unroll
;     for (int m = 0; m < 8; m++) a1[m] = lds128(base + (offA ^ 64) + m * 2048);
; #pragma unroll
;     for (int n = 0; n < 4; n++) b1[n] = lds128(base + (offB ^ 64) + n * 2048);
;     WAIT_LGKM(12);
; #pragma unroll
;     for (int m = 0; m < 8; m++) tie(a0[m]);
; #pragma unroll
;     for (int n = 0; n < 4; n++) tie(b0[n]);
; #pragma unroll
;     for (int m = 0; m < 8; m++)
; #pragma unroll
;       for (int n = 0; n < 4; n++) acc[m][n] = mfma16(a0[m], b0[n], acc[m][n]);
;     WAIT_LGKM(0);
; #pragma unroll
;     for (int m = 0; m < 8; m++) tie(a1[m]);
; #pragma unroll
;     for (int n = 0; n < 4; n++) tie(b1[n]);
; #pragma unroll
;     for (int m = 0; m < 8; m++)
; #pragma unroll
;       for (int n = 0; n < 4; n++) acc[m][n] = mfma16(a1[m], b1[n], acc[m][n]);
.Lg_e2_wd:
	s_waitcnt lgkmcnt(0)
	s_barrier
	s_add_u32 s21, s7, 1
	s_cmp_eq_u32 s21, 3
	s_cselect_b32 s21, 0, s21
	s_mul_i32 s22, s21, 0xc000
	v_add_u32_e32 v8, s22, v156
	v_add_u32_e32 v9, s22, v157
	s_mul_i32 s101, s7, 0xc000
	s_add_u32 s101, s101, s100
	s_cmp_lt_u32 s1, 5
	s_cbranch_scc0 .Lg_e2_noissue
	v_mfma_f32_16x16x32_f16 a[0:3], v[138:141], a[200:203], a[0:3]
	ds_read_b128 v[122:125], v9 offset:0
	v_mfma_f32_16x16x32_f16 a[4:7], v[138:141], a[204:207], a[4:7]
	v_lshl_add_u64 v[10:11], v[26:27], 0, s[2:3]
	s_add_u32 m0, s101, 0x0
	v_lshl_add_u64 v[14:15], v[10:11], 0, s[74:75]
	global_load_lds_dwordx4 v[14:15], off
	v_mfma_f32_16x16x32_f16 a[8:11], v[138:141], a[208:211], a[8:11]
	ds_read_b128 v[126:129], v9 offset:2048
	v_mfma_f32_16x16x32_f16 a[16:19], v[138:141], a[212:215], a[16:19]
	s_add_u32 m0, s101, 0x1000
	v_lshl_add_u64 v[14:15], v[10:11], 0, s[24:25]
	global_load_lds_dwordx4 v[14:15], off
	v_mfma_f32_16x16x32_f16 a[32:35], v[142:145], a[200:203], a[32:35]
	ds_read_b128 v[130:133], v9 offset:4096
	v_mfma_f32_16x16x32_f16 a[48:51], v[142:145], a[204:207], a[48:51]
	s_add_u32 m0, s101, 0x2000
	v_lshl_add_u64 v[14:15], v[10:11], 0, s[76:77]
	global_load_lds_dwordx4 v[14:15], off
	v_mfma_f32_16x16x32_f16 a[64:67], v[142:145], a[208:211], a[64:67]
	ds_read_b128 v[134:137], v9 offset:6144
	v_mfma_f32_16x16x32_f16 a[80:83], v[142:145], a[212:215], a[80:83]
	s_add_u32 m0, s101, 0x3000
	v_lshl_add_u64 v[14:15], v[10:11], 0, s[26:27]
	global_load_lds_dwordx4 v[14:15], off
	v_mfma_f32_16x16x32_f16 a[96:99], v[0:3], a[200:203], a[96:99]
	ds_read_b128 v[90:93], v8 offset:0
	v_mfma_f32_16x16x32_f16 a[112:115], v[0:3], a[204:207], a[112:115]
	s_add_u32 m0, s101, 0x4000
	v_lshl_add_u64 v[14:15], v[10:11], 0, s[86:87]
	global_load_lds_dwordx4 v[14:15], off
	v_mfma_f32_16x16x32_f16 a[124:127], v[0:3], a[208:211], a[124:127]
	ds_read_b128 v[94:97], v8 offset:2048
	v_mfma_f32_16x16x32_f16 a[120:123], v[0:3], a[212:215], a[120:123]
	s_mov_b64 s[4:5], 0x28100
	s_add_u32 m0, s101, 0x5000
	v_lshl_add_u64 v[14:15], v[10:11], 0, s[4:5]
	global_load_lds_dwordx4 v[14:15], off
	v_mfma_f32_16x16x32_f16 a[116:119], v[4:7], a[200:203], a[116:119]
	ds_read_b128 v[98:101], v8 offset:4096
	v_mfma_f32_16x16x32_f16 a[108:111], v[4:7], a[204:207], a[108:111]
	s_add_u32 m0, s101, 0x6000
	v_lshl_add_u64 v[14:15], v[10:11], 0, s[80:81]
	global_load_lds_dwordx4 v[14:15], off
	v_mfma_f32_16x16x32_f16 a[104:107], v[4:7], a[208:211], a[104:107]
	ds_read_b128 v[102:105], v8 offset:6144
	v_mfma_f32_16x16x32_f16 a[100:103], v[4:7], a[212:215], a[100:103]
	s_mov_b64 s[4:5], 0x38100
	s_add_u32 m0, s101, 0x7000
	v_lshl_add_u64 v[14:15], v[10:11], 0, s[4:5]
	global_load_lds_dwordx4 v[14:15], off
	v_mfma_f32_16x16x32_f16 a[92:95], v[152:155], a[200:203], a[92:95]
	ds_read_b128 v[106:109], v8 offset:8192
	v_mfma_f32_16x16x32_f16 a[88:91], v[152:155], a[204:207], a[88:91]
	v_lshl_add_u64 v[12:13], v[28:29], 0, s[2:3]
	s_add_u32 m0, s101, 0x8000
	v_lshl_add_u64 v[14:15], v[12:13], 0, s[74:75]
	global_load_lds_dwordx4 v[14:15], off
	v_mfma_f32_16x16x32_f16 a[84:87], v[152:155], a[208:211], a[84:87]
	ds_read_b128 v[110:113], v8 offset:10240
	v_mfma_f32_16x16x32_f16 a[76:79], v[152:155], a[212:215], a[76:79]
	s_add_u32 m0, s101, 0x9000
	v_lshl_add_u64 v[14:15], v[12:13], 0, s[24:25]
	global_load_lds_dwordx4 v[14:15], off
	v_mfma_f32_16x16x32_f16 a[72:75], v[162:165], a[200:203], a[72:75]
	ds_read_b128 v[114:117], v8 offset:12288
	v_mfma_f32_16x16x32_f16 a[68:71], v[162:165], a[204:207], a[68:71]
	s_add_u32 m0, s101, 0xa000
	v_lshl_add_u64 v[14:15], v[12:13], 0, s[76:77]
	global_load_lds_dwordx4 v[14:15], off
	v_mfma_f32_16x16x32_f16 a[60:63], v[162:165], a[208:211], a[60:63]
	ds_read_b128 v[118:121], v8 offset:14336
	v_mfma_f32_16x16x32_f16 a[56:59], v[162:165], a[212:215], a[56:59]
	s_add_u32 m0, s101, 0xb000
	v_lshl_add_u64 v[14:15], v[12:13], 0, s[26:27]
	global_load_lds_dwordx4 v[14:15], off
	v_mfma_f32_16x16x32_f16 a[52:55], v[166:169], a[200:203], a[52:55]
	v_mfma_f32_16x16x32_f16 a[44:47], v[166:169], a[204:207], a[44:47]
	v_mfma_f32_16x16x32_f16 a[40:43], v[166:169], a[208:211], a[40:43]
	v_mfma_f32_16x16x32_f16 a[36:39], v[166:169], a[212:215], a[36:39]
	v_mfma_f32_16x16x32_f16 a[28:31], v[180:183], a[200:203], a[28:31]
	v_mfma_f32_16x16x32_f16 a[24:27], v[180:183], a[204:207], a[24:27]
	v_mfma_f32_16x16x32_f16 a[20:23], v[180:183], a[208:211], a[20:23]
	v_mfma_f32_16x16x32_f16 a[12:15], v[180:183], a[212:215], a[12:15]
	s_branch .Lg_e2_next
; DI void wait_vm0() { asm volatile("s_waitcnt vmcnt(0)" ::: "memory"); }
; DI f4 mfma16(h8 a, h8 b, f4 c) { return __builtin_amdgcn_mfma_f32_16x16x32_f16(a, b, c, 0, 0, 0); }
; DI h8 lds128(unsigned a) { h8 r; asm volatile("ds_read_b128 %0, %1" : "=v"(r) : "v"(a)); return r; }
; DI void tie(h8& x) { asm volatile("" : "+v"(x)); }
; #define WAIT_LGKM(n) asm volatile("s_waitcnt lgkmcnt(" #n ")" ::: "memory")
; DI void raw_barrier() { asm volatile("" ::: "memory"); __builtin_amdgcn_s_barrier(); asm volatile("" ::: "memory"); }
; template <bool PRE = false, class AF, class BF>
; DI void gemm256(AF aptr, BF bptr, int nk, char* smem, f4 (&acc)[8][4]) {
;     ...
;   for (int kt = 0; kt < nk; kt++) {
;     if (kt + 1 < nk) asm volatile("s_waitcnt vmcnt(12)" ::: "memory"); else wait_vm0();
;     raw_barrier();
;     if (kt + 2 < nk) issue(kt + 2, st == 0 ? 2 : st - 1);
;     const unsigned base = sbase + st * 49152;
;     st = st == 2 ? 0 : st + 1;
;     h8 a0[8], b0[4], a1[8], b1[4];
; #pragma unroll
;     for (int m = 0; m < 8; m++) a0[m] = lds128(base + offA + m * 2048);
; #pragma unroll
;     for (int n = 0; n < 4; n++) b0[n] = lds128(base + offB + n * 2048);
; #pragma unroll
;     for (int m = 0; m < 8; m++) a1[m] = lds128(base + (offA ^ 64) + m * 2048);
; #pragma unroll
;     for (int n = 0; n < 4; n++) b1[n] = lds128(base + (offB ^ 64) + n * 2048);
;     WAIT_LGKM(12);
; #pragma unroll
;     for (int m = 0; m < 8; m++) tie(a0[m]);
; #pragma unroll
;     for (int n = 0; n < 4; n++) tie(b0[n]);
; #pragma unroll
;     for (int m = 0; m < 8; m++)
; #pragma unroll
;       for (int n = 0; n < 4; n++) acc[m][n] = mfma16(a0[m], b0[n], acc[m][n]);
;     WAIT_LGKM(0);
; #pragma unroll
;     for (int m = 0; m < 8; m++) tie(a1[m]);
; #pragma unroll
;     for (int n = 0; n < 4; n++) tie(b1[n]);
; #pragma unroll
;     for (int m = 0; m < 8; m++)
; #pragma unroll
;       for (int n = 0; n < 4; n++) acc[m][n] = mfma16(a1[m], b1[n], acc[m][n]);
;   }
.Lg_e2_noissue:
	v_mfma_f32_16x16x32_f16 a[0:3], v[138:141], a[200:203], a[0:3]
	ds_read_b128 v[122:125], v9 offset:0
	v_mfma_f32_16x16x32_f16 a[4:7], v[138:141], a[204:207], a[4:7]
	v_mfma_f32_16x16x32_f16 a[8:11], v[138:141], a[208:211], a[8:11]
	ds_read_b128 v[126:129], v9 offset:2048
	v_mfma_f32_16x16x32_f16 a[16:19], v[138:141], a[212:215], a[16:19]
	v_mfma_f32_16x16x32_f16 a[32:35], v[142:145], a[200:203], a[32:35]
	ds_read_b128 v[130:133], v9 offset:4096
	v_mfma_f32_16x16x32_f16 a[48:51], v[142:145], a[204:207], a[48:51]
	v_mfma_f32_16x16x32_f16 a[64:67], v[142:145], a[208:211], a[64:67]
	ds_read_b128 v[134:137], v9 offset:6144
	v_mfma_f32_16x16x32_f16 a[80:83], v[142:145], a[212:215], a[80:83]
	v_mfma_f32_16x16x32_f16 a[96:99], v[0:3], a[200:203], a[96:99]
	ds_read_b128 v[90:93], v8 offset:0
	v_mfma_f32_16x16x32_f16 a[112:115], v[0:3], a[204:207], a[112:115]
	v_mfma_f32_16x16x32_f16 a[124:127], v[0:3], a[208:211], a[124:127]
	ds_read_b128 v[94:97], v8 offset:2048
	v_mfma_f32_16x16x32_f16 a[120:123], v[0:3], a[212:215], a[120:123]
	v_mfma_f32_16x16x32_f16 a[116:119], v[4:7], a[200:203], a[116:119]
	ds_read_b128 v[98:101], v8 offset:4096
	v_mfma_f32_16x16x32_f16 a[108:111], v[4:7], a[204:207], a[108:111]
	v_mfma_f32_16x16x32_f16 a[104:107], v[4:7], a[208:211], a[104:107]
	ds_read_b128 v[102:105], v8 offset:6144
	v_mfma_f32_16x16x32_f16 a[100:103], v[4:7], a[212:215], a[100:103]
	v_mfma_f32_16x16x32_f16 a[92:95], v[152:155], a[200:203], a[92:95]
	ds_read_b128 v[106:109], v8 offset:8192
	v_mfma_f32_16x16x32_f16 a[88:91], v[152:155], a[204:207], a[88:91]
	v_mfma_f32_16x16x32_f16 a[84:87], v[152:155], a[208:211], a[84:87]
	ds_read_b128 v[110:113], v8 offset:10240
	v_mfma_f32_16x16x32_f16 a[76:79], v[152:155], a[212:215], a[76:79]
	v_mfma_f32_16x16x32_f16 a[72:75], v[162:165], a[200:203], a[72:75]
	ds_read_b128 v[114:117], v8 offset:12288
	v_mfma_f32_16x16x32_f16 a[68:71], v[162:165], a[204:207], a[68:71]
	v_mfma_f32_16x16x32_f16 a[60:63], v[162:165], a[208:211], a[60:63]
	ds_read_b128 v[118:121], v8 offset:14336
	v_mfma_f32_16x16x32_f16 a[56:59], v[162:165], a[212:215], a[56:59]
	v_mfma_f32_16x16x32_f16 a[52:55], v[166:169], a[200:203], a[52:55]
	v_mfma_f32_16x16x32_f16 a[44:47], v[166:169], a[204:207], a[44:47]
	v_mfma_f32_16x16x32_f16 a[40:43], v[166:169], a[208:211], a[40:43]
	v_mfma_f32_16x16x32_f16 a[36:39], v[166:169], a[212:215], a[36:39]
	v_mfma_f32_16x16x32_f16 a[28:31], v[180:183], a[200:203], a[28:31]
	v_mfma_f32_16x16x32_f16 a[24:27], v[180:183], a[204:207], a[24:27]
	v_mfma_f32_16x16x32_f16 a[20:23], v[180:183], a[208:211], a[20:23]
	v_mfma_f32_16x16x32_f16 a[12:15], v[180:183], a[212:215], a[12:15]
.Lg_e2_next:
	s_mov_b32 s7, s21
	s_add_u32 s1, s1, 1
	s_add_u32 s2, s2, 0x80
	s_addc_u32 s3, s3, 0
	s_branch .Lg_e2_loop
.Lg_e2_last:
	s_waitcnt lgkmcnt(0)
	v_mfma_f32_16x16x32_f16 a[0:3], v[138:141], a[200:203], a[0:3]
	v_mfma_f32_16x16x32_f16 a[4:7], v[138:141], a[204:207], a[4:7]
	v_mfma_f32_16x16x32_f16 a[8:11], v[138:141], a[208:211], a[8:11]
	v_mfma_f32_16x16x32_f16 a[16:19], v[138:141], a[212:215], a[16:19]
	v_mfma_f32_16x16x32_f16 a[32:35], v[142:145], a[200:203], a[32:35]
	v_mfma_f32_16x16x32_f16 a[48:51], v[142:145], a[204:207], a[48:51]
	v_mfma_f32_16x16x32_f16 a[64:67], v[142:145], a[208:211], a[64:67]
	v_mfma_f32_16x16x32_f16 a[80:83], v[142:145], a[212:215], a[80:83]
	v_mfma_f32_16x16x32_f16 a[96:99], v[0:3], a[200:203], a[96:99]
	v_mfma_f32_16x16x32_f16 a[112:115], v[0:3], a[204:207], a[112:115]
	v_mfma_f32_16x16x32_f16 a[124:127], v[0:3], a[208:211], a[124:127]
	v_mfma_f32_16x16x32_f16 a[120:123], v[0:3], a[212:215], a[120:123]
	v_mfma_f32_16x16x32_f16 a[116:119], v[4:7], a[200:203], a[116:119]
	v_mfma_f32_16x16x32_f16 a[108:111], v[4:7], a[204:207], a[108:111]
	v_mfma_f32_16x16x32_f16 a[104:107], v[4:7], a[208:211], a[104:107]
	v_mfma_f32_16x16x32_f16 a[100:103], v[4:7], a[212:215], a[100:103]
	v_mfma_f32_16x16x32_f16 a[92:95], v[152:155], a[200:203], a[92:95]
	v_mfma_f32_16x16x32_f16 a[88:91], v[152:155], a[204:207], a[88:91]
	v_mfma_f32_16x16x32_f16 a[84:87], v[152:155], a[208:211], a[84:87]
	v_mfma_f32_16x16x32_f16 a[76:79], v[152:155], a[212:215], a[76:79]
	v_mfma_f32_16x16x32_f16 a[72:75], v[162:165], a[200:203], a[72:75]
	v_mfma_f32_16x16x32_f16 a[68:71], v[162:165], a[204:207], a[68:71]
	v_mfma_f32_16x16x32_f16 a[60:63], v[162:165], a[208:211], a[60:63]
	v_mfma_f32_16x16x32_f16 a[56:59], v[162:165], a[212:215], a[56:59]
	v_mfma_f32_16x16x32_f16 a[52:55], v[166:169], a[200:203], a[52:55]
	v_mfma_f32_16x16x32_f16 a[44:47], v[166:169], a[204:207], a[44:47]
	v_mfma_f32_16x16x32_f16 a[40:43], v[166:169], a[208:211], a[40:43]
	v_mfma_f32_16x16x32_f16 a[36:39], v[166:169], a[212:215], a[36:39]
	v_mfma_f32_16x16x32_f16 a[28:31], v[180:183], a[200:203], a[28:31]
	v_mfma_f32_16x16x32_f16 a[24:27], v[180:183], a[204:207], a[24:27]
	v_mfma_f32_16x16x32_f16 a[20:23], v[180:183], a[208:211], a[20:23]
	v_mfma_f32_16x16x32_f16 a[12:15], v[180:183], a[212:215], a[12:15]
	s_nop 7
	s_nop 7

; __global__ void __launch_bounds__(256, 1) fwd_megakernel(Params Pin) {
;   Params P = Pin; bind_ws(P);
;   __shared__ __attribute__((aligned(16))) char smem[147456 + 8192];
;   __shared__ int tb[33];
;   __shared__ int s_item;
amdhsa.kernels:
  - .agpr_count:     226
    .args:
      - .offset:         0
        .size:           520
        .value_kind:     by_value
      - .offset:         520
        .size:           4
        .value_kind:     hidden_block_count_x
      - .offset:         524
        .size:           4
        .value_kind:     hidden_block_count_y
      - .offset:         528
        .size:           4
        .value_kind:     hidden_block_count_z
      - .offset:         532
        .size:           2
        .value_kind:     hidden_group_size_x
      - .offset:         534
        .size:           2
        .value_kind:     hidden_group_size_y
      - .offset:         536
        .size:           2
        .value_kind:     hidden_group_size_z
      - .offset:         538
        .size:           2
        .value_kind:     hidden_remainder_x
      - .offset:         540
        .size:           2
        .value_kind:     hidden_remainder_y
      - .offset:         542
        .size:           2
        .value_kind:     hidden_remainder_z
      - .offset:         560
        .size:           8
        .value_kind:     hidden_global_offset_x
      - .offset:         568
        .size:           8
        .value_kind:     hidden_global_offset_y
      - .offset:         576
        .size:           8
        .value_kind:     hidden_global_offset_z
      - .offset:         584
        .size:           2
        .value_kind:     hidden_grid_dims
      - .offset:         608
        .size:           8
        .value_kind:     hidden_multigrid_sync_arg
    .group_segment_fixed_size: 155784
    .kernarg_segment_align: 8
    .kernarg_segment_size: 776
    .language:       OpenCL C
    .language_version:
      - 2
      - 0
    .max_flat_workgroup_size: 256
    .name:           _Z14fwd_megakernel6Params
    .private_segment_fixed_size: 0
    .sgpr_count:     108
    .sgpr_spill_count: 209
    .symbol:         _Z14fwd_megakernel6Params.kd
    .uniform_work_group_size: 1
    .uses_dynamic_stack: false
    .vgpr_count:     482
    .vgpr_spill_count: 0
    .wavefront_size: 64
